# GEMM loops: trailing barrier signalled one MFMA early (last MFMA of each block issues after the barrier), on top of the trimmed hand-off
# baseline (speedup 1.0000x reference)
; #define PG8_STAGE(bufoff, gbase, voff) do { _Pragma("unroll") for (int _i = 0; _i < 2; ++_i) \
;         __builtin_amdgcn_global_load_lds((const unsigned*)((const char*)(gbase) + (voff)[_i]), (PG8_LAS unsigned*)(lds + (bufoff) + ldsw + _i * 8192), 16, 0, 0); } while (0)
; #define PG8_LDA(dst, b, h) do { _Pragma("unroll") for (int m = 0; m < 4; ++m) _Pragma("unroll") for (int k = 0; k < 2; ++k) dst[m][k] = *(const PG8_LAS bf16x8*)(lds + PG8_SA(b, h) + aoff + m * 2048 + k * 1024); } while (0)
; #define PG8_LDB(dst, b, h) do { _Pragma("unroll") for (int n = 0; n < 2; ++n) _Pragma("unroll") for (int k = 0; k < 2; ++k) dst[n][k] = *(const PG8_LAS bf16x8*)(lds + PG8_SB(b, h) + boff + n * 2048 + k * 1024); } while (0)
; #define PG8_MMA(ai, bj, At, Bt) do { __builtin_amdgcn_s_setprio(1); _Pragma("unroll") for (int m = 0; m < 4; ++m) _Pragma("unroll") for (int n = 0; n < 2; ++n) _Pragma("unroll") for (int k = 0; k < 2; ++k) \
;         acc[ai][bj][m][n] = __builtin_amdgcn_mfma_f32_16x16x32_bf16(Bt[n][k], At[m][k], acc[ai][bj][m][n], 0, 0, 0); __builtin_amdgcn_s_setprio(0); } while (0)
; #define PG8_WAIT_V(n) asm volatile("s_waitcnt vmcnt(" #n ")" ::: "memory")
; #define PG8_WAIT_L(n) asm volatile("s_waitcnt lgkmcnt(" #n ")" ::: "memory")
; template <class Epi, class Sched, bool ALIGN_EPI = false, bool SP2 = false>
; __device__ __forceinline__ void gemm_phase(PG8_LAS unsigned char* lds, const Gemm g, const Sched& S, const Epi& E) {
;     ...
;             const bool last = (t == nt - 2);
;             const char* a1 = cA + (size_t)(t + 1) * kstep;
;             const char* a2 = last ? nA : cA + (size_t)(t + 2) * kstep; const char* b2 = last ? nB : cB + (size_t)(t + 2) * kstep;
;             const char* a3 = a2 + kstep; const char* b3 = b2 + kstep;
;             if (last && has_next) S.a_ready(nxt);
;             if constexpr (SP2) {
;             PG8_LDB(B0, 0, 0); PG8_LDB(B1, 0, 1); PG8_SCHED; PG8_LDA(At, 0, 0); PG8_STAGE(PG8_SA(1, 1), a1 + hstepA, voffA);
;             PG8_WAIT_V(8); PG8_WAIT_L(0); PG8_BAR; PG8_MMA(0, 0, At, B0); PG8_MMA(0, 1, At, B1); PG8_BAR; PG8_SCHED;
;             PG8_LDA(At, 0, 1); PG8_STAGE(PG8_SB(0, 0), b2, voffB); PG8_STAGE(PG8_SB(0, 1), b2 + hstepB, voffB); PG8_STAGE(PG8_SA(0, 0), a2, voffA);
;             PG8_WAIT_V(8); PG8_WAIT_L(0); PG8_BAR; PG8_MMA(1, 0, At, B0); PG8_MMA(1, 1, At, B1); PG8_BAR; PG8_SCHED;
.LBB0_244:
	ds_read_b128 v[152:155], v147
	ds_read_b128 v[156:159], v147 offset:1024
	ds_read_b128 v[160:163], v147 offset:2048
	ds_read_b128 v[164:167], v147 offset:3072
	ds_read_b128 v[168:171], v148
	ds_read_b128 v[172:175], v148 offset:1024
	ds_read_b128 v[176:179], v148 offset:2048
	ds_read_b128 v[180:183], v148 offset:3072
	s_add_u32 s28, s26, 0xfffc0080
	s_addc_u32 s29, s27, -1
	s_cmp_eq_u32 s68, 12
	s_cselect_b32 s31, s15, s29
	s_cselect_b32 s30, s62, s28
	s_cselect_b32 s29, s13, s67
	s_cselect_b32 s28, s63, s66
	v_lshl_add_u64 v[184:185], s[26:27], 0, v[136:137]
	s_add_i32 m0, s25, 0xc000
	ds_read_b128 v[188:191], v149
	ds_read_b128 v[192:195], v149 offset:1024
	ds_read_b128 v[196:199], v149 offset:2048
	ds_read_b128 v[200:203], v149 offset:3072
	ds_read_b128 v[204:207], v149 offset:4096
	ds_read_b128 v[208:211], v149 offset:5120
	ds_read_b128 v[212:215], v149 offset:6144
	ds_read_b128 v[216:219], v149 offset:7168
	global_load_lds_dwordx4 v[184:185], off
	v_lshl_add_u64 v[184:185], s[26:27], 0, v[138:139]
	s_add_i32 m0, s25, 0xe000
	s_nop 0
	global_load_lds_dwordx4 v[184:185], off
	s_waitcnt vmcnt(8) lgkmcnt(0)
	s_barrier
	s_setprio 1
	v_mfma_f32_16x16x32_bf16 v[116:119], v[152:155], v[188:191], v[116:119]
	v_mfma_f32_16x16x32_bf16 v[108:111], v[160:163], v[188:191], v[108:111]
	v_mfma_f32_16x16x32_bf16 v[104:107], v[152:155], v[196:199], v[104:107]
	v_mfma_f32_16x16x32_bf16 v[100:103], v[160:163], v[196:199], v[100:103]
	v_mfma_f32_16x16x32_bf16 v[92:95], v[152:155], v[204:207], v[92:95]
	v_mfma_f32_16x16x32_bf16 v[84:87], v[160:163], v[204:207], v[84:87]
	v_mfma_f32_16x16x32_bf16 v[76:79], v[152:155], v[212:215], v[76:79]
	v_mfma_f32_16x16x32_bf16 v[68:71], v[160:163], v[212:215], v[68:71]
	v_mfma_f32_16x16x32_bf16 v[116:119], v[156:159], v[192:195], v[116:119]
	v_mfma_f32_16x16x32_bf16 v[108:111], v[164:167], v[192:195], v[108:111]
	v_mfma_f32_16x16x32_bf16 v[104:107], v[156:159], v[200:203], v[104:107]
	v_mfma_f32_16x16x32_bf16 v[100:103], v[164:167], v[200:203], v[100:103]
	v_mfma_f32_16x16x32_bf16 v[92:95], v[156:159], v[208:211], v[92:95]
	v_mfma_f32_16x16x32_bf16 v[84:87], v[164:167], v[208:211], v[84:87]
	v_mfma_f32_16x16x32_bf16 v[76:79], v[156:159], v[216:219], v[76:79]
	v_mfma_f32_16x16x32_bf16 v[68:71], v[164:167], v[216:219], v[68:71]
	s_setprio 0
	s_setprio 1
	v_mfma_f32_16x16x32_bf16 v[124:127], v[168:171], v[188:191], v[124:127]
	v_mfma_f32_16x16x32_bf16 v[120:123], v[176:179], v[188:191], v[120:123]
	v_mfma_f32_16x16x32_bf16 v[112:115], v[168:171], v[196:199], v[112:115]
	v_mfma_f32_16x16x32_bf16 v[96:99], v[176:179], v[196:199], v[96:99]
	v_mfma_f32_16x16x32_bf16 v[88:91], v[168:171], v[204:207], v[88:91]
	v_mfma_f32_16x16x32_bf16 v[80:83], v[176:179], v[204:207], v[80:83]
	v_mfma_f32_16x16x32_bf16 v[72:75], v[168:171], v[212:215], v[72:75]
	v_mfma_f32_16x16x32_bf16 v[64:67], v[176:179], v[212:215], v[64:67]
	v_mfma_f32_16x16x32_bf16 v[124:127], v[172:175], v[192:195], v[124:127]
	v_mfma_f32_16x16x32_bf16 v[120:123], v[180:183], v[192:195], v[120:123]
	v_mfma_f32_16x16x32_bf16 v[112:115], v[172:175], v[200:203], v[112:115]
	v_mfma_f32_16x16x32_bf16 v[96:99], v[180:183], v[200:203], v[96:99]
	v_mfma_f32_16x16x32_bf16 v[88:91], v[172:175], v[208:211], v[88:91]
	v_mfma_f32_16x16x32_bf16 v[80:83], v[180:183], v[208:211], v[80:83]
	v_mfma_f32_16x16x32_bf16 v[72:75], v[172:175], v[216:219], v[72:75]
	s_barrier
	v_mfma_f32_16x16x32_bf16 v[64:67], v[180:183], v[216:219], v[64:67]
	s_setprio 0
	s_add_i32 s58, s46, s36
	v_lshl_add_u64 v[184:185], s[28:29], 0, v[132:133]
	s_mov_b32 m0, s58
	ds_read_b128 v[188:191], v149 offset:16384
	ds_read_b128 v[192:195], v149 offset:17408
	ds_read_b128 v[196:199], v149 offset:18432
	ds_read_b128 v[200:203], v149 offset:19456
	ds_read_b128 v[204:207], v149 offset:20480
	ds_read_b128 v[208:211], v149 offset:21504
	ds_read_b128 v[212:215], v149 offset:22528
	ds_read_b128 v[216:219], v149 offset:23552
	global_load_lds_dwordx4 v[184:185], off
	s_add_i32 m0, s58, 0x2000
	s_add_u32 s58, s28, 0x40000
	v_lshl_add_u64 v[220:221], s[28:29], 0, v[128:129]
	s_addc_u32 s59, s29, 0
	s_add_i32 s69, s47, s36
	global_load_lds_dwordx4 v[220:221], off
	v_lshl_add_u64 v[222:223], s[58:59], 0, v[132:133]
	s_mov_b32 m0, s69
	v_lshl_add_u64 v[224:225], s[30:31], 0, v[130:131]
	global_load_lds_dwordx4 v[222:223], off
	v_lshl_add_u64 v[222:223], s[58:59], 0, v[128:129]
	s_add_i32 m0, s69, 0x2000
	s_nop 0
	global_load_lds_dwordx4 v[222:223], off
	v_lshl_add_u64 v[222:223], s[30:31], 0, v[134:135]
	s_mov_b32 m0, s25
	s_nop 0
	global_load_lds_dwordx4 v[222:223], off
	s_mov_b32 m0, s39
	s_nop 0
	global_load_lds_dwordx4 v[224:225], off
	s_waitcnt vmcnt(8) lgkmcnt(0)
	s_barrier
; #define PG8_STAGE(bufoff, gbase, voff) do { _Pragma("unroll") for (int _i = 0; _i < 2; ++_i) \
;         __builtin_amdgcn_global_load_lds((const unsigned*)((const char*)(gbase) + (voff)[_i]), (PG8_LAS unsigned*)(lds + (bufoff) + ldsw + _i * 8192), 16, 0, 0); } while (0)
; #define PG8_LDA(dst, b, h) do { _Pragma("unroll") for (int m = 0; m < 4; ++m) _Pragma("unroll") for (int k = 0; k < 2; ++k) dst[m][k] = *(const PG8_LAS bf16x8*)(lds + PG8_SA(b, h) + aoff + m * 2048 + k * 1024); } while (0)
; #define PG8_LDB(dst, b, h) do { _Pragma("unroll") for (int n = 0; n < 2; ++n) _Pragma("unroll") for (int k = 0; k < 2; ++k) dst[n][k] = *(const PG8_LAS bf16x8*)(lds + PG8_SB(b, h) + boff + n * 2048 + k * 1024); } while (0)
; #define PG8_MMA(ai, bj, At, Bt) do { __builtin_amdgcn_s_setprio(1); _Pragma("unroll") for (int m = 0; m < 4; ++m) _Pragma("unroll") for (int n = 0; n < 2; ++n) _Pragma("unroll") for (int k = 0; k < 2; ++k) \
;         acc[ai][bj][m][n] = __builtin_amdgcn_mfma_f32_16x16x32_bf16(Bt[n][k], At[m][k], acc[ai][bj][m][n], 0, 0, 0); __builtin_amdgcn_s_setprio(0); } while (0)
; #define PG8_WAIT_V(n) asm volatile("s_waitcnt vmcnt(" #n ")" ::: "memory")
; #define PG8_WAIT_L(n) asm volatile("s_waitcnt lgkmcnt(" #n ")" ::: "memory")
; #define PG8_BAR __builtin_amdgcn_s_barrier()
; #define PG8_SCHED __builtin_amdgcn_sched_barrier(0)
; template <class Epi, class Sched, bool ALIGN_EPI = false, bool SP2 = false>
; __device__ __forceinline__ void gemm_phase(PG8_LAS unsigned char* lds, const Gemm g, const Sched& S, const Epi& E) {
;     ...
;             PG8_WAIT_V(8); PG8_WAIT_L(0); PG8_BAR; PG8_MMA(1, 0, At, B0); PG8_MMA(1, 1, At, B1); PG8_BAR; PG8_SCHED;
;             PG8_LDB(B0, 1, 0); PG8_LDB(B1, 1, 1); PG8_SCHED; PG8_LDA(At, 1, 0); PG8_STAGE(PG8_SA(0, 1), a2 + hstepA, voffA);
;             PG8_WAIT_V(8); PG8_WAIT_L(0); PG8_BAR; PG8_MMA(0, 0, At, B0); PG8_MMA(0, 1, At, B1); PG8_BAR; PG8_SCHED;
	s_setprio 1
	v_mfma_f32_16x16x32_bf16 v[60:63], v[152:155], v[188:191], v[60:63]
	v_mfma_f32_16x16x32_bf16 v[52:55], v[160:163], v[188:191], v[52:55]
	v_mfma_f32_16x16x32_bf16 v[44:47], v[152:155], v[196:199], v[44:47]
	v_mfma_f32_16x16x32_bf16 v[36:39], v[160:163], v[196:199], v[36:39]
	v_mfma_f32_16x16x32_bf16 v[28:31], v[152:155], v[204:207], v[28:31]
	v_mfma_f32_16x16x32_bf16 v[20:23], v[160:163], v[204:207], v[20:23]
	v_mfma_f32_16x16x32_bf16 v[12:15], v[152:155], v[212:215], v[12:15]
	v_mfma_f32_16x16x32_bf16 v[4:7], v[160:163], v[212:215], v[4:7]
	v_mfma_f32_16x16x32_bf16 v[60:63], v[156:159], v[192:195], v[60:63]
	v_mfma_f32_16x16x32_bf16 v[52:55], v[164:167], v[192:195], v[52:55]
	v_mfma_f32_16x16x32_bf16 v[44:47], v[156:159], v[200:203], v[44:47]
	v_mfma_f32_16x16x32_bf16 v[36:39], v[164:167], v[200:203], v[36:39]
	v_mfma_f32_16x16x32_bf16 v[28:31], v[156:159], v[208:211], v[28:31]
	v_mfma_f32_16x16x32_bf16 v[20:23], v[164:167], v[208:211], v[20:23]
	v_mfma_f32_16x16x32_bf16 v[12:15], v[156:159], v[216:219], v[12:15]
	v_mfma_f32_16x16x32_bf16 v[4:7], v[164:167], v[216:219], v[4:7]
	s_setprio 0
	s_setprio 1
	v_mfma_f32_16x16x32_bf16 v[56:59], v[168:171], v[188:191], v[56:59]
	v_mfma_f32_16x16x32_bf16 v[48:51], v[176:179], v[188:191], v[48:51]
	v_mfma_f32_16x16x32_bf16 v[40:43], v[168:171], v[196:199], v[40:43]
	v_mfma_f32_16x16x32_bf16 v[32:35], v[176:179], v[196:199], v[32:35]
	v_mfma_f32_16x16x32_bf16 v[24:27], v[168:171], v[204:207], v[24:27]
	v_mfma_f32_16x16x32_bf16 v[16:19], v[176:179], v[204:207], v[16:19]
	v_mfma_f32_16x16x32_bf16 v[8:11], v[168:171], v[212:215], v[8:11]
	v_mfma_f32_16x16x32_bf16 v[0:3], v[176:179], v[212:215], v[0:3]
	v_mfma_f32_16x16x32_bf16 v[56:59], v[172:175], v[192:195], v[56:59]
	v_mfma_f32_16x16x32_bf16 v[48:51], v[180:183], v[192:195], v[48:51]
	v_mfma_f32_16x16x32_bf16 v[40:43], v[172:175], v[200:203], v[40:43]
	v_mfma_f32_16x16x32_bf16 v[32:35], v[180:183], v[200:203], v[32:35]
	v_mfma_f32_16x16x32_bf16 v[24:27], v[172:175], v[208:211], v[24:27]
	v_mfma_f32_16x16x32_bf16 v[16:19], v[180:183], v[208:211], v[16:19]
	v_mfma_f32_16x16x32_bf16 v[8:11], v[172:175], v[216:219], v[8:11]
	s_barrier
	v_mfma_f32_16x16x32_bf16 v[0:3], v[180:183], v[216:219], v[0:3]
	s_setprio 0
	s_add_i32 s58, 0, 0x18000
	v_add_u32_e32 v151, s58, v145
	s_add_i32 s59, 0, 0x1c000
	ds_read_b128 v[152:155], v151
	ds_read_b128 v[156:159], v151 offset:1024
	ds_read_b128 v[160:163], v151 offset:2048
	ds_read_b128 v[164:167], v151 offset:3072
	v_add_u32_e32 v151, s59, v145
	ds_read_b128 v[168:171], v151
	ds_read_b128 v[172:175], v151 offset:1024
	ds_read_b128 v[176:179], v151 offset:2048
	ds_read_b128 v[180:183], v151 offset:3072
	s_add_u32 s30, s30, 0x40000
	s_addc_u32 s31, s31, 0
	s_mov_b32 m0, s40
	v_lshl_add_u64 v[226:227], s[30:31], 0, v[134:135]
	ds_read_b128 v[188:191], v149 offset:32768
	ds_read_b128 v[192:195], v149 offset:33792
	ds_read_b128 v[196:199], v149 offset:34816
	ds_read_b128 v[200:203], v149 offset:35840
	ds_read_b128 v[204:207], v149 offset:36864
	ds_read_b128 v[208:211], v149 offset:37888
	ds_read_b128 v[212:215], v149 offset:38912
	ds_read_b128 v[216:219], v149 offset:39936
	global_load_lds_dwordx4 v[226:227], off
	v_lshl_add_u64 v[226:227], s[30:31], 0, v[130:131]
	s_mov_b32 m0, s41
	s_nop 0
	global_load_lds_dwordx4 v[226:227], off
	s_waitcnt vmcnt(8) lgkmcnt(0)
	s_barrier
	s_setprio 1
	v_mfma_f32_16x16x32_bf16 v[116:119], v[152:155], v[188:191], v[116:119]
	v_mfma_f32_16x16x32_bf16 v[108:111], v[160:163], v[188:191], v[108:111]
	v_mfma_f32_16x16x32_bf16 v[104:107], v[152:155], v[196:199], v[104:107]
	v_mfma_f32_16x16x32_bf16 v[100:103], v[160:163], v[196:199], v[100:103]
	v_mfma_f32_16x16x32_bf16 v[92:95], v[152:155], v[204:207], v[92:95]
	v_mfma_f32_16x16x32_bf16 v[84:87], v[160:163], v[204:207], v[84:87]
	v_mfma_f32_16x16x32_bf16 v[76:79], v[152:155], v[212:215], v[76:79]
	v_mfma_f32_16x16x32_bf16 v[68:71], v[160:163], v[212:215], v[68:71]
	v_mfma_f32_16x16x32_bf16 v[116:119], v[156:159], v[192:195], v[116:119]
	v_mfma_f32_16x16x32_bf16 v[108:111], v[164:167], v[192:195], v[108:111]
	v_mfma_f32_16x16x32_bf16 v[104:107], v[156:159], v[200:203], v[104:107]
	v_mfma_f32_16x16x32_bf16 v[100:103], v[164:167], v[200:203], v[100:103]
	v_mfma_f32_16x16x32_bf16 v[92:95], v[156:159], v[208:211], v[92:95]
	v_mfma_f32_16x16x32_bf16 v[84:87], v[164:167], v[208:211], v[84:87]
	v_mfma_f32_16x16x32_bf16 v[76:79], v[156:159], v[216:219], v[76:79]
	v_mfma_f32_16x16x32_bf16 v[68:71], v[164:167], v[216:219], v[68:71]
	s_setprio 0
	s_setprio 1
	v_mfma_f32_16x16x32_bf16 v[124:127], v[168:171], v[188:191], v[124:127]
	v_mfma_f32_16x16x32_bf16 v[120:123], v[176:179], v[188:191], v[120:123]
	v_mfma_f32_16x16x32_bf16 v[112:115], v[168:171], v[196:199], v[112:115]
	v_mfma_f32_16x16x32_bf16 v[96:99], v[176:179], v[196:199], v[96:99]
	v_mfma_f32_16x16x32_bf16 v[88:91], v[168:171], v[204:207], v[88:91]
	v_mfma_f32_16x16x32_bf16 v[80:83], v[176:179], v[204:207], v[80:83]
	v_mfma_f32_16x16x32_bf16 v[72:75], v[168:171], v[212:215], v[72:75]
	v_mfma_f32_16x16x32_bf16 v[64:67], v[176:179], v[212:215], v[64:67]
	v_mfma_f32_16x16x32_bf16 v[124:127], v[172:175], v[192:195], v[124:127]
	v_mfma_f32_16x16x32_bf16 v[120:123], v[180:183], v[192:195], v[120:123]
	v_mfma_f32_16x16x32_bf16 v[112:115], v[172:175], v[200:203], v[112:115]
	v_mfma_f32_16x16x32_bf16 v[96:99], v[180:183], v[200:203], v[96:99]
	v_mfma_f32_16x16x32_bf16 v[88:91], v[172:175], v[208:211], v[88:91]
	v_mfma_f32_16x16x32_bf16 v[80:83], v[180:183], v[208:211], v[80:83]
	v_mfma_f32_16x16x32_bf16 v[72:75], v[172:175], v[216:219], v[72:75]
	s_barrier
; #define PG8_STAGE(bufoff, gbase, voff) do { _Pragma("unroll") for (int _i = 0; _i < 2; ++_i) \
;         __builtin_amdgcn_global_load_lds((const unsigned*)((const char*)(gbase) + (voff)[_i]), (PG8_LAS unsigned*)(lds + (bufoff) + ldsw + _i * 8192), 16, 0, 0); } while (0)
; #define PG8_LDA(dst, b, h) do { _Pragma("unroll") for (int m = 0; m < 4; ++m) _Pragma("unroll") for (int k = 0; k < 2; ++k) dst[m][k] = *(const PG8_LAS bf16x8*)(lds + PG8_SA(b, h) + aoff + m * 2048 + k * 1024); } while (0)
; #define PG8_MMA(ai, bj, At, Bt) do { __builtin_amdgcn_s_setprio(1); _Pragma("unroll") for (int m = 0; m < 4; ++m) _Pragma("unroll") for (int n = 0; n < 2; ++n) _Pragma("unroll") for (int k = 0; k < 2; ++k) \
;         acc[ai][bj][m][n] = __builtin_amdgcn_mfma_f32_16x16x32_bf16(Bt[n][k], At[m][k], acc[ai][bj][m][n], 0, 0, 0); __builtin_amdgcn_s_setprio(0); } while (0)
; #define PG8_WAIT_V(n) asm volatile("s_waitcnt vmcnt(" #n ")" ::: "memory")
; #define PG8_WAIT_L(n) asm volatile("s_waitcnt lgkmcnt(" #n ")" ::: "memory")
; #define PG8_BAR __builtin_amdgcn_s_barrier()
; #define PG8_SCHED __builtin_amdgcn_sched_barrier(0)
; template <class Epi, class Sched, bool ALIGN_EPI = false, bool SP2 = false>
; __device__ __forceinline__ void gemm_phase(PG8_LAS unsigned char* lds, const Gemm g, const Sched& S, const Epi& E) {
;     ...
;             PG8_LDA(At, 1, 1); PG8_STAGE(PG8_SB(1, 0), b3, voffB); PG8_STAGE(PG8_SB(1, 1), b3 + hstepB, voffB); PG8_STAGE(PG8_SA(1, 0), a3, voffA);
;             PG8_WAIT_V(8); PG8_WAIT_L(0); PG8_BAR; PG8_MMA(1, 0, At, B0); PG8_MMA(1, 1, At, B1); PG8_BAR; PG8_SCHED;
	v_mfma_f32_16x16x32_bf16 v[64:67], v[180:183], v[216:219], v[64:67]
	s_setprio 0
	s_add_i32 s30, s58, s36
	v_lshl_add_u64 v[184:185], v[184:185], 0, s[8:9]
	s_mov_b32 m0, s30
	ds_read_b128 v[188:191], v149 offset:49152
	ds_read_b128 v[192:195], v149 offset:50176
	ds_read_b128 v[196:199], v149 offset:51200
	ds_read_b128 v[200:203], v149 offset:52224
	ds_read_b128 v[204:207], v149 offset:53248
	ds_read_b128 v[208:211], v149 offset:54272
	ds_read_b128 v[212:215], v149 offset:55296
	ds_read_b128 v[216:219], v149 offset:56320
	global_load_lds_dwordx4 v[184:185], off
	s_add_i32 m0, s30, 0x2000
	s_add_u32 s28, s28, 0x40080
	v_lshl_add_u64 v[184:185], v[220:221], 0, s[8:9]
	s_addc_u32 s29, s29, 0
	s_add_i32 s30, s59, s36
	global_load_lds_dwordx4 v[184:185], off
	v_lshl_add_u64 v[184:185], s[28:29], 0, v[132:133]
	s_mov_b32 m0, s30
	s_nop 0
	global_load_lds_dwordx4 v[184:185], off
	v_lshl_add_u64 v[184:185], s[28:29], 0, v[128:129]
	s_add_i32 m0, s30, 0x2000
	s_nop 0
	global_load_lds_dwordx4 v[184:185], off
	v_lshl_add_u64 v[184:185], v[222:223], 0, s[8:9]
	s_mov_b32 m0, s43
	s_nop 0
	global_load_lds_dwordx4 v[184:185], off
	v_lshl_add_u64 v[184:185], v[224:225], 0, s[8:9]
	s_mov_b32 m0, s44
	s_nop 0
	global_load_lds_dwordx4 v[184:185], off
	s_waitcnt vmcnt(8) lgkmcnt(0)
	s_barrier
	s_setprio 1
	v_mfma_f32_16x16x32_bf16 v[60:63], v[152:155], v[188:191], v[60:63]
	v_mfma_f32_16x16x32_bf16 v[52:55], v[160:163], v[188:191], v[52:55]
	v_mfma_f32_16x16x32_bf16 v[44:47], v[152:155], v[196:199], v[44:47]
	v_mfma_f32_16x16x32_bf16 v[36:39], v[160:163], v[196:199], v[36:39]
	v_mfma_f32_16x16x32_bf16 v[28:31], v[152:155], v[204:207], v[28:31]
	v_mfma_f32_16x16x32_bf16 v[20:23], v[160:163], v[204:207], v[20:23]
	v_mfma_f32_16x16x32_bf16 v[12:15], v[152:155], v[212:215], v[12:15]
	v_mfma_f32_16x16x32_bf16 v[4:7], v[160:163], v[212:215], v[4:7]
	v_mfma_f32_16x16x32_bf16 v[60:63], v[156:159], v[192:195], v[60:63]
	v_mfma_f32_16x16x32_bf16 v[52:55], v[164:167], v[192:195], v[52:55]
	v_mfma_f32_16x16x32_bf16 v[44:47], v[156:159], v[200:203], v[44:47]
	v_mfma_f32_16x16x32_bf16 v[36:39], v[164:167], v[200:203], v[36:39]
	v_mfma_f32_16x16x32_bf16 v[28:31], v[156:159], v[208:211], v[28:31]
	v_mfma_f32_16x16x32_bf16 v[20:23], v[164:167], v[208:211], v[20:23]
	v_mfma_f32_16x16x32_bf16 v[12:15], v[156:159], v[216:219], v[12:15]
	v_mfma_f32_16x16x32_bf16 v[4:7], v[164:167], v[216:219], v[4:7]
	s_setprio 0
	s_setprio 1
	v_mfma_f32_16x16x32_bf16 v[56:59], v[168:171], v[188:191], v[56:59]
	v_mfma_f32_16x16x32_bf16 v[48:51], v[176:179], v[188:191], v[48:51]
	v_mfma_f32_16x16x32_bf16 v[40:43], v[168:171], v[196:199], v[40:43]
	v_mfma_f32_16x16x32_bf16 v[32:35], v[176:179], v[196:199], v[32:35]
	v_mfma_f32_16x16x32_bf16 v[24:27], v[168:171], v[204:207], v[24:27]
	v_mfma_f32_16x16x32_bf16 v[16:19], v[176:179], v[204:207], v[16:19]
	v_mfma_f32_16x16x32_bf16 v[8:11], v[168:171], v[212:215], v[8:11]
	v_mfma_f32_16x16x32_bf16 v[0:3], v[176:179], v[212:215], v[0:3]
	v_mfma_f32_16x16x32_bf16 v[56:59], v[172:175], v[192:195], v[56:59]
	v_mfma_f32_16x16x32_bf16 v[48:51], v[180:183], v[192:195], v[48:51]
	v_mfma_f32_16x16x32_bf16 v[40:43], v[172:175], v[200:203], v[40:43]
	v_mfma_f32_16x16x32_bf16 v[32:35], v[180:183], v[200:203], v[32:35]
	v_mfma_f32_16x16x32_bf16 v[24:27], v[172:175], v[208:211], v[24:27]
	v_mfma_f32_16x16x32_bf16 v[16:19], v[180:183], v[208:211], v[16:19]
	v_mfma_f32_16x16x32_bf16 v[8:11], v[172:175], v[216:219], v[8:11]
	s_barrier
	v_mfma_f32_16x16x32_bf16 v[0:3], v[180:183], v[216:219], v[0:3]
	s_setprio 0
	s_add_i32 s68, s68, 2
	s_add_u32 s26, s26, 0x100
	s_addc_u32 s27, s27, 0
	s_add_u32 s66, s66, 0x100
	s_addc_u32 s67, s67, 0
	s_cmp_gt_u32 s68, 13
	s_cbranch_scc0 .LBB0_244
	s_and_b64 vcc, exec, s[10:11]
	s_cbranch_vccz .LBB0_247
	s_barrier

; #define PG8_STAGE(bufoff, gbase, voff) do { _Pragma("unroll") for (int _i = 0; _i < 2; ++_i) \
;         __builtin_amdgcn_global_load_lds((const unsigned*)((const char*)(gbase) + (voff)[_i]), (PG8_LAS unsigned*)(lds + (bufoff) + ldsw + _i * 8192), 16, 0, 0); } while (0)
; #define PG8_LDA(dst, b, h) do { _Pragma("unroll") for (int m = 0; m < 4; ++m) _Pragma("unroll") for (int k = 0; k < 2; ++k) dst[m][k] = *(const PG8_LAS bf16x8*)(lds + PG8_SA(b, h) + aoff + m * 2048 + k * 1024); } while (0)
; #define PG8_LDB(dst, b, h) do { _Pragma("unroll") for (int n = 0; n < 2; ++n) _Pragma("unroll") for (int k = 0; k < 2; ++k) dst[n][k] = *(const PG8_LAS bf16x8*)(lds + PG8_SB(b, h) + boff + n * 2048 + k * 1024); } while (0)
; #define PG8_MMA(ai, bj, At, Bt) do { __builtin_amdgcn_s_setprio(1); _Pragma("unroll") for (int m = 0; m < 4; ++m) _Pragma("unroll") for (int n = 0; n < 2; ++n) _Pragma("unroll") for (int k = 0; k < 2; ++k) \
;         acc[ai][bj][m][n] = __builtin_amdgcn_mfma_f32_16x16x32_bf16(Bt[n][k], At[m][k], acc[ai][bj][m][n], 0, 0, 0); __builtin_amdgcn_s_setprio(0); } while (0)
; #define PG8_WAIT_V(n) asm volatile("s_waitcnt vmcnt(" #n ")" ::: "memory")
; #define PG8_WAIT_L(n) asm volatile("s_waitcnt lgkmcnt(" #n ")" ::: "memory")
; template <class Epi, class Sched, bool ALIGN_EPI = false, bool SP2 = false>
; __device__ __forceinline__ void gemm_phase(PG8_LAS unsigned char* lds, const Gemm g, const Sched& S, const Epi& E) {
;     ...
;             const bool last = (t == nt - 2);
;             const char* a1 = cA + (size_t)(t + 1) * kstep;
;             const char* a2 = last ? nA : cA + (size_t)(t + 2) * kstep; const char* b2 = last ? nB : cB + (size_t)(t + 2) * kstep;
;             const char* a3 = a2 + kstep; const char* b3 = b2 + kstep;
;             if (last && has_next) S.a_ready(nxt);
;             if constexpr (SP2) {
;             PG8_LDB(B0, 0, 0); PG8_LDB(B1, 0, 1); PG8_SCHED; PG8_LDA(At, 0, 0); PG8_STAGE(PG8_SA(1, 1), a1 + hstepA, voffA);
;             PG8_WAIT_V(8); PG8_WAIT_L(0); PG8_BAR; PG8_MMA(0, 0, At, B0); PG8_MMA(0, 1, At, B1); PG8_BAR; PG8_SCHED;
;             PG8_LDA(At, 0, 1); PG8_STAGE(PG8_SB(0, 0), b2, voffB); PG8_STAGE(PG8_SB(0, 1), b2 + hstepB, voffB); PG8_STAGE(PG8_SA(0, 0), a2, voffA);
;             PG8_WAIT_V(8); PG8_WAIT_L(0); PG8_BAR; PG8_MMA(1, 0, At, B0); PG8_MMA(1, 1, At, B1); PG8_BAR; PG8_SCHED;
.LBB0_318:
	ds_read_b128 v[128:131], v191
	ds_read_b128 v[132:135], v191 offset:1024
	ds_read_b128 v[136:139], v191 offset:2048
	ds_read_b128 v[140:143], v191 offset:3072
	ds_read_b128 v[144:147], v192
	ds_read_b128 v[148:151], v192 offset:1024
	ds_read_b128 v[168:171], v192 offset:2048
	ds_read_b128 v[172:175], v192 offset:3072
	s_add_u32 s28, s26, 0x100
	s_addc_u32 s29, s27, 0
	s_cmp_eq_u32 s72, 40
	s_cselect_b32 s35, s11, s29
	s_cselect_b32 s34, s10, s28
	s_cselect_b32 s31, s23, s71
	s_cselect_b32 s30, s22, s70
	v_lshl_add_u64 v[184:185], s[26:27], 0, v[160:161]
	s_add_i32 m0, s39, 0xc000
	ds_read_b128 v[176:179], v193
	ds_read_b128 v[180:183], v193 offset:1024
	ds_read_b128 v[196:199], v193 offset:2048
	ds_read_b128 v[200:203], v193 offset:3072
	ds_read_b128 v[204:207], v193 offset:4096
	ds_read_b128 v[208:211], v193 offset:5120
	ds_read_b128 v[212:215], v193 offset:6144
	ds_read_b128 v[216:219], v193 offset:7168
	global_load_lds_dwordx4 v[184:185], off
	v_lshl_add_u64 v[184:185], s[26:27], 0, v[162:163]
	s_add_i32 m0, s39, 0xe000
	s_nop 0
	global_load_lds_dwordx4 v[184:185], off
	s_waitcnt vmcnt(8) lgkmcnt(0)
	s_barrier
	s_setprio 1
	v_mfma_f32_16x16x32_bf16 v[124:127], v[128:131], v[176:179], v[124:127]
	v_mfma_f32_16x16x32_bf16 v[120:123], v[136:139], v[176:179], v[120:123]
	v_mfma_f32_16x16x32_bf16 v[108:111], v[128:131], v[196:199], v[108:111]
	v_mfma_f32_16x16x32_bf16 v[104:107], v[136:139], v[196:199], v[104:107]
	v_mfma_f32_16x16x32_bf16 v[92:95], v[128:131], v[204:207], v[92:95]
	v_mfma_f32_16x16x32_bf16 v[88:91], v[136:139], v[204:207], v[88:91]
	v_mfma_f32_16x16x32_bf16 v[76:79], v[128:131], v[212:215], v[76:79]
	v_mfma_f32_16x16x32_bf16 v[72:75], v[136:139], v[212:215], v[72:75]
	v_mfma_f32_16x16x32_bf16 v[124:127], v[132:135], v[180:183], v[124:127]
	v_mfma_f32_16x16x32_bf16 v[120:123], v[140:143], v[180:183], v[120:123]
	v_mfma_f32_16x16x32_bf16 v[108:111], v[132:135], v[200:203], v[108:111]
	v_mfma_f32_16x16x32_bf16 v[104:107], v[140:143], v[200:203], v[104:107]
	v_mfma_f32_16x16x32_bf16 v[92:95], v[132:135], v[208:211], v[92:95]
	v_mfma_f32_16x16x32_bf16 v[88:91], v[140:143], v[208:211], v[88:91]
	v_mfma_f32_16x16x32_bf16 v[76:79], v[132:135], v[216:219], v[76:79]
	v_mfma_f32_16x16x32_bf16 v[72:75], v[140:143], v[216:219], v[72:75]
	s_setprio 0
	s_setprio 1
	v_mfma_f32_16x16x32_bf16 v[116:119], v[144:147], v[176:179], v[116:119]
	v_mfma_f32_16x16x32_bf16 v[112:115], v[168:171], v[176:179], v[112:115]
	v_mfma_f32_16x16x32_bf16 v[100:103], v[144:147], v[196:199], v[100:103]
	v_mfma_f32_16x16x32_bf16 v[96:99], v[168:171], v[196:199], v[96:99]
	v_mfma_f32_16x16x32_bf16 v[84:87], v[144:147], v[204:207], v[84:87]
	v_mfma_f32_16x16x32_bf16 v[80:83], v[168:171], v[204:207], v[80:83]
	v_mfma_f32_16x16x32_bf16 v[68:71], v[144:147], v[212:215], v[68:71]
	v_mfma_f32_16x16x32_bf16 v[64:67], v[168:171], v[212:215], v[64:67]
	v_mfma_f32_16x16x32_bf16 v[116:119], v[148:151], v[180:183], v[116:119]
	v_mfma_f32_16x16x32_bf16 v[112:115], v[172:175], v[180:183], v[112:115]
	v_mfma_f32_16x16x32_bf16 v[100:103], v[148:151], v[200:203], v[100:103]
	v_mfma_f32_16x16x32_bf16 v[96:99], v[172:175], v[200:203], v[96:99]
	v_mfma_f32_16x16x32_bf16 v[84:87], v[148:151], v[208:211], v[84:87]
	v_mfma_f32_16x16x32_bf16 v[80:83], v[172:175], v[208:211], v[80:83]
	v_mfma_f32_16x16x32_bf16 v[68:71], v[148:151], v[216:219], v[68:71]
	s_barrier
	v_mfma_f32_16x16x32_bf16 v[64:67], v[172:175], v[216:219], v[64:67]
	s_setprio 0
	s_add_i32 s26, s49, s38
	v_lshl_add_u64 v[184:185], s[30:31], 0, v[154:155]
	s_mov_b32 m0, s26
	ds_read_b128 v[176:179], v193 offset:16384
	ds_read_b128 v[180:183], v193 offset:17408
	ds_read_b128 v[196:199], v193 offset:18432
	ds_read_b128 v[200:203], v193 offset:19456
	ds_read_b128 v[204:207], v193 offset:20480
	ds_read_b128 v[208:211], v193 offset:21504
	ds_read_b128 v[212:215], v193 offset:22528
	ds_read_b128 v[216:219], v193 offset:23552
	global_load_lds_dwordx4 v[184:185], off
	s_add_i32 m0, s26, 0x2000
	s_add_u32 s26, s30, 0xb0000
	v_lshl_add_u64 v[220:221], s[30:31], 0, v[158:159]
	s_addc_u32 s27, s31, 0
	s_add_i32 s58, s62, s38
	global_load_lds_dwordx4 v[220:221], off
	v_lshl_add_u64 v[222:223], s[26:27], 0, v[154:155]
	s_mov_b32 m0, s58
	v_lshl_add_u64 v[224:225], s[34:35], 0, v[156:157]
	global_load_lds_dwordx4 v[222:223], off
	v_lshl_add_u64 v[222:223], s[26:27], 0, v[158:159]
	s_add_i32 m0, s58, 0x2000
	s_nop 0
	global_load_lds_dwordx4 v[222:223], off
	v_lshl_add_u64 v[222:223], s[34:35], 0, v[152:153]
	s_mov_b32 m0, s39
	s_nop 0
	global_load_lds_dwordx4 v[222:223], off
	s_mov_b32 m0, s40
	s_nop 0
	global_load_lds_dwordx4 v[224:225], off
	s_waitcnt vmcnt(8) lgkmcnt(0)
	s_barrier
; #define PG8_STAGE(bufoff, gbase, voff) do { _Pragma("unroll") for (int _i = 0; _i < 2; ++_i) \
;         __builtin_amdgcn_global_load_lds((const unsigned*)((const char*)(gbase) + (voff)[_i]), (PG8_LAS unsigned*)(lds + (bufoff) + ldsw + _i * 8192), 16, 0, 0); } while (0)
; #define PG8_LDA(dst, b, h) do { _Pragma("unroll") for (int m = 0; m < 4; ++m) _Pragma("unroll") for (int k = 0; k < 2; ++k) dst[m][k] = *(const PG8_LAS bf16x8*)(lds + PG8_SA(b, h) + aoff + m * 2048 + k * 1024); } while (0)
; #define PG8_LDB(dst, b, h) do { _Pragma("unroll") for (int n = 0; n < 2; ++n) _Pragma("unroll") for (int k = 0; k < 2; ++k) dst[n][k] = *(const PG8_LAS bf16x8*)(lds + PG8_SB(b, h) + boff + n * 2048 + k * 1024); } while (0)
; #define PG8_MMA(ai, bj, At, Bt) do { __builtin_amdgcn_s_setprio(1); _Pragma("unroll") for (int m = 0; m < 4; ++m) _Pragma("unroll") for (int n = 0; n < 2; ++n) _Pragma("unroll") for (int k = 0; k < 2; ++k) \
;         acc[ai][bj][m][n] = __builtin_amdgcn_mfma_f32_16x16x32_bf16(Bt[n][k], At[m][k], acc[ai][bj][m][n], 0, 0, 0); __builtin_amdgcn_s_setprio(0); } while (0)
; #define PG8_WAIT_V(n) asm volatile("s_waitcnt vmcnt(" #n ")" ::: "memory")
; #define PG8_WAIT_L(n) asm volatile("s_waitcnt lgkmcnt(" #n ")" ::: "memory")
; #define PG8_BAR __builtin_amdgcn_s_barrier()
; #define PG8_SCHED __builtin_amdgcn_sched_barrier(0)
; template <class Epi, class Sched, bool ALIGN_EPI = false, bool SP2 = false>
; __device__ __forceinline__ void gemm_phase(PG8_LAS unsigned char* lds, const Gemm g, const Sched& S, const Epi& E) {
;     ...
;             PG8_WAIT_V(8); PG8_WAIT_L(0); PG8_BAR; PG8_MMA(1, 0, At, B0); PG8_MMA(1, 1, At, B1); PG8_BAR; PG8_SCHED;
;             PG8_LDB(B0, 1, 0); PG8_LDB(B1, 1, 1); PG8_SCHED; PG8_LDA(At, 1, 0); PG8_STAGE(PG8_SA(0, 1), a2 + hstepA, voffA);
;             PG8_WAIT_V(8); PG8_WAIT_L(0); PG8_BAR; PG8_MMA(0, 0, At, B0); PG8_MMA(0, 1, At, B1); PG8_BAR; PG8_SCHED;
	s_setprio 1
	v_mfma_f32_16x16x32_bf16 v[60:63], v[128:131], v[176:179], v[60:63]
	v_mfma_f32_16x16x32_bf16 v[56:59], v[136:139], v[176:179], v[56:59]
	v_mfma_f32_16x16x32_bf16 v[44:47], v[128:131], v[196:199], v[44:47]
	v_mfma_f32_16x16x32_bf16 v[40:43], v[136:139], v[196:199], v[40:43]
	v_mfma_f32_16x16x32_bf16 v[28:31], v[128:131], v[204:207], v[28:31]
	v_mfma_f32_16x16x32_bf16 v[24:27], v[136:139], v[204:207], v[24:27]
	v_mfma_f32_16x16x32_bf16 v[12:15], v[128:131], v[212:215], v[12:15]
	v_mfma_f32_16x16x32_bf16 v[8:11], v[136:139], v[212:215], v[8:11]
	v_mfma_f32_16x16x32_bf16 v[60:63], v[132:135], v[180:183], v[60:63]
	v_mfma_f32_16x16x32_bf16 v[56:59], v[140:143], v[180:183], v[56:59]
	v_mfma_f32_16x16x32_bf16 v[44:47], v[132:135], v[200:203], v[44:47]
	v_mfma_f32_16x16x32_bf16 v[40:43], v[140:143], v[200:203], v[40:43]
	v_mfma_f32_16x16x32_bf16 v[28:31], v[132:135], v[208:211], v[28:31]
	v_mfma_f32_16x16x32_bf16 v[24:27], v[140:143], v[208:211], v[24:27]
	v_mfma_f32_16x16x32_bf16 v[12:15], v[132:135], v[216:219], v[12:15]
	v_mfma_f32_16x16x32_bf16 v[8:11], v[140:143], v[216:219], v[8:11]
	s_setprio 0
	s_setprio 1
	v_mfma_f32_16x16x32_bf16 v[52:55], v[144:147], v[176:179], v[52:55]
	v_mfma_f32_16x16x32_bf16 v[48:51], v[168:171], v[176:179], v[48:51]
	v_mfma_f32_16x16x32_bf16 v[36:39], v[144:147], v[196:199], v[36:39]
	v_mfma_f32_16x16x32_bf16 v[32:35], v[168:171], v[196:199], v[32:35]
	v_mfma_f32_16x16x32_bf16 v[20:23], v[144:147], v[204:207], v[20:23]
	v_mfma_f32_16x16x32_bf16 v[16:19], v[168:171], v[204:207], v[16:19]
	v_mfma_f32_16x16x32_bf16 v[4:7], v[144:147], v[212:215], v[4:7]
	v_mfma_f32_16x16x32_bf16 v[0:3], v[168:171], v[212:215], v[0:3]
	v_mfma_f32_16x16x32_bf16 v[52:55], v[148:151], v[180:183], v[52:55]
	v_mfma_f32_16x16x32_bf16 v[48:51], v[172:175], v[180:183], v[48:51]
	v_mfma_f32_16x16x32_bf16 v[36:39], v[148:151], v[200:203], v[36:39]
	v_mfma_f32_16x16x32_bf16 v[32:35], v[172:175], v[200:203], v[32:35]
	v_mfma_f32_16x16x32_bf16 v[20:23], v[148:151], v[208:211], v[20:23]
	v_mfma_f32_16x16x32_bf16 v[16:19], v[172:175], v[208:211], v[16:19]
	v_mfma_f32_16x16x32_bf16 v[4:7], v[148:151], v[216:219], v[4:7]
	s_barrier
	v_mfma_f32_16x16x32_bf16 v[0:3], v[172:175], v[216:219], v[0:3]
	s_setprio 0
	s_add_i32 s58, 0, 0x18000
	s_add_i32 s59, 0, 0x1c000
	v_add_u32_e32 v140, s58, v189
	v_add_u32_e32 v172, s59, v189
	ds_read_b128 v[128:131], v140
	ds_read_b128 v[132:135], v140 offset:1024
	ds_read_b128 v[136:139], v140 offset:2048
	ds_read_b128 v[140:143], v140 offset:3072
	ds_read_b128 v[144:147], v172
	ds_read_b128 v[148:151], v172 offset:1024
	ds_read_b128 v[168:171], v172 offset:2048
	ds_read_b128 v[172:175], v172 offset:3072
	s_add_u32 s26, s34, 0xb0000
	s_addc_u32 s27, s35, 0
	s_mov_b32 m0, s41
	v_lshl_add_u64 v[226:227], s[26:27], 0, v[152:153]
	ds_read_b128 v[176:179], v193 offset:32768
	ds_read_b128 v[180:183], v193 offset:33792
	ds_read_b128 v[196:199], v193 offset:34816
	ds_read_b128 v[200:203], v193 offset:35840
	ds_read_b128 v[204:207], v193 offset:36864
	ds_read_b128 v[208:211], v193 offset:37888
	ds_read_b128 v[212:215], v193 offset:38912
	ds_read_b128 v[216:219], v193 offset:39936
	global_load_lds_dwordx4 v[226:227], off
	v_lshl_add_u64 v[226:227], s[26:27], 0, v[156:157]
	s_mov_b32 m0, s42
	s_nop 0
	global_load_lds_dwordx4 v[226:227], off
	s_waitcnt vmcnt(8) lgkmcnt(0)
	s_barrier
	s_setprio 1
	v_mfma_f32_16x16x32_bf16 v[124:127], v[128:131], v[176:179], v[124:127]
	v_mfma_f32_16x16x32_bf16 v[120:123], v[136:139], v[176:179], v[120:123]
	v_mfma_f32_16x16x32_bf16 v[108:111], v[128:131], v[196:199], v[108:111]
	v_mfma_f32_16x16x32_bf16 v[104:107], v[136:139], v[196:199], v[104:107]
	v_mfma_f32_16x16x32_bf16 v[92:95], v[128:131], v[204:207], v[92:95]
	v_mfma_f32_16x16x32_bf16 v[88:91], v[136:139], v[204:207], v[88:91]
	v_mfma_f32_16x16x32_bf16 v[76:79], v[128:131], v[212:215], v[76:79]
	v_mfma_f32_16x16x32_bf16 v[72:75], v[136:139], v[212:215], v[72:75]
	v_mfma_f32_16x16x32_bf16 v[124:127], v[132:135], v[180:183], v[124:127]
	v_mfma_f32_16x16x32_bf16 v[120:123], v[140:143], v[180:183], v[120:123]
	v_mfma_f32_16x16x32_bf16 v[108:111], v[132:135], v[200:203], v[108:111]
	v_mfma_f32_16x16x32_bf16 v[104:107], v[140:143], v[200:203], v[104:107]
	v_mfma_f32_16x16x32_bf16 v[92:95], v[132:135], v[208:211], v[92:95]
	v_mfma_f32_16x16x32_bf16 v[88:91], v[140:143], v[208:211], v[88:91]
	v_mfma_f32_16x16x32_bf16 v[76:79], v[132:135], v[216:219], v[76:79]
	v_mfma_f32_16x16x32_bf16 v[72:75], v[140:143], v[216:219], v[72:75]
	s_setprio 0
	s_setprio 1
	v_mfma_f32_16x16x32_bf16 v[116:119], v[144:147], v[176:179], v[116:119]
	v_mfma_f32_16x16x32_bf16 v[112:115], v[168:171], v[176:179], v[112:115]
	v_mfma_f32_16x16x32_bf16 v[100:103], v[144:147], v[196:199], v[100:103]
	v_mfma_f32_16x16x32_bf16 v[96:99], v[168:171], v[196:199], v[96:99]
	v_mfma_f32_16x16x32_bf16 v[84:87], v[144:147], v[204:207], v[84:87]
	v_mfma_f32_16x16x32_bf16 v[80:83], v[168:171], v[204:207], v[80:83]
	v_mfma_f32_16x16x32_bf16 v[68:71], v[144:147], v[212:215], v[68:71]
	v_mfma_f32_16x16x32_bf16 v[64:67], v[168:171], v[212:215], v[64:67]
	v_mfma_f32_16x16x32_bf16 v[116:119], v[148:151], v[180:183], v[116:119]
	v_mfma_f32_16x16x32_bf16 v[112:115], v[172:175], v[180:183], v[112:115]
	v_mfma_f32_16x16x32_bf16 v[100:103], v[148:151], v[200:203], v[100:103]
	v_mfma_f32_16x16x32_bf16 v[96:99], v[172:175], v[200:203], v[96:99]
	v_mfma_f32_16x16x32_bf16 v[84:87], v[148:151], v[208:211], v[84:87]
	v_mfma_f32_16x16x32_bf16 v[80:83], v[172:175], v[208:211], v[80:83]
	v_mfma_f32_16x16x32_bf16 v[68:71], v[148:151], v[216:219], v[68:71]
	s_barrier
; #define PG8_STAGE(bufoff, gbase, voff) do { _Pragma("unroll") for (int _i = 0; _i < 2; ++_i) \
;         __builtin_amdgcn_global_load_lds((const unsigned*)((const char*)(gbase) + (voff)[_i]), (PG8_LAS unsigned*)(lds + (bufoff) + ldsw + _i * 8192), 16, 0, 0); } while (0)
; #define PG8_LDA(dst, b, h) do { _Pragma("unroll") for (int m = 0; m < 4; ++m) _Pragma("unroll") for (int k = 0; k < 2; ++k) dst[m][k] = *(const PG8_LAS bf16x8*)(lds + PG8_SA(b, h) + aoff + m * 2048 + k * 1024); } while (0)
; #define PG8_MMA(ai, bj, At, Bt) do { __builtin_amdgcn_s_setprio(1); _Pragma("unroll") for (int m = 0; m < 4; ++m) _Pragma("unroll") for (int n = 0; n < 2; ++n) _Pragma("unroll") for (int k = 0; k < 2; ++k) \
;         acc[ai][bj][m][n] = __builtin_amdgcn_mfma_f32_16x16x32_bf16(Bt[n][k], At[m][k], acc[ai][bj][m][n], 0, 0, 0); __builtin_amdgcn_s_setprio(0); } while (0)
; #define PG8_WAIT_V(n) asm volatile("s_waitcnt vmcnt(" #n ")" ::: "memory")
; #define PG8_WAIT_L(n) asm volatile("s_waitcnt lgkmcnt(" #n ")" ::: "memory")
; #define PG8_BAR __builtin_amdgcn_s_barrier()
; #define PG8_SCHED __builtin_amdgcn_sched_barrier(0)
; template <class Epi, class Sched, bool ALIGN_EPI = false, bool SP2 = false>
; __device__ __forceinline__ void gemm_phase(PG8_LAS unsigned char* lds, const Gemm g, const Sched& S, const Epi& E) {
;     ...
;         for (int t = 0; t < nt; t += 2) {
;             const bool last = (t == nt - 2);
;     ...
;             PG8_LDA(At, 1, 1); PG8_STAGE(PG8_SB(1, 0), b3, voffB); PG8_STAGE(PG8_SB(1, 1), b3 + hstepB, voffB); PG8_STAGE(PG8_SA(1, 0), a3, voffA);
;             PG8_WAIT_V(8); PG8_WAIT_L(0); PG8_BAR; PG8_MMA(1, 0, At, B0); PG8_MMA(1, 1, At, B1); PG8_BAR; PG8_SCHED;
	v_mfma_f32_16x16x32_bf16 v[64:67], v[172:175], v[216:219], v[64:67]
	s_setprio 0
	s_add_i32 s26, s58, s38
	v_lshl_add_u64 v[184:185], v[184:185], 0, s[14:15]
	s_mov_b32 m0, s26
	ds_read_b128 v[176:179], v193 offset:49152
	ds_read_b128 v[180:183], v193 offset:50176
	ds_read_b128 v[196:199], v193 offset:51200
	ds_read_b128 v[200:203], v193 offset:52224
	ds_read_b128 v[204:207], v193 offset:53248
	ds_read_b128 v[208:211], v193 offset:54272
	ds_read_b128 v[212:215], v193 offset:55296
	ds_read_b128 v[216:219], v193 offset:56320
	global_load_lds_dwordx4 v[184:185], off
	s_add_i32 m0, s26, 0x2000
	s_add_u32 s26, s30, 0xb0080
	v_lshl_add_u64 v[184:185], v[220:221], 0, s[14:15]
	s_addc_u32 s27, s31, 0
	s_add_i32 s30, s59, s38
	global_load_lds_dwordx4 v[184:185], off
	v_lshl_add_u64 v[184:185], s[26:27], 0, v[154:155]
	s_mov_b32 m0, s30
	s_nop 0
	global_load_lds_dwordx4 v[184:185], off
	v_lshl_add_u64 v[184:185], s[26:27], 0, v[158:159]
	s_add_i32 m0, s30, 0x2000
	s_nop 0
	global_load_lds_dwordx4 v[184:185], off
	v_lshl_add_u64 v[184:185], v[222:223], 0, s[14:15]
	s_mov_b32 m0, s44
	s_nop 0
	global_load_lds_dwordx4 v[184:185], off
	v_lshl_add_u64 v[184:185], v[224:225], 0, s[14:15]
	s_mov_b32 m0, s45
	s_nop 0
	global_load_lds_dwordx4 v[184:185], off
	s_waitcnt vmcnt(8) lgkmcnt(0)
	s_barrier
	s_setprio 1
	v_mfma_f32_16x16x32_bf16 v[60:63], v[128:131], v[176:179], v[60:63]
	v_mfma_f32_16x16x32_bf16 v[56:59], v[136:139], v[176:179], v[56:59]
	v_mfma_f32_16x16x32_bf16 v[44:47], v[128:131], v[196:199], v[44:47]
	v_mfma_f32_16x16x32_bf16 v[40:43], v[136:139], v[196:199], v[40:43]
	v_mfma_f32_16x16x32_bf16 v[28:31], v[128:131], v[204:207], v[28:31]
	v_mfma_f32_16x16x32_bf16 v[24:27], v[136:139], v[204:207], v[24:27]
	v_mfma_f32_16x16x32_bf16 v[12:15], v[128:131], v[212:215], v[12:15]
	v_mfma_f32_16x16x32_bf16 v[8:11], v[136:139], v[212:215], v[8:11]
	v_mfma_f32_16x16x32_bf16 v[60:63], v[132:135], v[180:183], v[60:63]
	v_mfma_f32_16x16x32_bf16 v[56:59], v[140:143], v[180:183], v[56:59]
	v_mfma_f32_16x16x32_bf16 v[44:47], v[132:135], v[200:203], v[44:47]
	v_mfma_f32_16x16x32_bf16 v[40:43], v[140:143], v[200:203], v[40:43]
	v_mfma_f32_16x16x32_bf16 v[28:31], v[132:135], v[208:211], v[28:31]
	v_mfma_f32_16x16x32_bf16 v[24:27], v[140:143], v[208:211], v[24:27]
	v_mfma_f32_16x16x32_bf16 v[12:15], v[132:135], v[216:219], v[12:15]
	v_mfma_f32_16x16x32_bf16 v[8:11], v[140:143], v[216:219], v[8:11]
	s_setprio 0
	s_setprio 1
	v_mfma_f32_16x16x32_bf16 v[52:55], v[144:147], v[176:179], v[52:55]
	v_mfma_f32_16x16x32_bf16 v[48:51], v[168:171], v[176:179], v[48:51]
	v_mfma_f32_16x16x32_bf16 v[36:39], v[144:147], v[196:199], v[36:39]
	v_mfma_f32_16x16x32_bf16 v[32:35], v[168:171], v[196:199], v[32:35]
	v_mfma_f32_16x16x32_bf16 v[20:23], v[144:147], v[204:207], v[20:23]
	v_mfma_f32_16x16x32_bf16 v[16:19], v[168:171], v[204:207], v[16:19]
	v_mfma_f32_16x16x32_bf16 v[4:7], v[144:147], v[212:215], v[4:7]
	v_mfma_f32_16x16x32_bf16 v[0:3], v[168:171], v[212:215], v[0:3]
	v_mfma_f32_16x16x32_bf16 v[52:55], v[148:151], v[180:183], v[52:55]
	v_mfma_f32_16x16x32_bf16 v[48:51], v[172:175], v[180:183], v[48:51]
	v_mfma_f32_16x16x32_bf16 v[36:39], v[148:151], v[200:203], v[36:39]
	v_mfma_f32_16x16x32_bf16 v[32:35], v[172:175], v[200:203], v[32:35]
	v_mfma_f32_16x16x32_bf16 v[20:23], v[148:151], v[208:211], v[20:23]
	v_mfma_f32_16x16x32_bf16 v[16:19], v[172:175], v[208:211], v[16:19]
	v_mfma_f32_16x16x32_bf16 v[4:7], v[148:151], v[216:219], v[4:7]
	s_barrier
	v_mfma_f32_16x16x32_bf16 v[0:3], v[172:175], v[216:219], v[0:3]
	s_setprio 0
	s_add_i32 s72, s72, 2
	s_add_u32 s70, s70, 0x100
	s_addc_u32 s71, s71, 0
	s_cmp_gt_u32 s72, 41
	s_mov_b64 s[26:27], s[28:29]
	s_cbranch_scc0 .LBB0_318
	s_and_b64 vcc, exec, s[20:21]
	s_cbranch_vccz .LBB0_321
	s_barrier

; #define PG8_STAGE(bufoff, gbase, voff) do { _Pragma("unroll") for (int _i = 0; _i < 2; ++_i) \
;         __builtin_amdgcn_global_load_lds((const unsigned*)((const char*)(gbase) + (voff)[_i]), (PG8_LAS unsigned*)(lds + (bufoff) + ldsw + _i * 8192), 16, 0, 0); } while (0)
; #define PG8_LDA(dst, b, h) do { _Pragma("unroll") for (int m = 0; m < 4; ++m) _Pragma("unroll") for (int k = 0; k < 2; ++k) dst[m][k] = *(const PG8_LAS bf16x8*)(lds + PG8_SA(b, h) + aoff + m * 2048 + k * 1024); } while (0)
; #define PG8_LDB(dst, b, h) do { _Pragma("unroll") for (int n = 0; n < 2; ++n) _Pragma("unroll") for (int k = 0; k < 2; ++k) dst[n][k] = *(const PG8_LAS bf16x8*)(lds + PG8_SB(b, h) + boff + n * 2048 + k * 1024); } while (0)
; #define PG8_MMA(ai, bj, At, Bt) do { __builtin_amdgcn_s_setprio(1); _Pragma("unroll") for (int m = 0; m < 4; ++m) _Pragma("unroll") for (int n = 0; n < 2; ++n) _Pragma("unroll") for (int k = 0; k < 2; ++k) \
;         acc[ai][bj][m][n] = __builtin_amdgcn_mfma_f32_16x16x32_bf16(Bt[n][k], At[m][k], acc[ai][bj][m][n], 0, 0, 0); __builtin_amdgcn_s_setprio(0); } while (0)
; #define PG8_WAIT_V(n) asm volatile("s_waitcnt vmcnt(" #n ")" ::: "memory")
; #define PG8_BAR __builtin_amdgcn_s_barrier()
; template <class Epi, class Sched, bool ALIGN_EPI = false, bool SP2 = false>
; __device__ __forceinline__ void gemm_phase(PG8_LAS unsigned char* lds, const Gemm g, const Sched& S, const Epi& E) {
;     ...
;         for (int t = 0; t < nt; t += 2) {
;             const bool last = (t == nt - 2);
;             const char* a1 = cA + (size_t)(t + 1) * kstep;
;             const char* a2 = last ? nA : cA + (size_t)(t + 2) * kstep; const char* b2 = last ? nB : cB + (size_t)(t + 2) * kstep;
;             const char* a3 = a2 + kstep; const char* b3 = b2 + kstep;
;             if (last && has_next) S.a_ready(nxt);
;             if constexpr (SP2) {
;             PG8_LDB(B0, 0, 0); PG8_LDB(B1, 0, 1); PG8_SCHED; PG8_LDA(At, 0, 0); PG8_STAGE(PG8_SA(1, 1), a1 + hstepA, voffA);
;             PG8_WAIT_V(8); PG8_WAIT_L(0); PG8_BAR; PG8_MMA(0, 0, At, B0); PG8_MMA(0, 1, At, B1); PG8_BAR; PG8_SCHED;
;             PG8_LDA(At, 0, 1); PG8_STAGE(PG8_SB(0, 0), b2, voffB); PG8_STAGE(PG8_SB(0, 1), b2 + hstepB, voffB); PG8_STAGE(PG8_SA(0, 0), a2, voffA);
;             PG8_WAIT_V(8); PG8_WAIT_L(0); PG8_BAR; PG8_MMA(1, 0, At, B0); PG8_MMA(1, 1, At, B1); PG8_BAR; PG8_SCHED;
.LBB0_404:
	ds_read_b128 v[152:155], v165
	ds_read_b128 v[156:159], v165 offset:1024
	ds_read_b128 v[178:181], v165 offset:2048
	ds_read_b128 v[182:185], v165 offset:3072
	ds_read_b128 v[188:191], v166
	ds_read_b128 v[192:195], v166 offset:1024
	ds_read_b128 v[196:199], v166 offset:2048
	ds_read_b128 v[200:203], v166 offset:3072
	s_add_u32 s46, s14, 0xfffc0080
	s_addc_u32 s47, s15, -1
	s_cmp_eq_u32 s91, 12
	s_cselect_b32 s49, s11, s47
	s_cselect_b32 s48, s13, s46
	s_cselect_b32 s47, s39, s67
	s_cselect_b32 s46, s41, s66
	v_lshl_add_u64 v[160:161], s[14:15], 0, v[144:145]
	s_add_i32 m0, s71, 0xc000
	ds_read_b128 v[204:207], v167
	ds_read_b128 v[208:211], v167 offset:1024
	ds_read_b128 v[212:215], v167 offset:2048
	ds_read_b128 v[216:219], v167 offset:3072
	ds_read_b128 v[220:223], v167 offset:4096
	ds_read_b128 v[224:227], v167 offset:5120
	ds_read_b128 v[228:231], v167 offset:6144
	ds_read_b128 v[232:235], v167 offset:7168
	global_load_lds_dwordx4 v[160:161], off
	v_lshl_add_u64 v[160:161], s[14:15], 0, v[146:147]
	s_add_i32 m0, s71, 0xe000
	s_nop 0
	global_load_lds_dwordx4 v[160:161], off
	s_waitcnt vmcnt(8) lgkmcnt(0)
	s_barrier
	s_setprio 1
	v_mfma_f32_16x16x32_bf16 v[124:127], v[152:155], v[204:207], v[124:127]
	v_mfma_f32_16x16x32_bf16 v[120:123], v[178:181], v[204:207], v[120:123]
	v_mfma_f32_16x16x32_bf16 v[108:111], v[152:155], v[212:215], v[108:111]
	v_mfma_f32_16x16x32_bf16 v[104:107], v[178:181], v[212:215], v[104:107]
	v_mfma_f32_16x16x32_bf16 v[92:95], v[152:155], v[220:223], v[92:95]
	v_mfma_f32_16x16x32_bf16 v[88:91], v[178:181], v[220:223], v[88:91]
	v_mfma_f32_16x16x32_bf16 v[76:79], v[152:155], v[228:231], v[76:79]
	v_mfma_f32_16x16x32_bf16 v[72:75], v[178:181], v[228:231], v[72:75]
	v_mfma_f32_16x16x32_bf16 v[124:127], v[156:159], v[208:211], v[124:127]
	v_mfma_f32_16x16x32_bf16 v[120:123], v[182:185], v[208:211], v[120:123]
	v_mfma_f32_16x16x32_bf16 v[108:111], v[156:159], v[216:219], v[108:111]
	v_mfma_f32_16x16x32_bf16 v[104:107], v[182:185], v[216:219], v[104:107]
	v_mfma_f32_16x16x32_bf16 v[92:95], v[156:159], v[224:227], v[92:95]
	v_mfma_f32_16x16x32_bf16 v[88:91], v[182:185], v[224:227], v[88:91]
	v_mfma_f32_16x16x32_bf16 v[76:79], v[156:159], v[232:235], v[76:79]
	v_mfma_f32_16x16x32_bf16 v[72:75], v[182:185], v[232:235], v[72:75]
	s_setprio 0
	s_setprio 1
	v_mfma_f32_16x16x32_bf16 v[116:119], v[188:191], v[204:207], v[116:119]
	v_mfma_f32_16x16x32_bf16 v[112:115], v[196:199], v[204:207], v[112:115]
	v_mfma_f32_16x16x32_bf16 v[100:103], v[188:191], v[212:215], v[100:103]
	v_mfma_f32_16x16x32_bf16 v[96:99], v[196:199], v[212:215], v[96:99]
	v_mfma_f32_16x16x32_bf16 v[84:87], v[188:191], v[220:223], v[84:87]
	v_mfma_f32_16x16x32_bf16 v[80:83], v[196:199], v[220:223], v[80:83]
	v_mfma_f32_16x16x32_bf16 v[68:71], v[188:191], v[228:231], v[68:71]
	v_mfma_f32_16x16x32_bf16 v[64:67], v[196:199], v[228:231], v[64:67]
	v_mfma_f32_16x16x32_bf16 v[116:119], v[192:195], v[208:211], v[116:119]
	v_mfma_f32_16x16x32_bf16 v[112:115], v[200:203], v[208:211], v[112:115]
	v_mfma_f32_16x16x32_bf16 v[100:103], v[192:195], v[216:219], v[100:103]
	v_mfma_f32_16x16x32_bf16 v[96:99], v[200:203], v[216:219], v[96:99]
	v_mfma_f32_16x16x32_bf16 v[84:87], v[192:195], v[224:227], v[84:87]
	v_mfma_f32_16x16x32_bf16 v[80:83], v[200:203], v[224:227], v[80:83]
	v_mfma_f32_16x16x32_bf16 v[68:71], v[192:195], v[232:235], v[68:71]
	s_barrier
	v_mfma_f32_16x16x32_bf16 v[64:67], v[200:203], v[232:235], v[64:67]
	s_setprio 0
	s_add_i32 s58, s83, s70
	v_lshl_add_u64 v[160:161], s[46:47], 0, v[130:131]
	s_mov_b32 m0, s58
	ds_read_b128 v[204:207], v167 offset:16384
	ds_read_b128 v[208:211], v167 offset:17408
	ds_read_b128 v[212:215], v167 offset:18432
	ds_read_b128 v[216:219], v167 offset:19456
	ds_read_b128 v[220:223], v167 offset:20480
	ds_read_b128 v[224:227], v167 offset:21504
	ds_read_b128 v[228:231], v167 offset:22528
	ds_read_b128 v[232:235], v167 offset:23552
	global_load_lds_dwordx4 v[160:161], off
	s_add_i32 m0, s58, 0x2000
	s_add_u32 s58, s46, 0x40000
	v_lshl_add_u64 v[236:237], s[46:47], 0, v[134:135]
	s_addc_u32 s59, s47, 0
	s_add_i32 s92, s84, s70
	global_load_lds_dwordx4 v[236:237], off
	v_lshl_add_u64 v[238:239], s[58:59], 0, v[130:131]
	s_mov_b32 m0, s92
	v_lshl_add_u64 v[240:241], s[48:49], 0, v[132:133]
	global_load_lds_dwordx4 v[238:239], off
	v_lshl_add_u64 v[238:239], s[58:59], 0, v[134:135]
	s_add_i32 m0, s92, 0x2000
	s_nop 0
	global_load_lds_dwordx4 v[238:239], off
	v_lshl_add_u64 v[238:239], s[48:49], 0, v[128:129]
	s_mov_b32 m0, s71
	s_nop 0
	global_load_lds_dwordx4 v[238:239], off
	s_mov_b32 m0, s72
	s_nop 0
	global_load_lds_dwordx4 v[240:241], off
	s_waitcnt vmcnt(8) lgkmcnt(0)
	s_barrier
; #define PG8_STAGE(bufoff, gbase, voff) do { _Pragma("unroll") for (int _i = 0; _i < 2; ++_i) \
;         __builtin_amdgcn_global_load_lds((const unsigned*)((const char*)(gbase) + (voff)[_i]), (PG8_LAS unsigned*)(lds + (bufoff) + ldsw + _i * 8192), 16, 0, 0); } while (0)
; #define PG8_LDA(dst, b, h) do { _Pragma("unroll") for (int m = 0; m < 4; ++m) _Pragma("unroll") for (int k = 0; k < 2; ++k) dst[m][k] = *(const PG8_LAS bf16x8*)(lds + PG8_SA(b, h) + aoff + m * 2048 + k * 1024); } while (0)
; #define PG8_LDB(dst, b, h) do { _Pragma("unroll") for (int n = 0; n < 2; ++n) _Pragma("unroll") for (int k = 0; k < 2; ++k) dst[n][k] = *(const PG8_LAS bf16x8*)(lds + PG8_SB(b, h) + boff + n * 2048 + k * 1024); } while (0)
; #define PG8_MMA(ai, bj, At, Bt) do { __builtin_amdgcn_s_setprio(1); _Pragma("unroll") for (int m = 0; m < 4; ++m) _Pragma("unroll") for (int n = 0; n < 2; ++n) _Pragma("unroll") for (int k = 0; k < 2; ++k) \
;         acc[ai][bj][m][n] = __builtin_amdgcn_mfma_f32_16x16x32_bf16(Bt[n][k], At[m][k], acc[ai][bj][m][n], 0, 0, 0); __builtin_amdgcn_s_setprio(0); } while (0)
; #define PG8_WAIT_V(n) asm volatile("s_waitcnt vmcnt(" #n ")" ::: "memory")
; #define PG8_WAIT_L(n) asm volatile("s_waitcnt lgkmcnt(" #n ")" ::: "memory")
; #define PG8_BAR __builtin_amdgcn_s_barrier()
; #define PG8_SCHED __builtin_amdgcn_sched_barrier(0)
; template <class Epi, class Sched, bool ALIGN_EPI = false, bool SP2 = false>
; __device__ __forceinline__ void gemm_phase(PG8_LAS unsigned char* lds, const Gemm g, const Sched& S, const Epi& E) {
;     ...
;             PG8_WAIT_V(8); PG8_WAIT_L(0); PG8_BAR; PG8_MMA(1, 0, At, B0); PG8_MMA(1, 1, At, B1); PG8_BAR; PG8_SCHED;
;             PG8_LDB(B0, 1, 0); PG8_LDB(B1, 1, 1); PG8_SCHED; PG8_LDA(At, 1, 0); PG8_STAGE(PG8_SA(0, 1), a2 + hstepA, voffA);
;             PG8_WAIT_V(8); PG8_WAIT_L(0); PG8_BAR; PG8_MMA(0, 0, At, B0); PG8_MMA(0, 1, At, B1); PG8_BAR; PG8_SCHED;
	s_setprio 1
	v_mfma_f32_16x16x32_bf16 v[60:63], v[152:155], v[204:207], v[60:63]
	v_mfma_f32_16x16x32_bf16 v[56:59], v[178:181], v[204:207], v[56:59]
	v_mfma_f32_16x16x32_bf16 v[44:47], v[152:155], v[212:215], v[44:47]
	v_mfma_f32_16x16x32_bf16 v[40:43], v[178:181], v[212:215], v[40:43]
	v_mfma_f32_16x16x32_bf16 v[28:31], v[152:155], v[220:223], v[28:31]
	v_mfma_f32_16x16x32_bf16 v[24:27], v[178:181], v[220:223], v[24:27]
	v_mfma_f32_16x16x32_bf16 v[12:15], v[152:155], v[228:231], v[12:15]
	v_mfma_f32_16x16x32_bf16 v[8:11], v[178:181], v[228:231], v[8:11]
	v_mfma_f32_16x16x32_bf16 v[60:63], v[156:159], v[208:211], v[60:63]
	v_mfma_f32_16x16x32_bf16 v[56:59], v[182:185], v[208:211], v[56:59]
	v_mfma_f32_16x16x32_bf16 v[44:47], v[156:159], v[216:219], v[44:47]
	v_mfma_f32_16x16x32_bf16 v[40:43], v[182:185], v[216:219], v[40:43]
	v_mfma_f32_16x16x32_bf16 v[28:31], v[156:159], v[224:227], v[28:31]
	v_mfma_f32_16x16x32_bf16 v[24:27], v[182:185], v[224:227], v[24:27]
	v_mfma_f32_16x16x32_bf16 v[12:15], v[156:159], v[232:235], v[12:15]
	v_mfma_f32_16x16x32_bf16 v[8:11], v[182:185], v[232:235], v[8:11]
	s_setprio 0
	s_setprio 1
	v_mfma_f32_16x16x32_bf16 v[52:55], v[188:191], v[204:207], v[52:55]
	v_mfma_f32_16x16x32_bf16 v[48:51], v[196:199], v[204:207], v[48:51]
	v_mfma_f32_16x16x32_bf16 v[36:39], v[188:191], v[212:215], v[36:39]
	v_mfma_f32_16x16x32_bf16 v[32:35], v[196:199], v[212:215], v[32:35]
	v_mfma_f32_16x16x32_bf16 v[20:23], v[188:191], v[220:223], v[20:23]
	v_mfma_f32_16x16x32_bf16 v[16:19], v[196:199], v[220:223], v[16:19]
	v_mfma_f32_16x16x32_bf16 v[4:7], v[188:191], v[228:231], v[4:7]
	v_mfma_f32_16x16x32_bf16 v[0:3], v[196:199], v[228:231], v[0:3]
	v_mfma_f32_16x16x32_bf16 v[52:55], v[192:195], v[208:211], v[52:55]
	v_mfma_f32_16x16x32_bf16 v[48:51], v[200:203], v[208:211], v[48:51]
	v_mfma_f32_16x16x32_bf16 v[36:39], v[192:195], v[216:219], v[36:39]
	v_mfma_f32_16x16x32_bf16 v[32:35], v[200:203], v[216:219], v[32:35]
	v_mfma_f32_16x16x32_bf16 v[20:23], v[192:195], v[224:227], v[20:23]
	v_mfma_f32_16x16x32_bf16 v[16:19], v[200:203], v[224:227], v[16:19]
	v_mfma_f32_16x16x32_bf16 v[4:7], v[192:195], v[232:235], v[4:7]
	s_barrier
	v_mfma_f32_16x16x32_bf16 v[0:3], v[200:203], v[232:235], v[0:3]
	s_setprio 0
	s_add_i32 s58, 0, 0x18000
	v_add_u32_e32 v136, s58, v163
	s_add_i32 s59, 0, 0x1c000
	ds_read_b128 v[152:155], v136
	ds_read_b128 v[156:159], v136 offset:1024
	ds_read_b128 v[178:181], v136 offset:2048
	ds_read_b128 v[182:185], v136 offset:3072
	v_add_u32_e32 v136, s59, v163
	ds_read_b128 v[188:191], v136
	ds_read_b128 v[192:195], v136 offset:1024
	ds_read_b128 v[196:199], v136 offset:2048
	ds_read_b128 v[200:203], v136 offset:3072
	s_add_u32 s48, s48, 0x40000
	s_addc_u32 s49, s49, 0
	s_mov_b32 m0, s73
	v_lshl_add_u64 v[242:243], s[48:49], 0, v[128:129]
	ds_read_b128 v[204:207], v167 offset:32768
	ds_read_b128 v[208:211], v167 offset:33792
	ds_read_b128 v[212:215], v167 offset:34816
	ds_read_b128 v[216:219], v167 offset:35840
	ds_read_b128 v[220:223], v167 offset:36864
	ds_read_b128 v[224:227], v167 offset:37888
	ds_read_b128 v[228:231], v167 offset:38912
	ds_read_b128 v[232:235], v167 offset:39936
	global_load_lds_dwordx4 v[242:243], off
	v_lshl_add_u64 v[242:243], s[48:49], 0, v[132:133]
	s_mov_b32 m0, s74
	s_nop 0
	global_load_lds_dwordx4 v[242:243], off
	s_waitcnt vmcnt(8) lgkmcnt(0)
	s_barrier
	s_setprio 1
	v_mfma_f32_16x16x32_bf16 v[124:127], v[152:155], v[204:207], v[124:127]
	v_mfma_f32_16x16x32_bf16 v[120:123], v[178:181], v[204:207], v[120:123]
	v_mfma_f32_16x16x32_bf16 v[108:111], v[152:155], v[212:215], v[108:111]
	v_mfma_f32_16x16x32_bf16 v[104:107], v[178:181], v[212:215], v[104:107]
	v_mfma_f32_16x16x32_bf16 v[92:95], v[152:155], v[220:223], v[92:95]
	v_mfma_f32_16x16x32_bf16 v[88:91], v[178:181], v[220:223], v[88:91]
	v_mfma_f32_16x16x32_bf16 v[76:79], v[152:155], v[228:231], v[76:79]
	v_mfma_f32_16x16x32_bf16 v[72:75], v[178:181], v[228:231], v[72:75]
	v_mfma_f32_16x16x32_bf16 v[124:127], v[156:159], v[208:211], v[124:127]
	v_mfma_f32_16x16x32_bf16 v[120:123], v[182:185], v[208:211], v[120:123]
	v_mfma_f32_16x16x32_bf16 v[108:111], v[156:159], v[216:219], v[108:111]
	v_mfma_f32_16x16x32_bf16 v[104:107], v[182:185], v[216:219], v[104:107]
	v_mfma_f32_16x16x32_bf16 v[92:95], v[156:159], v[224:227], v[92:95]
	v_mfma_f32_16x16x32_bf16 v[88:91], v[182:185], v[224:227], v[88:91]
	v_mfma_f32_16x16x32_bf16 v[76:79], v[156:159], v[232:235], v[76:79]
	v_mfma_f32_16x16x32_bf16 v[72:75], v[182:185], v[232:235], v[72:75]
	s_setprio 0
	s_setprio 1
	v_mfma_f32_16x16x32_bf16 v[116:119], v[188:191], v[204:207], v[116:119]
	v_mfma_f32_16x16x32_bf16 v[112:115], v[196:199], v[204:207], v[112:115]
	v_mfma_f32_16x16x32_bf16 v[100:103], v[188:191], v[212:215], v[100:103]
	v_mfma_f32_16x16x32_bf16 v[96:99], v[196:199], v[212:215], v[96:99]
	v_mfma_f32_16x16x32_bf16 v[84:87], v[188:191], v[220:223], v[84:87]
	v_mfma_f32_16x16x32_bf16 v[80:83], v[196:199], v[220:223], v[80:83]
	v_mfma_f32_16x16x32_bf16 v[68:71], v[188:191], v[228:231], v[68:71]
	v_mfma_f32_16x16x32_bf16 v[64:67], v[196:199], v[228:231], v[64:67]
	v_mfma_f32_16x16x32_bf16 v[116:119], v[192:195], v[208:211], v[116:119]
	v_mfma_f32_16x16x32_bf16 v[112:115], v[200:203], v[208:211], v[112:115]
	v_mfma_f32_16x16x32_bf16 v[100:103], v[192:195], v[216:219], v[100:103]
	v_mfma_f32_16x16x32_bf16 v[96:99], v[200:203], v[216:219], v[96:99]
	v_mfma_f32_16x16x32_bf16 v[84:87], v[192:195], v[224:227], v[84:87]
	v_mfma_f32_16x16x32_bf16 v[80:83], v[200:203], v[224:227], v[80:83]
	v_mfma_f32_16x16x32_bf16 v[68:71], v[192:195], v[232:235], v[68:71]
	s_barrier
; #define PG8_STAGE(bufoff, gbase, voff) do { _Pragma("unroll") for (int _i = 0; _i < 2; ++_i) \
;         __builtin_amdgcn_global_load_lds((const unsigned*)((const char*)(gbase) + (voff)[_i]), (PG8_LAS unsigned*)(lds + (bufoff) + ldsw + _i * 8192), 16, 0, 0); } while (0)
; #define PG8_LDA(dst, b, h) do { _Pragma("unroll") for (int m = 0; m < 4; ++m) _Pragma("unroll") for (int k = 0; k < 2; ++k) dst[m][k] = *(const PG8_LAS bf16x8*)(lds + PG8_SA(b, h) + aoff + m * 2048 + k * 1024); } while (0)
; #define PG8_MMA(ai, bj, At, Bt) do { __builtin_amdgcn_s_setprio(1); _Pragma("unroll") for (int m = 0; m < 4; ++m) _Pragma("unroll") for (int n = 0; n < 2; ++n) _Pragma("unroll") for (int k = 0; k < 2; ++k) \
;         acc[ai][bj][m][n] = __builtin_amdgcn_mfma_f32_16x16x32_bf16(Bt[n][k], At[m][k], acc[ai][bj][m][n], 0, 0, 0); __builtin_amdgcn_s_setprio(0); } while (0)
; #define PG8_WAIT_V(n) asm volatile("s_waitcnt vmcnt(" #n ")" ::: "memory")
; #define PG8_WAIT_L(n) asm volatile("s_waitcnt lgkmcnt(" #n ")" ::: "memory")
; #define PG8_BAR __builtin_amdgcn_s_barrier()
; #define PG8_SCHED __builtin_amdgcn_sched_barrier(0)
; template <class Epi, class Sched, bool ALIGN_EPI = false, bool SP2 = false>
; __device__ __forceinline__ void gemm_phase(PG8_LAS unsigned char* lds, const Gemm g, const Sched& S, const Epi& E) {
;     ...
;         for (int t = 0; t < nt; t += 2) {
;             const bool last = (t == nt - 2);
;     ...
;             PG8_LDA(At, 1, 1); PG8_STAGE(PG8_SB(1, 0), b3, voffB); PG8_STAGE(PG8_SB(1, 1), b3 + hstepB, voffB); PG8_STAGE(PG8_SA(1, 0), a3, voffA);
;             PG8_WAIT_V(8); PG8_WAIT_L(0); PG8_BAR; PG8_MMA(1, 0, At, B0); PG8_MMA(1, 1, At, B1); PG8_BAR; PG8_SCHED;
	v_mfma_f32_16x16x32_bf16 v[64:67], v[200:203], v[232:235], v[64:67]
	s_setprio 0
	s_add_i32 s48, s58, s70
	v_lshl_add_u64 v[160:161], v[160:161], 0, s[30:31]
	s_mov_b32 m0, s48
	ds_read_b128 v[204:207], v167 offset:49152
	ds_read_b128 v[208:211], v167 offset:50176
	ds_read_b128 v[212:215], v167 offset:51200
	ds_read_b128 v[216:219], v167 offset:52224
	ds_read_b128 v[220:223], v167 offset:53248
	ds_read_b128 v[224:227], v167 offset:54272
	ds_read_b128 v[228:231], v167 offset:55296
	ds_read_b128 v[232:235], v167 offset:56320
	global_load_lds_dwordx4 v[160:161], off
	s_add_i32 m0, s48, 0x2000
	s_add_u32 s46, s46, 0x40080
	v_lshl_add_u64 v[160:161], v[236:237], 0, s[30:31]
	s_addc_u32 s47, s47, 0
	s_add_i32 s48, s59, s70
	global_load_lds_dwordx4 v[160:161], off
	v_lshl_add_u64 v[160:161], s[46:47], 0, v[130:131]
	s_mov_b32 m0, s48
	s_nop 0
	global_load_lds_dwordx4 v[160:161], off
	v_lshl_add_u64 v[160:161], s[46:47], 0, v[134:135]
	s_add_i32 m0, s48, 0x2000
	s_nop 0
	global_load_lds_dwordx4 v[160:161], off
	v_lshl_add_u64 v[160:161], v[238:239], 0, s[30:31]
	s_mov_b32 m0, s76
	s_nop 0
	global_load_lds_dwordx4 v[160:161], off
	v_lshl_add_u64 v[160:161], v[240:241], 0, s[30:31]
	s_mov_b32 m0, s77
	s_nop 0
	global_load_lds_dwordx4 v[160:161], off
	s_waitcnt vmcnt(8) lgkmcnt(0)
	s_barrier
	s_setprio 1
	v_mfma_f32_16x16x32_bf16 v[60:63], v[152:155], v[204:207], v[60:63]
	v_mfma_f32_16x16x32_bf16 v[56:59], v[178:181], v[204:207], v[56:59]
	v_mfma_f32_16x16x32_bf16 v[44:47], v[152:155], v[212:215], v[44:47]
	v_mfma_f32_16x16x32_bf16 v[40:43], v[178:181], v[212:215], v[40:43]
	v_mfma_f32_16x16x32_bf16 v[28:31], v[152:155], v[220:223], v[28:31]
	v_mfma_f32_16x16x32_bf16 v[24:27], v[178:181], v[220:223], v[24:27]
	v_mfma_f32_16x16x32_bf16 v[12:15], v[152:155], v[228:231], v[12:15]
	v_mfma_f32_16x16x32_bf16 v[8:11], v[178:181], v[228:231], v[8:11]
	v_mfma_f32_16x16x32_bf16 v[60:63], v[156:159], v[208:211], v[60:63]
	v_mfma_f32_16x16x32_bf16 v[56:59], v[182:185], v[208:211], v[56:59]
	v_mfma_f32_16x16x32_bf16 v[44:47], v[156:159], v[216:219], v[44:47]
	v_mfma_f32_16x16x32_bf16 v[40:43], v[182:185], v[216:219], v[40:43]
	v_mfma_f32_16x16x32_bf16 v[28:31], v[156:159], v[224:227], v[28:31]
	v_mfma_f32_16x16x32_bf16 v[24:27], v[182:185], v[224:227], v[24:27]
	v_mfma_f32_16x16x32_bf16 v[12:15], v[156:159], v[232:235], v[12:15]
	v_mfma_f32_16x16x32_bf16 v[8:11], v[182:185], v[232:235], v[8:11]
	s_setprio 0
	s_setprio 1
	v_mfma_f32_16x16x32_bf16 v[52:55], v[188:191], v[204:207], v[52:55]
	v_mfma_f32_16x16x32_bf16 v[48:51], v[196:199], v[204:207], v[48:51]
	v_mfma_f32_16x16x32_bf16 v[36:39], v[188:191], v[212:215], v[36:39]
	v_mfma_f32_16x16x32_bf16 v[32:35], v[196:199], v[212:215], v[32:35]
	v_mfma_f32_16x16x32_bf16 v[20:23], v[188:191], v[220:223], v[20:23]
	v_mfma_f32_16x16x32_bf16 v[16:19], v[196:199], v[220:223], v[16:19]
	v_mfma_f32_16x16x32_bf16 v[4:7], v[188:191], v[228:231], v[4:7]
	v_mfma_f32_16x16x32_bf16 v[0:3], v[196:199], v[228:231], v[0:3]
	v_mfma_f32_16x16x32_bf16 v[52:55], v[192:195], v[208:211], v[52:55]
	v_mfma_f32_16x16x32_bf16 v[48:51], v[200:203], v[208:211], v[48:51]
	v_mfma_f32_16x16x32_bf16 v[36:39], v[192:195], v[216:219], v[36:39]
	v_mfma_f32_16x16x32_bf16 v[32:35], v[200:203], v[216:219], v[32:35]
	v_mfma_f32_16x16x32_bf16 v[20:23], v[192:195], v[224:227], v[20:23]
	v_mfma_f32_16x16x32_bf16 v[16:19], v[200:203], v[224:227], v[16:19]
	v_mfma_f32_16x16x32_bf16 v[4:7], v[192:195], v[232:235], v[4:7]
	s_barrier
	v_mfma_f32_16x16x32_bf16 v[0:3], v[200:203], v[232:235], v[0:3]
	s_setprio 0
	s_add_i32 s91, s91, 2
	s_add_u32 s14, s14, 0x100
	s_addc_u32 s15, s15, 0
	s_add_u32 s66, s66, 0x100
	s_addc_u32 s67, s67, 0
	s_cmp_gt_u32 s91, 13
	s_cbranch_scc0 .LBB0_404
	s_and_b64 vcc, exec, s[34:35]
	s_cbranch_vccz .LBB0_407
	s_barrier

; #define PG8_STAGE(bufoff, gbase, voff) do { _Pragma("unroll") for (int _i = 0; _i < 2; ++_i) \
;         __builtin_amdgcn_global_load_lds((const unsigned*)((const char*)(gbase) + (voff)[_i]), (PG8_LAS unsigned*)(lds + (bufoff) + ldsw + _i * 8192), 16, 0, 0); } while (0)
; #define PG8_LDA(dst, b, h) do { _Pragma("unroll") for (int m = 0; m < 4; ++m) _Pragma("unroll") for (int k = 0; k < 2; ++k) dst[m][k] = *(const PG8_LAS bf16x8*)(lds + PG8_SA(b, h) + aoff + m * 2048 + k * 1024); } while (0)
; #define PG8_LDB(dst, b, h) do { _Pragma("unroll") for (int n = 0; n < 2; ++n) _Pragma("unroll") for (int k = 0; k < 2; ++k) dst[n][k] = *(const PG8_LAS bf16x8*)(lds + PG8_SB(b, h) + boff + n * 2048 + k * 1024); } while (0)
; #define PG8_MMA(ai, bj, At, Bt) do { __builtin_amdgcn_s_setprio(1); _Pragma("unroll") for (int m = 0; m < 4; ++m) _Pragma("unroll") for (int n = 0; n < 2; ++n) _Pragma("unroll") for (int k = 0; k < 2; ++k) \
;         acc[ai][bj][m][n] = __builtin_amdgcn_mfma_f32_16x16x32_bf16(Bt[n][k], At[m][k], acc[ai][bj][m][n], 0, 0, 0); __builtin_amdgcn_s_setprio(0); } while (0)
; #define PG8_WAIT_V(n) asm volatile("s_waitcnt vmcnt(" #n ")" ::: "memory")
; #define PG8_BAR __builtin_amdgcn_s_barrier()
; template <class Epi, class Sched, bool ALIGN_EPI = false, bool SP2 = false>
; __device__ __forceinline__ void gemm_phase(PG8_LAS unsigned char* lds, const Gemm g, const Sched& S, const Epi& E) {
;     ...
;         for (int t = 0; t < nt; t += 2) {
;             const bool last = (t == nt - 2);
;             const char* a1 = cA + (size_t)(t + 1) * kstep;
;             const char* a2 = last ? nA : cA + (size_t)(t + 2) * kstep; const char* b2 = last ? nB : cB + (size_t)(t + 2) * kstep;
;             const char* a3 = a2 + kstep; const char* b3 = b2 + kstep;
;             if (last && has_next) S.a_ready(nxt);
;             if constexpr (SP2) {
;             PG8_LDB(B0, 0, 0); PG8_LDB(B1, 0, 1); PG8_SCHED; PG8_LDA(At, 0, 0); PG8_STAGE(PG8_SA(1, 1), a1 + hstepA, voffA);
;             PG8_WAIT_V(8); PG8_WAIT_L(0); PG8_BAR; PG8_MMA(0, 0, At, B0); PG8_MMA(0, 1, At, B1); PG8_BAR; PG8_SCHED;
;             PG8_LDA(At, 0, 1); PG8_STAGE(PG8_SB(0, 0), b2, voffB); PG8_STAGE(PG8_SB(0, 1), b2 + hstepB, voffB); PG8_STAGE(PG8_SA(0, 0), a2, voffA);
;             PG8_WAIT_V(8); PG8_WAIT_L(0); PG8_BAR; PG8_MMA(1, 0, At, B0); PG8_MMA(1, 1, At, B1); PG8_BAR; PG8_SCHED;
.LBB0_524:
	ds_read_b128 v[144:147], v153
	ds_read_b128 v[158:161], v153 offset:1024
	ds_read_b128 v[162:165], v153 offset:2048
	ds_read_b128 v[166:169], v153 offset:3072
	ds_read_b128 v[170:173], v154
	ds_read_b128 v[174:177], v154 offset:1024
	ds_read_b128 v[178:181], v154 offset:2048
	ds_read_b128 v[182:185], v154 offset:3072
	s_add_u32 s30, s28, 0x100
	s_addc_u32 s31, s29, 0
	s_cmp_eq_u32 s76, 2
	s_cselect_b32 s37, s9, s31
	s_cselect_b32 s36, s8, s30
	s_cselect_b32 s35, s25, s75
	s_cselect_b32 s34, s24, s74
	v_lshl_add_u64 v[148:149], s[28:29], 0, v[136:137]
	s_add_i32 m0, s42, 0xc000
	ds_read_b128 v[188:191], v155
	ds_read_b128 v[192:195], v155 offset:1024
	ds_read_b128 v[196:199], v155 offset:2048
	ds_read_b128 v[200:203], v155 offset:3072
	ds_read_b128 v[204:207], v155 offset:4096
	ds_read_b128 v[208:211], v155 offset:5120
	ds_read_b128 v[212:215], v155 offset:6144
	ds_read_b128 v[216:219], v155 offset:7168
	global_load_lds_dwordx4 v[148:149], off
	v_lshl_add_u64 v[148:149], s[28:29], 0, v[138:139]
	s_add_i32 m0, s42, 0xe000
	s_nop 0
	global_load_lds_dwordx4 v[148:149], off
	s_waitcnt vmcnt(8) lgkmcnt(0)
	s_barrier
	s_setprio 1
	v_mfma_f32_16x16x32_bf16 v[124:127], v[144:147], v[188:191], v[124:127]
	v_mfma_f32_16x16x32_bf16 v[120:123], v[162:165], v[188:191], v[120:123]
	v_mfma_f32_16x16x32_bf16 v[108:111], v[144:147], v[196:199], v[108:111]
	v_mfma_f32_16x16x32_bf16 v[104:107], v[162:165], v[196:199], v[104:107]
	v_mfma_f32_16x16x32_bf16 v[92:95], v[144:147], v[204:207], v[92:95]
	v_mfma_f32_16x16x32_bf16 v[88:91], v[162:165], v[204:207], v[88:91]
	v_mfma_f32_16x16x32_bf16 v[76:79], v[144:147], v[212:215], v[76:79]
	v_mfma_f32_16x16x32_bf16 v[72:75], v[162:165], v[212:215], v[72:75]
	v_mfma_f32_16x16x32_bf16 v[124:127], v[158:161], v[192:195], v[124:127]
	v_mfma_f32_16x16x32_bf16 v[120:123], v[166:169], v[192:195], v[120:123]
	v_mfma_f32_16x16x32_bf16 v[108:111], v[158:161], v[200:203], v[108:111]
	v_mfma_f32_16x16x32_bf16 v[104:107], v[166:169], v[200:203], v[104:107]
	v_mfma_f32_16x16x32_bf16 v[92:95], v[158:161], v[208:211], v[92:95]
	v_mfma_f32_16x16x32_bf16 v[88:91], v[166:169], v[208:211], v[88:91]
	v_mfma_f32_16x16x32_bf16 v[76:79], v[158:161], v[216:219], v[76:79]
	v_mfma_f32_16x16x32_bf16 v[72:75], v[166:169], v[216:219], v[72:75]
	s_setprio 0
	s_setprio 1
	v_mfma_f32_16x16x32_bf16 v[116:119], v[170:173], v[188:191], v[116:119]
	v_mfma_f32_16x16x32_bf16 v[112:115], v[178:181], v[188:191], v[112:115]
	v_mfma_f32_16x16x32_bf16 v[100:103], v[170:173], v[196:199], v[100:103]
	v_mfma_f32_16x16x32_bf16 v[96:99], v[178:181], v[196:199], v[96:99]
	v_mfma_f32_16x16x32_bf16 v[84:87], v[170:173], v[204:207], v[84:87]
	v_mfma_f32_16x16x32_bf16 v[80:83], v[178:181], v[204:207], v[80:83]
	v_mfma_f32_16x16x32_bf16 v[68:71], v[170:173], v[212:215], v[68:71]
	v_mfma_f32_16x16x32_bf16 v[64:67], v[178:181], v[212:215], v[64:67]
	v_mfma_f32_16x16x32_bf16 v[116:119], v[174:177], v[192:195], v[116:119]
	v_mfma_f32_16x16x32_bf16 v[112:115], v[182:185], v[192:195], v[112:115]
	v_mfma_f32_16x16x32_bf16 v[100:103], v[174:177], v[200:203], v[100:103]
	v_mfma_f32_16x16x32_bf16 v[96:99], v[182:185], v[200:203], v[96:99]
	v_mfma_f32_16x16x32_bf16 v[84:87], v[174:177], v[208:211], v[84:87]
	v_mfma_f32_16x16x32_bf16 v[80:83], v[182:185], v[208:211], v[80:83]
	v_mfma_f32_16x16x32_bf16 v[68:71], v[174:177], v[216:219], v[68:71]
	s_barrier
	v_mfma_f32_16x16x32_bf16 v[64:67], v[182:185], v[216:219], v[64:67]
	s_setprio 0
	s_add_i32 s28, s66, s40
	v_lshl_add_u64 v[148:149], s[34:35], 0, v[132:133]
	s_mov_b32 m0, s28
	ds_read_b128 v[188:191], v155 offset:16384
	ds_read_b128 v[192:195], v155 offset:17408
	ds_read_b128 v[196:199], v155 offset:18432
	ds_read_b128 v[200:203], v155 offset:19456
	ds_read_b128 v[204:207], v155 offset:20480
	ds_read_b128 v[208:211], v155 offset:21504
	ds_read_b128 v[212:215], v155 offset:22528
	ds_read_b128 v[216:219], v155 offset:23552
	global_load_lds_dwordx4 v[148:149], off
	s_add_i32 m0, s28, 0x2000
	s_add_u32 s28, s34, 0x18000
	v_lshl_add_u64 v[220:221], s[34:35], 0, v[128:129]
	s_addc_u32 s29, s35, 0
	s_add_i32 s58, s67, s40
	global_load_lds_dwordx4 v[220:221], off
	v_lshl_add_u64 v[222:223], s[28:29], 0, v[132:133]
	s_mov_b32 m0, s58
	v_lshl_add_u64 v[224:225], s[36:37], 0, v[130:131]
	global_load_lds_dwordx4 v[222:223], off
	v_lshl_add_u64 v[222:223], s[28:29], 0, v[128:129]
	s_add_i32 m0, s58, 0x2000
	s_nop 0
	global_load_lds_dwordx4 v[222:223], off
	v_lshl_add_u64 v[222:223], s[36:37], 0, v[134:135]
	s_mov_b32 m0, s42
	s_nop 0
	global_load_lds_dwordx4 v[222:223], off
	s_mov_b32 m0, s43
	s_nop 0
	global_load_lds_dwordx4 v[224:225], off
	s_waitcnt vmcnt(8) lgkmcnt(0)
	s_barrier
; #define PG8_STAGE(bufoff, gbase, voff) do { _Pragma("unroll") for (int _i = 0; _i < 2; ++_i) \
;         __builtin_amdgcn_global_load_lds((const unsigned*)((const char*)(gbase) + (voff)[_i]), (PG8_LAS unsigned*)(lds + (bufoff) + ldsw + _i * 8192), 16, 0, 0); } while (0)
; #define PG8_LDA(dst, b, h) do { _Pragma("unroll") for (int m = 0; m < 4; ++m) _Pragma("unroll") for (int k = 0; k < 2; ++k) dst[m][k] = *(const PG8_LAS bf16x8*)(lds + PG8_SA(b, h) + aoff + m * 2048 + k * 1024); } while (0)
; #define PG8_LDB(dst, b, h) do { _Pragma("unroll") for (int n = 0; n < 2; ++n) _Pragma("unroll") for (int k = 0; k < 2; ++k) dst[n][k] = *(const PG8_LAS bf16x8*)(lds + PG8_SB(b, h) + boff + n * 2048 + k * 1024); } while (0)
; #define PG8_MMA(ai, bj, At, Bt) do { __builtin_amdgcn_s_setprio(1); _Pragma("unroll") for (int m = 0; m < 4; ++m) _Pragma("unroll") for (int n = 0; n < 2; ++n) _Pragma("unroll") for (int k = 0; k < 2; ++k) \
;         acc[ai][bj][m][n] = __builtin_amdgcn_mfma_f32_16x16x32_bf16(Bt[n][k], At[m][k], acc[ai][bj][m][n], 0, 0, 0); __builtin_amdgcn_s_setprio(0); } while (0)
; #define PG8_WAIT_V(n) asm volatile("s_waitcnt vmcnt(" #n ")" ::: "memory")
; #define PG8_WAIT_L(n) asm volatile("s_waitcnt lgkmcnt(" #n ")" ::: "memory")
; #define PG8_BAR __builtin_amdgcn_s_barrier()
; #define PG8_SCHED __builtin_amdgcn_sched_barrier(0)
; template <class Epi, class Sched, bool ALIGN_EPI = false, bool SP2 = false>
; __device__ __forceinline__ void gemm_phase(PG8_LAS unsigned char* lds, const Gemm g, const Sched& S, const Epi& E) {
;     ...
;             PG8_WAIT_V(8); PG8_WAIT_L(0); PG8_BAR; PG8_MMA(1, 0, At, B0); PG8_MMA(1, 1, At, B1); PG8_BAR; PG8_SCHED;
;             PG8_LDB(B0, 1, 0); PG8_LDB(B1, 1, 1); PG8_SCHED; PG8_LDA(At, 1, 0); PG8_STAGE(PG8_SA(0, 1), a2 + hstepA, voffA);
;             PG8_WAIT_V(8); PG8_WAIT_L(0); PG8_BAR; PG8_MMA(0, 0, At, B0); PG8_MMA(0, 1, At, B1); PG8_BAR; PG8_SCHED;
	s_setprio 1
	v_mfma_f32_16x16x32_bf16 v[60:63], v[144:147], v[188:191], v[60:63]
	v_mfma_f32_16x16x32_bf16 v[56:59], v[162:165], v[188:191], v[56:59]
	v_mfma_f32_16x16x32_bf16 v[44:47], v[144:147], v[196:199], v[44:47]
	v_mfma_f32_16x16x32_bf16 v[40:43], v[162:165], v[196:199], v[40:43]
	v_mfma_f32_16x16x32_bf16 v[28:31], v[144:147], v[204:207], v[28:31]
	v_mfma_f32_16x16x32_bf16 v[24:27], v[162:165], v[204:207], v[24:27]
	v_mfma_f32_16x16x32_bf16 v[12:15], v[144:147], v[212:215], v[12:15]
	v_mfma_f32_16x16x32_bf16 v[8:11], v[162:165], v[212:215], v[8:11]
	v_mfma_f32_16x16x32_bf16 v[60:63], v[158:161], v[192:195], v[60:63]
	v_mfma_f32_16x16x32_bf16 v[56:59], v[166:169], v[192:195], v[56:59]
	v_mfma_f32_16x16x32_bf16 v[44:47], v[158:161], v[200:203], v[44:47]
	v_mfma_f32_16x16x32_bf16 v[40:43], v[166:169], v[200:203], v[40:43]
	v_mfma_f32_16x16x32_bf16 v[28:31], v[158:161], v[208:211], v[28:31]
	v_mfma_f32_16x16x32_bf16 v[24:27], v[166:169], v[208:211], v[24:27]
	v_mfma_f32_16x16x32_bf16 v[12:15], v[158:161], v[216:219], v[12:15]
	v_mfma_f32_16x16x32_bf16 v[8:11], v[166:169], v[216:219], v[8:11]
	s_setprio 0
	s_setprio 1
	v_mfma_f32_16x16x32_bf16 v[52:55], v[170:173], v[188:191], v[52:55]
	v_mfma_f32_16x16x32_bf16 v[48:51], v[178:181], v[188:191], v[48:51]
	v_mfma_f32_16x16x32_bf16 v[36:39], v[170:173], v[196:199], v[36:39]
	v_mfma_f32_16x16x32_bf16 v[32:35], v[178:181], v[196:199], v[32:35]
	v_mfma_f32_16x16x32_bf16 v[20:23], v[170:173], v[204:207], v[20:23]
	v_mfma_f32_16x16x32_bf16 v[16:19], v[178:181], v[204:207], v[16:19]
	v_mfma_f32_16x16x32_bf16 v[4:7], v[170:173], v[212:215], v[4:7]
	v_mfma_f32_16x16x32_bf16 v[0:3], v[178:181], v[212:215], v[0:3]
	v_mfma_f32_16x16x32_bf16 v[52:55], v[174:177], v[192:195], v[52:55]
	v_mfma_f32_16x16x32_bf16 v[48:51], v[182:185], v[192:195], v[48:51]
	v_mfma_f32_16x16x32_bf16 v[36:39], v[174:177], v[200:203], v[36:39]
	v_mfma_f32_16x16x32_bf16 v[32:35], v[182:185], v[200:203], v[32:35]
	v_mfma_f32_16x16x32_bf16 v[20:23], v[174:177], v[208:211], v[20:23]
	v_mfma_f32_16x16x32_bf16 v[16:19], v[182:185], v[208:211], v[16:19]
	v_mfma_f32_16x16x32_bf16 v[4:7], v[174:177], v[216:219], v[4:7]
	s_barrier
	v_mfma_f32_16x16x32_bf16 v[0:3], v[182:185], v[216:219], v[0:3]
	s_setprio 0
	s_add_i32 s58, 0, 0x18000
	v_add_u32_e32 v157, s58, v151
	s_add_i32 s59, 0, 0x1c000
	ds_read_b128 v[144:147], v157
	ds_read_b128 v[158:161], v157 offset:1024
	ds_read_b128 v[162:165], v157 offset:2048
	ds_read_b128 v[166:169], v157 offset:3072
	v_add_u32_e32 v157, s59, v151
	ds_read_b128 v[170:173], v157
	ds_read_b128 v[174:177], v157 offset:1024
	ds_read_b128 v[178:181], v157 offset:2048
	ds_read_b128 v[182:185], v157 offset:3072
	s_add_u32 s28, s36, 0x30000
	s_addc_u32 s29, s37, 0
	s_mov_b32 m0, s44
	v_lshl_add_u64 v[226:227], s[28:29], 0, v[134:135]
	ds_read_b128 v[188:191], v155 offset:32768
	ds_read_b128 v[192:195], v155 offset:33792
	ds_read_b128 v[196:199], v155 offset:34816
	ds_read_b128 v[200:203], v155 offset:35840
	ds_read_b128 v[204:207], v155 offset:36864
	ds_read_b128 v[208:211], v155 offset:37888
	ds_read_b128 v[212:215], v155 offset:38912
	ds_read_b128 v[216:219], v155 offset:39936
	global_load_lds_dwordx4 v[226:227], off
	v_lshl_add_u64 v[226:227], s[28:29], 0, v[130:131]
	s_mov_b32 m0, s45
	s_nop 0
	global_load_lds_dwordx4 v[226:227], off
	s_waitcnt vmcnt(8) lgkmcnt(0)
	s_barrier
	s_setprio 1
	v_mfma_f32_16x16x32_bf16 v[124:127], v[144:147], v[188:191], v[124:127]
	v_mfma_f32_16x16x32_bf16 v[120:123], v[162:165], v[188:191], v[120:123]
	v_mfma_f32_16x16x32_bf16 v[108:111], v[144:147], v[196:199], v[108:111]
	v_mfma_f32_16x16x32_bf16 v[104:107], v[162:165], v[196:199], v[104:107]
	v_mfma_f32_16x16x32_bf16 v[92:95], v[144:147], v[204:207], v[92:95]
	v_mfma_f32_16x16x32_bf16 v[88:91], v[162:165], v[204:207], v[88:91]
	v_mfma_f32_16x16x32_bf16 v[76:79], v[144:147], v[212:215], v[76:79]
	v_mfma_f32_16x16x32_bf16 v[72:75], v[162:165], v[212:215], v[72:75]
	v_mfma_f32_16x16x32_bf16 v[124:127], v[158:161], v[192:195], v[124:127]
	v_mfma_f32_16x16x32_bf16 v[120:123], v[166:169], v[192:195], v[120:123]
	v_mfma_f32_16x16x32_bf16 v[108:111], v[158:161], v[200:203], v[108:111]
	v_mfma_f32_16x16x32_bf16 v[104:107], v[166:169], v[200:203], v[104:107]
	v_mfma_f32_16x16x32_bf16 v[92:95], v[158:161], v[208:211], v[92:95]
	v_mfma_f32_16x16x32_bf16 v[88:91], v[166:169], v[208:211], v[88:91]
	v_mfma_f32_16x16x32_bf16 v[76:79], v[158:161], v[216:219], v[76:79]
	v_mfma_f32_16x16x32_bf16 v[72:75], v[166:169], v[216:219], v[72:75]
	s_setprio 0
	s_setprio 1
	v_mfma_f32_16x16x32_bf16 v[116:119], v[170:173], v[188:191], v[116:119]
	v_mfma_f32_16x16x32_bf16 v[112:115], v[178:181], v[188:191], v[112:115]
	v_mfma_f32_16x16x32_bf16 v[100:103], v[170:173], v[196:199], v[100:103]
	v_mfma_f32_16x16x32_bf16 v[96:99], v[178:181], v[196:199], v[96:99]
	v_mfma_f32_16x16x32_bf16 v[84:87], v[170:173], v[204:207], v[84:87]
	v_mfma_f32_16x16x32_bf16 v[80:83], v[178:181], v[204:207], v[80:83]
	v_mfma_f32_16x16x32_bf16 v[68:71], v[170:173], v[212:215], v[68:71]
	v_mfma_f32_16x16x32_bf16 v[64:67], v[178:181], v[212:215], v[64:67]
	v_mfma_f32_16x16x32_bf16 v[116:119], v[174:177], v[192:195], v[116:119]
	v_mfma_f32_16x16x32_bf16 v[112:115], v[182:185], v[192:195], v[112:115]
	v_mfma_f32_16x16x32_bf16 v[100:103], v[174:177], v[200:203], v[100:103]
	v_mfma_f32_16x16x32_bf16 v[96:99], v[182:185], v[200:203], v[96:99]
	v_mfma_f32_16x16x32_bf16 v[84:87], v[174:177], v[208:211], v[84:87]
	v_mfma_f32_16x16x32_bf16 v[80:83], v[182:185], v[208:211], v[80:83]
	v_mfma_f32_16x16x32_bf16 v[68:71], v[174:177], v[216:219], v[68:71]
	s_barrier
; #define PG8_STAGE(bufoff, gbase, voff) do { _Pragma("unroll") for (int _i = 0; _i < 2; ++_i) \
;         __builtin_amdgcn_global_load_lds((const unsigned*)((const char*)(gbase) + (voff)[_i]), (PG8_LAS unsigned*)(lds + (bufoff) + ldsw + _i * 8192), 16, 0, 0); } while (0)
; #define PG8_LDA(dst, b, h) do { _Pragma("unroll") for (int m = 0; m < 4; ++m) _Pragma("unroll") for (int k = 0; k < 2; ++k) dst[m][k] = *(const PG8_LAS bf16x8*)(lds + PG8_SA(b, h) + aoff + m * 2048 + k * 1024); } while (0)
; #define PG8_MMA(ai, bj, At, Bt) do { __builtin_amdgcn_s_setprio(1); _Pragma("unroll") for (int m = 0; m < 4; ++m) _Pragma("unroll") for (int n = 0; n < 2; ++n) _Pragma("unroll") for (int k = 0; k < 2; ++k) \
;         acc[ai][bj][m][n] = __builtin_amdgcn_mfma_f32_16x16x32_bf16(Bt[n][k], At[m][k], acc[ai][bj][m][n], 0, 0, 0); __builtin_amdgcn_s_setprio(0); } while (0)
; #define PG8_WAIT_V(n) asm volatile("s_waitcnt vmcnt(" #n ")" ::: "memory")
; #define PG8_WAIT_L(n) asm volatile("s_waitcnt lgkmcnt(" #n ")" ::: "memory")
; #define PG8_BAR __builtin_amdgcn_s_barrier()
; #define PG8_SCHED __builtin_amdgcn_sched_barrier(0)
; template <class Epi, class Sched, bool ALIGN_EPI = false, bool SP2 = false>
; __device__ __forceinline__ void gemm_phase(PG8_LAS unsigned char* lds, const Gemm g, const Sched& S, const Epi& E) {
;     ...
;         for (int t = 0; t < nt; t += 2) {
;             const bool last = (t == nt - 2);
;     ...
;             PG8_LDA(At, 1, 1); PG8_STAGE(PG8_SB(1, 0), b3, voffB); PG8_STAGE(PG8_SB(1, 1), b3 + hstepB, voffB); PG8_STAGE(PG8_SA(1, 0), a3, voffA);
;             PG8_WAIT_V(8); PG8_WAIT_L(0); PG8_BAR; PG8_MMA(1, 0, At, B0); PG8_MMA(1, 1, At, B1); PG8_BAR; PG8_SCHED;
	v_mfma_f32_16x16x32_bf16 v[64:67], v[182:185], v[216:219], v[64:67]
	s_setprio 0
	s_add_i32 s28, s58, s40
	v_lshl_add_u64 v[148:149], v[148:149], 0, s[12:13]
	s_mov_b32 m0, s28
	ds_read_b128 v[188:191], v155 offset:49152
	ds_read_b128 v[192:195], v155 offset:50176
	ds_read_b128 v[196:199], v155 offset:51200
	ds_read_b128 v[200:203], v155 offset:52224
	ds_read_b128 v[204:207], v155 offset:53248
	ds_read_b128 v[208:211], v155 offset:54272
	ds_read_b128 v[212:215], v155 offset:55296
	ds_read_b128 v[216:219], v155 offset:56320
	global_load_lds_dwordx4 v[148:149], off
	s_add_i32 m0, s28, 0x2000
	s_add_u32 s28, s34, 0x18080
	v_lshl_add_u64 v[148:149], v[220:221], 0, s[12:13]
	s_addc_u32 s29, s35, 0
	s_add_i32 s34, s59, s40
	global_load_lds_dwordx4 v[148:149], off
	v_lshl_add_u64 v[148:149], s[28:29], 0, v[132:133]
	s_mov_b32 m0, s34
	s_nop 0
	global_load_lds_dwordx4 v[148:149], off
	v_lshl_add_u64 v[148:149], s[28:29], 0, v[128:129]
	s_add_i32 m0, s34, 0x2000
	s_nop 0
	global_load_lds_dwordx4 v[148:149], off
	v_lshl_add_u64 v[148:149], v[222:223], 0, s[12:13]
	s_mov_b32 m0, s47
	s_nop 0
	global_load_lds_dwordx4 v[148:149], off
	v_lshl_add_u64 v[148:149], v[224:225], 0, s[12:13]
	s_mov_b32 m0, s48
	s_nop 0
	global_load_lds_dwordx4 v[148:149], off
	s_waitcnt vmcnt(8) lgkmcnt(0)
	s_barrier
	s_setprio 1
	v_mfma_f32_16x16x32_bf16 v[60:63], v[144:147], v[188:191], v[60:63]
	v_mfma_f32_16x16x32_bf16 v[56:59], v[162:165], v[188:191], v[56:59]
	v_mfma_f32_16x16x32_bf16 v[44:47], v[144:147], v[196:199], v[44:47]
	v_mfma_f32_16x16x32_bf16 v[40:43], v[162:165], v[196:199], v[40:43]
	v_mfma_f32_16x16x32_bf16 v[28:31], v[144:147], v[204:207], v[28:31]
	v_mfma_f32_16x16x32_bf16 v[24:27], v[162:165], v[204:207], v[24:27]
	v_mfma_f32_16x16x32_bf16 v[12:15], v[144:147], v[212:215], v[12:15]
	v_mfma_f32_16x16x32_bf16 v[8:11], v[162:165], v[212:215], v[8:11]
	v_mfma_f32_16x16x32_bf16 v[60:63], v[158:161], v[192:195], v[60:63]
	v_mfma_f32_16x16x32_bf16 v[56:59], v[166:169], v[192:195], v[56:59]
	v_mfma_f32_16x16x32_bf16 v[44:47], v[158:161], v[200:203], v[44:47]
	v_mfma_f32_16x16x32_bf16 v[40:43], v[166:169], v[200:203], v[40:43]
	v_mfma_f32_16x16x32_bf16 v[28:31], v[158:161], v[208:211], v[28:31]
	v_mfma_f32_16x16x32_bf16 v[24:27], v[166:169], v[208:211], v[24:27]
	v_mfma_f32_16x16x32_bf16 v[12:15], v[158:161], v[216:219], v[12:15]
	v_mfma_f32_16x16x32_bf16 v[8:11], v[166:169], v[216:219], v[8:11]
	s_setprio 0
	s_setprio 1
	v_mfma_f32_16x16x32_bf16 v[52:55], v[170:173], v[188:191], v[52:55]
	v_mfma_f32_16x16x32_bf16 v[48:51], v[178:181], v[188:191], v[48:51]
	v_mfma_f32_16x16x32_bf16 v[36:39], v[170:173], v[196:199], v[36:39]
	v_mfma_f32_16x16x32_bf16 v[32:35], v[178:181], v[196:199], v[32:35]
	v_mfma_f32_16x16x32_bf16 v[20:23], v[170:173], v[204:207], v[20:23]
	v_mfma_f32_16x16x32_bf16 v[16:19], v[178:181], v[204:207], v[16:19]
	v_mfma_f32_16x16x32_bf16 v[4:7], v[170:173], v[212:215], v[4:7]
	v_mfma_f32_16x16x32_bf16 v[0:3], v[178:181], v[212:215], v[0:3]
	v_mfma_f32_16x16x32_bf16 v[52:55], v[174:177], v[192:195], v[52:55]
	v_mfma_f32_16x16x32_bf16 v[48:51], v[182:185], v[192:195], v[48:51]
	v_mfma_f32_16x16x32_bf16 v[36:39], v[174:177], v[200:203], v[36:39]
	v_mfma_f32_16x16x32_bf16 v[32:35], v[182:185], v[200:203], v[32:35]
	v_mfma_f32_16x16x32_bf16 v[20:23], v[174:177], v[208:211], v[20:23]
	v_mfma_f32_16x16x32_bf16 v[16:19], v[182:185], v[208:211], v[16:19]
	v_mfma_f32_16x16x32_bf16 v[4:7], v[174:177], v[216:219], v[4:7]
	s_barrier
	v_mfma_f32_16x16x32_bf16 v[0:3], v[182:185], v[216:219], v[0:3]
	s_setprio 0
	s_add_i32 s76, s76, 2
	s_add_u32 s74, s74, 0x100
	s_addc_u32 s75, s75, 0
	s_cmp_gt_u32 s76, 3
	s_mov_b64 s[28:29], s[30:31]
	s_cbranch_scc0 .LBB0_524
	s_and_b64 vcc, exec, s[14:15]
	s_cbranch_vccz .LBB0_527
	s_barrier

; #define PG8_STAGE(bufoff, gbase, voff) do { _Pragma("unroll") for (int _i = 0; _i < 2; ++_i) \
;         __builtin_amdgcn_global_load_lds((const unsigned*)((const char*)(gbase) + (voff)[_i]), (PG8_LAS unsigned*)(lds + (bufoff) + ldsw + _i * 8192), 16, 0, 0); } while (0)
; #define PG8_LDA(dst, b, h) do { _Pragma("unroll") for (int m = 0; m < 4; ++m) _Pragma("unroll") for (int k = 0; k < 2; ++k) dst[m][k] = *(const PG8_LAS bf16x8*)(lds + PG8_SA(b, h) + aoff + m * 2048 + k * 1024); } while (0)
; #define PG8_LDB(dst, b, h) do { _Pragma("unroll") for (int n = 0; n < 2; ++n) _Pragma("unroll") for (int k = 0; k < 2; ++k) dst[n][k] = *(const PG8_LAS bf16x8*)(lds + PG8_SB(b, h) + boff + n * 2048 + k * 1024); } while (0)
; #define PG8_WAIT_V(n) asm volatile("s_waitcnt vmcnt(" #n ")" ::: "memory")
; #define PG8_WAIT_L(n) asm volatile("s_waitcnt lgkmcnt(" #n ")" ::: "memory")
; #define PG8_BAR __builtin_amdgcn_s_barrier()
; #define PG8_SCHED __builtin_amdgcn_sched_barrier(0)
; template <class Epi, class Sched, bool ALIGN_EPI = false, bool SP2 = false>
; __device__ __forceinline__ void gemm_phase(PG8_LAS unsigned char* lds, const Gemm g, const Sched& S, const Epi& E) {
;     ...
;         const bool has_next = S.next(ui + 1, nxt);
;         const char* nA = has_next ? (const char*)g.A + (size_t)nxt.pm * tstepA : cA; const char* nB = has_next ? (const char*)g.Bt + (size_t)nxt.pn * tstepB : cB;
;         for (int t = 0; t < nt; t += 2) {
;             const bool last = (t == nt - 2);
;             const char* a1 = cA + (size_t)(t + 1) * kstep;
;             const char* a2 = last ? nA : cA + (size_t)(t + 2) * kstep; const char* b2 = last ? nB : cB + (size_t)(t + 2) * kstep;
;             const char* a3 = a2 + kstep; const char* b3 = b2 + kstep;
;             if (last && has_next) S.a_ready(nxt);
;             if constexpr (SP2) {
;             PG8_LDB(B0, 0, 0); PG8_LDB(B1, 0, 1); PG8_SCHED; PG8_LDA(At, 0, 0); PG8_STAGE(PG8_SA(1, 1), a1 + hstepA, voffA);
;             PG8_WAIT_V(8); PG8_WAIT_L(0); PG8_BAR; PG8_MMA(0, 0, At, B0); PG8_MMA(0, 1, At, B1); PG8_BAR; PG8_SCHED;
;             PG8_LDA(At, 0, 1); PG8_STAGE(PG8_SB(0, 0), b2, voffB); PG8_STAGE(PG8_SB(0, 1), b2 + hstepB, voffB); PG8_STAGE(PG8_SA(0, 0), a2, voffA);
;             PG8_WAIT_V(8); PG8_WAIT_L(0); PG8_BAR; PG8_MMA(1, 0, At, B0); PG8_MMA(1, 1, At, B1); PG8_BAR; PG8_SCHED;
.LBB0_542:
	s_add_u32 s39, s34, s38
	s_addc_u32 s44, s35, 0
	s_add_u32 s42, s39, 0x100
	s_addc_u32 s43, s44, 0
	s_and_b64 s[40:41], s[36:37], exec
	s_cselect_b32 s41, s27, s43
	s_cselect_b32 s40, s26, s42
	s_add_u32 s38, s30, s38
	s_addc_u32 s42, s31, 0
	s_add_u32 s38, s38, 0x100
	s_addc_u32 s42, s42, 0
	s_and_b64 s[36:37], s[36:37], exec
	s_cselect_b32 s43, s25, s42
	s_cselect_b32 s42, s89, s38
	s_add_u32 s46, s39, 0x30080
	ds_read_b128 v[140:143], v149
	ds_read_b128 v[154:157], v149 offset:1024
	ds_read_b128 v[158:161], v149 offset:2048
	ds_read_b128 v[162:165], v149 offset:3072
	ds_read_b128 v[166:169], v150
	ds_read_b128 v[170:173], v150 offset:1024
	ds_read_b128 v[174:177], v150 offset:2048
	ds_read_b128 v[178:181], v150 offset:3072
	s_addc_u32 s47, s44, 0
	s_add_i32 vcc_hi, s78, s68
	s_add_i32 m0, s70, 0xc000
	s_add_i32 s58, s70, 0xe000
	s_add_i32 s96, vcc_hi, 0x2000
	s_add_u32 s44, s42, 0x10000
	s_addc_u32 s45, s43, 0
	s_add_i32 vcc_lo, s79, s68
	s_add_i32 s97, vcc_lo, 0x2000
	s_add_i32 s95, 0, 0x18000
	s_add_i32 s94, 0, 0x1c000
	s_add_u32 s38, s40, 0x30000
	s_addc_u32 s39, s41, 0
	s_add_i32 s93, s95, s68
	s_add_i32 s91, s93, 0x2000
	s_add_u32 s36, s42, 0x10080
	s_addc_u32 s37, s43, 0
	s_add_i32 s92, s94, s68
	s_add_i32 s90, s92, 0x2000
	v_lshl_add_u64 v[144:145], s[46:47], 0, v[134:135]
	ds_read_b128 v[182:185], v151
	ds_read_b128 v[188:191], v151 offset:1024
	ds_read_b128 v[192:195], v151 offset:2048
	ds_read_b128 v[196:199], v151 offset:3072
	ds_read_b128 v[200:203], v151 offset:4096
	ds_read_b128 v[204:207], v151 offset:5120
	ds_read_b128 v[208:211], v151 offset:6144
	ds_read_b128 v[212:215], v151 offset:7168
	global_load_lds_dwordx4 v[144:145], off
	v_lshl_add_u64 v[144:145], s[46:47], 0, v[130:131]
	s_mov_b32 m0, s58
	s_nop 0
	global_load_lds_dwordx4 v[144:145], off
	s_waitcnt vmcnt(8) lgkmcnt(0)
	s_barrier
	s_setprio 1
	v_mfma_f32_16x16x32_bf16 v[124:127], v[140:143], v[182:185], v[124:127]
	v_mfma_f32_16x16x32_bf16 v[120:123], v[158:161], v[182:185], v[120:123]
	v_mfma_f32_16x16x32_bf16 v[108:111], v[140:143], v[192:195], v[108:111]
	v_mfma_f32_16x16x32_bf16 v[104:107], v[158:161], v[192:195], v[104:107]
	v_mfma_f32_16x16x32_bf16 v[92:95], v[140:143], v[200:203], v[92:95]
	v_mfma_f32_16x16x32_bf16 v[88:91], v[158:161], v[200:203], v[88:91]
	v_mfma_f32_16x16x32_bf16 v[76:79], v[140:143], v[208:211], v[76:79]
	v_mfma_f32_16x16x32_bf16 v[72:75], v[158:161], v[208:211], v[72:75]
	v_mfma_f32_16x16x32_bf16 v[124:127], v[154:157], v[188:191], v[124:127]
	v_mfma_f32_16x16x32_bf16 v[120:123], v[162:165], v[188:191], v[120:123]
	v_mfma_f32_16x16x32_bf16 v[108:111], v[154:157], v[196:199], v[108:111]
	v_mfma_f32_16x16x32_bf16 v[104:107], v[162:165], v[196:199], v[104:107]
	v_mfma_f32_16x16x32_bf16 v[92:95], v[154:157], v[204:207], v[92:95]
	v_mfma_f32_16x16x32_bf16 v[88:91], v[162:165], v[204:207], v[88:91]
	v_mfma_f32_16x16x32_bf16 v[76:79], v[154:157], v[212:215], v[76:79]
	v_mfma_f32_16x16x32_bf16 v[72:75], v[162:165], v[212:215], v[72:75]
	s_setprio 0
	s_setprio 1
	v_mfma_f32_16x16x32_bf16 v[116:119], v[166:169], v[182:185], v[116:119]
	v_mfma_f32_16x16x32_bf16 v[112:115], v[174:177], v[182:185], v[112:115]
	v_mfma_f32_16x16x32_bf16 v[100:103], v[166:169], v[192:195], v[100:103]
	v_mfma_f32_16x16x32_bf16 v[96:99], v[174:177], v[192:195], v[96:99]
	v_mfma_f32_16x16x32_bf16 v[84:87], v[166:169], v[200:203], v[84:87]
	v_mfma_f32_16x16x32_bf16 v[80:83], v[174:177], v[200:203], v[80:83]
	v_mfma_f32_16x16x32_bf16 v[68:71], v[166:169], v[208:211], v[68:71]
	v_mfma_f32_16x16x32_bf16 v[64:67], v[174:177], v[208:211], v[64:67]
	v_mfma_f32_16x16x32_bf16 v[116:119], v[170:173], v[188:191], v[116:119]
	v_mfma_f32_16x16x32_bf16 v[112:115], v[178:181], v[188:191], v[112:115]
	v_mfma_f32_16x16x32_bf16 v[100:103], v[170:173], v[196:199], v[100:103]
	v_mfma_f32_16x16x32_bf16 v[96:99], v[178:181], v[196:199], v[96:99]
	v_mfma_f32_16x16x32_bf16 v[84:87], v[170:173], v[204:207], v[84:87]
	v_mfma_f32_16x16x32_bf16 v[80:83], v[178:181], v[204:207], v[80:83]
	v_mfma_f32_16x16x32_bf16 v[68:71], v[170:173], v[212:215], v[68:71]
	s_barrier
	v_mfma_f32_16x16x32_bf16 v[64:67], v[178:181], v[212:215], v[64:67]
	s_setprio 0
	s_mov_b32 m0, vcc_hi
	v_lshl_add_u64 v[144:145], s[42:43], 0, v[132:133]
	ds_read_b128 v[182:185], v151 offset:16384
	ds_read_b128 v[188:191], v151 offset:17408
	ds_read_b128 v[192:195], v151 offset:18432
	ds_read_b128 v[196:199], v151 offset:19456
	ds_read_b128 v[200:203], v151 offset:20480
	ds_read_b128 v[204:207], v151 offset:21504
	ds_read_b128 v[208:211], v151 offset:22528
	ds_read_b128 v[212:215], v151 offset:23552
	global_load_lds_dwordx4 v[144:145], off
	v_lshl_add_u64 v[216:217], s[42:43], 0, v[128:129]
	s_mov_b32 m0, s96
	v_lshl_add_u64 v[218:219], s[44:45], 0, v[132:133]
	global_load_lds_dwordx4 v[216:217], off
	s_mov_b32 m0, vcc_lo
	v_lshl_add_u64 v[220:221], s[40:41], 0, v[130:131]
	global_load_lds_dwordx4 v[218:219], off
	v_lshl_add_u64 v[218:219], s[44:45], 0, v[128:129]
	s_mov_b32 m0, s97
	s_nop 0
	global_load_lds_dwordx4 v[218:219], off
	v_lshl_add_u64 v[218:219], s[40:41], 0, v[134:135]
	s_mov_b32 m0, s70
	s_nop 0
	global_load_lds_dwordx4 v[218:219], off
	s_mov_b32 m0, s71
	s_nop 0
	global_load_lds_dwordx4 v[220:221], off
	s_waitcnt vmcnt(8) lgkmcnt(0)
	s_barrier
; #define PG8_STAGE(bufoff, gbase, voff) do { _Pragma("unroll") for (int _i = 0; _i < 2; ++_i) \
;         __builtin_amdgcn_global_load_lds((const unsigned*)((const char*)(gbase) + (voff)[_i]), (PG8_LAS unsigned*)(lds + (bufoff) + ldsw + _i * 8192), 16, 0, 0); } while (0)
; #define PG8_LDA(dst, b, h) do { _Pragma("unroll") for (int m = 0; m < 4; ++m) _Pragma("unroll") for (int k = 0; k < 2; ++k) dst[m][k] = *(const PG8_LAS bf16x8*)(lds + PG8_SA(b, h) + aoff + m * 2048 + k * 1024); } while (0)
; #define PG8_LDB(dst, b, h) do { _Pragma("unroll") for (int n = 0; n < 2; ++n) _Pragma("unroll") for (int k = 0; k < 2; ++k) dst[n][k] = *(const PG8_LAS bf16x8*)(lds + PG8_SB(b, h) + boff + n * 2048 + k * 1024); } while (0)
; #define PG8_MMA(ai, bj, At, Bt) do { __builtin_amdgcn_s_setprio(1); _Pragma("unroll") for (int m = 0; m < 4; ++m) _Pragma("unroll") for (int n = 0; n < 2; ++n) _Pragma("unroll") for (int k = 0; k < 2; ++k) \
;         acc[ai][bj][m][n] = __builtin_amdgcn_mfma_f32_16x16x32_bf16(Bt[n][k], At[m][k], acc[ai][bj][m][n], 0, 0, 0); __builtin_amdgcn_s_setprio(0); } while (0)
; #define PG8_WAIT_V(n) asm volatile("s_waitcnt vmcnt(" #n ")" ::: "memory")
; #define PG8_WAIT_L(n) asm volatile("s_waitcnt lgkmcnt(" #n ")" ::: "memory")
; #define PG8_BAR __builtin_amdgcn_s_barrier()
; #define PG8_SCHED __builtin_amdgcn_sched_barrier(0)
; template <class Epi, class Sched, bool ALIGN_EPI = false, bool SP2 = false>
; __device__ __forceinline__ void gemm_phase(PG8_LAS unsigned char* lds, const Gemm g, const Sched& S, const Epi& E) {
;     ...
;             PG8_WAIT_V(8); PG8_WAIT_L(0); PG8_BAR; PG8_MMA(1, 0, At, B0); PG8_MMA(1, 1, At, B1); PG8_BAR; PG8_SCHED;
;             PG8_LDB(B0, 1, 0); PG8_LDB(B1, 1, 1); PG8_SCHED; PG8_LDA(At, 1, 0); PG8_STAGE(PG8_SA(0, 1), a2 + hstepA, voffA);
;             PG8_WAIT_V(8); PG8_WAIT_L(0); PG8_BAR; PG8_MMA(0, 0, At, B0); PG8_MMA(0, 1, At, B1); PG8_BAR; PG8_SCHED;
	s_setprio 1
	v_mfma_f32_16x16x32_bf16 v[60:63], v[140:143], v[182:185], v[60:63]
	v_mfma_f32_16x16x32_bf16 v[56:59], v[158:161], v[182:185], v[56:59]
	v_mfma_f32_16x16x32_bf16 v[44:47], v[140:143], v[192:195], v[44:47]
	v_mfma_f32_16x16x32_bf16 v[40:43], v[158:161], v[192:195], v[40:43]
	v_mfma_f32_16x16x32_bf16 v[28:31], v[140:143], v[200:203], v[28:31]
	v_mfma_f32_16x16x32_bf16 v[24:27], v[158:161], v[200:203], v[24:27]
	v_mfma_f32_16x16x32_bf16 v[12:15], v[140:143], v[208:211], v[12:15]
	v_mfma_f32_16x16x32_bf16 v[8:11], v[158:161], v[208:211], v[8:11]
	v_mfma_f32_16x16x32_bf16 v[60:63], v[154:157], v[188:191], v[60:63]
	v_mfma_f32_16x16x32_bf16 v[56:59], v[162:165], v[188:191], v[56:59]
	v_mfma_f32_16x16x32_bf16 v[44:47], v[154:157], v[196:199], v[44:47]
	v_mfma_f32_16x16x32_bf16 v[40:43], v[162:165], v[196:199], v[40:43]
	v_mfma_f32_16x16x32_bf16 v[28:31], v[154:157], v[204:207], v[28:31]
	v_mfma_f32_16x16x32_bf16 v[24:27], v[162:165], v[204:207], v[24:27]
	v_mfma_f32_16x16x32_bf16 v[12:15], v[154:157], v[212:215], v[12:15]
	v_mfma_f32_16x16x32_bf16 v[8:11], v[162:165], v[212:215], v[8:11]
	s_setprio 0
	s_setprio 1
	v_mfma_f32_16x16x32_bf16 v[52:55], v[166:169], v[182:185], v[52:55]
	v_mfma_f32_16x16x32_bf16 v[48:51], v[174:177], v[182:185], v[48:51]
	v_mfma_f32_16x16x32_bf16 v[36:39], v[166:169], v[192:195], v[36:39]
	v_mfma_f32_16x16x32_bf16 v[32:35], v[174:177], v[192:195], v[32:35]
	v_mfma_f32_16x16x32_bf16 v[20:23], v[166:169], v[200:203], v[20:23]
	v_mfma_f32_16x16x32_bf16 v[16:19], v[174:177], v[200:203], v[16:19]
	v_mfma_f32_16x16x32_bf16 v[4:7], v[166:169], v[208:211], v[4:7]
	v_mfma_f32_16x16x32_bf16 v[0:3], v[174:177], v[208:211], v[0:3]
	v_mfma_f32_16x16x32_bf16 v[52:55], v[170:173], v[188:191], v[52:55]
	v_mfma_f32_16x16x32_bf16 v[48:51], v[178:181], v[188:191], v[48:51]
	v_mfma_f32_16x16x32_bf16 v[36:39], v[170:173], v[196:199], v[36:39]
	v_mfma_f32_16x16x32_bf16 v[32:35], v[178:181], v[196:199], v[32:35]
	v_mfma_f32_16x16x32_bf16 v[20:23], v[170:173], v[204:207], v[20:23]
	v_mfma_f32_16x16x32_bf16 v[16:19], v[178:181], v[204:207], v[16:19]
	v_mfma_f32_16x16x32_bf16 v[4:7], v[170:173], v[212:215], v[4:7]
	s_barrier
	v_mfma_f32_16x16x32_bf16 v[0:3], v[178:181], v[212:215], v[0:3]
	s_setprio 0
	v_add_u32_e32 v153, s95, v147
	ds_read_b128 v[140:143], v153
	ds_read_b128 v[154:157], v153 offset:1024
	ds_read_b128 v[158:161], v153 offset:2048
	ds_read_b128 v[162:165], v153 offset:3072
	v_add_u32_e32 v153, s94, v147
	ds_read_b128 v[166:169], v153
	ds_read_b128 v[170:173], v153 offset:1024
	ds_read_b128 v[174:177], v153 offset:2048
	ds_read_b128 v[178:181], v153 offset:3072
	s_mov_b32 m0, s72
	v_lshl_add_u64 v[222:223], s[38:39], 0, v[134:135]
	ds_read_b128 v[182:185], v151 offset:32768
	ds_read_b128 v[188:191], v151 offset:33792
	ds_read_b128 v[192:195], v151 offset:34816
	ds_read_b128 v[196:199], v151 offset:35840
	ds_read_b128 v[200:203], v151 offset:36864
	ds_read_b128 v[204:207], v151 offset:37888
	ds_read_b128 v[208:211], v151 offset:38912
	ds_read_b128 v[212:215], v151 offset:39936
	global_load_lds_dwordx4 v[222:223], off
	v_lshl_add_u64 v[222:223], s[38:39], 0, v[130:131]
	s_mov_b32 m0, s73
	s_nop 0
	global_load_lds_dwordx4 v[222:223], off
	s_waitcnt vmcnt(8) lgkmcnt(0)
	s_barrier
	s_setprio 1
	v_mfma_f32_16x16x32_bf16 v[124:127], v[140:143], v[182:185], v[124:127]
	v_mfma_f32_16x16x32_bf16 v[120:123], v[158:161], v[182:185], v[120:123]
	v_mfma_f32_16x16x32_bf16 v[108:111], v[140:143], v[192:195], v[108:111]
	v_mfma_f32_16x16x32_bf16 v[104:107], v[158:161], v[192:195], v[104:107]
	v_mfma_f32_16x16x32_bf16 v[92:95], v[140:143], v[200:203], v[92:95]
	v_mfma_f32_16x16x32_bf16 v[88:91], v[158:161], v[200:203], v[88:91]
	v_mfma_f32_16x16x32_bf16 v[76:79], v[140:143], v[208:211], v[76:79]
	v_mfma_f32_16x16x32_bf16 v[72:75], v[158:161], v[208:211], v[72:75]
	v_mfma_f32_16x16x32_bf16 v[124:127], v[154:157], v[188:191], v[124:127]
	v_mfma_f32_16x16x32_bf16 v[120:123], v[162:165], v[188:191], v[120:123]
	v_mfma_f32_16x16x32_bf16 v[108:111], v[154:157], v[196:199], v[108:111]
	v_mfma_f32_16x16x32_bf16 v[104:107], v[162:165], v[196:199], v[104:107]
	v_mfma_f32_16x16x32_bf16 v[92:95], v[154:157], v[204:207], v[92:95]
	v_mfma_f32_16x16x32_bf16 v[88:91], v[162:165], v[204:207], v[88:91]
	v_mfma_f32_16x16x32_bf16 v[76:79], v[154:157], v[212:215], v[76:79]
	v_mfma_f32_16x16x32_bf16 v[72:75], v[162:165], v[212:215], v[72:75]
	s_setprio 0
	s_setprio 1
	v_mfma_f32_16x16x32_bf16 v[116:119], v[166:169], v[182:185], v[116:119]
	v_mfma_f32_16x16x32_bf16 v[112:115], v[174:177], v[182:185], v[112:115]
	v_mfma_f32_16x16x32_bf16 v[100:103], v[166:169], v[192:195], v[100:103]
	v_mfma_f32_16x16x32_bf16 v[96:99], v[174:177], v[192:195], v[96:99]
	v_mfma_f32_16x16x32_bf16 v[84:87], v[166:169], v[200:203], v[84:87]
	v_mfma_f32_16x16x32_bf16 v[80:83], v[174:177], v[200:203], v[80:83]
	v_mfma_f32_16x16x32_bf16 v[68:71], v[166:169], v[208:211], v[68:71]
	v_mfma_f32_16x16x32_bf16 v[64:67], v[174:177], v[208:211], v[64:67]
	v_mfma_f32_16x16x32_bf16 v[116:119], v[170:173], v[188:191], v[116:119]
	v_mfma_f32_16x16x32_bf16 v[112:115], v[178:181], v[188:191], v[112:115]
	v_mfma_f32_16x16x32_bf16 v[100:103], v[170:173], v[196:199], v[100:103]
	v_mfma_f32_16x16x32_bf16 v[96:99], v[178:181], v[196:199], v[96:99]
	v_mfma_f32_16x16x32_bf16 v[84:87], v[170:173], v[204:207], v[84:87]
	v_mfma_f32_16x16x32_bf16 v[80:83], v[178:181], v[204:207], v[80:83]
	v_mfma_f32_16x16x32_bf16 v[68:71], v[170:173], v[212:215], v[68:71]
	s_barrier
; #define PG8_STAGE(bufoff, gbase, voff) do { _Pragma("unroll") for (int _i = 0; _i < 2; ++_i) \
;         __builtin_amdgcn_global_load_lds((const unsigned*)((const char*)(gbase) + (voff)[_i]), (PG8_LAS unsigned*)(lds + (bufoff) + ldsw + _i * 8192), 16, 0, 0); } while (0)
; #define PG8_LDA(dst, b, h) do { _Pragma("unroll") for (int m = 0; m < 4; ++m) _Pragma("unroll") for (int k = 0; k < 2; ++k) dst[m][k] = *(const PG8_LAS bf16x8*)(lds + PG8_SA(b, h) + aoff + m * 2048 + k * 1024); } while (0)
; #define PG8_MMA(ai, bj, At, Bt) do { __builtin_amdgcn_s_setprio(1); _Pragma("unroll") for (int m = 0; m < 4; ++m) _Pragma("unroll") for (int n = 0; n < 2; ++n) _Pragma("unroll") for (int k = 0; k < 2; ++k) \
;         acc[ai][bj][m][n] = __builtin_amdgcn_mfma_f32_16x16x32_bf16(Bt[n][k], At[m][k], acc[ai][bj][m][n], 0, 0, 0); __builtin_amdgcn_s_setprio(0); } while (0)
; #define PG8_WAIT_V(n) asm volatile("s_waitcnt vmcnt(" #n ")" ::: "memory")
; #define PG8_WAIT_L(n) asm volatile("s_waitcnt lgkmcnt(" #n ")" ::: "memory")
; #define PG8_BAR __builtin_amdgcn_s_barrier()
; #define PG8_SCHED __builtin_amdgcn_sched_barrier(0)
; template <class Epi, class Sched, bool ALIGN_EPI = false, bool SP2 = false>
; __device__ __forceinline__ void gemm_phase(PG8_LAS unsigned char* lds, const Gemm g, const Sched& S, const Epi& E) {
;     ...
;         for (int t = 0; t < nt; t += 2) {
;     ...
;             PG8_LDA(At, 1, 1); PG8_STAGE(PG8_SB(1, 0), b3, voffB); PG8_STAGE(PG8_SB(1, 1), b3 + hstepB, voffB); PG8_STAGE(PG8_SA(1, 0), a3, voffA);
;             PG8_WAIT_V(8); PG8_WAIT_L(0); PG8_BAR; PG8_MMA(1, 0, At, B0); PG8_MMA(1, 1, At, B1); PG8_BAR; PG8_SCHED;
	v_mfma_f32_16x16x32_bf16 v[64:67], v[178:181], v[212:215], v[64:67]
	s_setprio 0
	s_mov_b32 m0, s93
	v_lshl_add_u64 v[144:145], v[144:145], 0, s[12:13]
	ds_read_b128 v[182:185], v151 offset:49152
	ds_read_b128 v[188:191], v151 offset:50176
	ds_read_b128 v[192:195], v151 offset:51200
	ds_read_b128 v[196:199], v151 offset:52224
	ds_read_b128 v[200:203], v151 offset:53248
	ds_read_b128 v[204:207], v151 offset:54272
	ds_read_b128 v[208:211], v151 offset:55296
	ds_read_b128 v[212:215], v151 offset:56320
	global_load_lds_dwordx4 v[144:145], off
	v_lshl_add_u64 v[144:145], v[216:217], 0, s[12:13]
	s_mov_b32 m0, s91
	s_nop 0
	global_load_lds_dwordx4 v[144:145], off
	v_lshl_add_u64 v[144:145], s[36:37], 0, v[132:133]
	s_mov_b32 m0, s92
	s_nop 0
	global_load_lds_dwordx4 v[144:145], off
	v_lshl_add_u64 v[144:145], s[36:37], 0, v[128:129]
	s_mov_b32 m0, s90
	s_nop 0
	global_load_lds_dwordx4 v[144:145], off
	v_lshl_add_u64 v[144:145], v[218:219], 0, s[12:13]
	s_mov_b32 m0, s75
	s_nop 0
	global_load_lds_dwordx4 v[144:145], off
	v_lshl_add_u64 v[144:145], v[220:221], 0, s[12:13]
	s_mov_b32 m0, s76
	s_nop 0
	global_load_lds_dwordx4 v[144:145], off
	s_waitcnt vmcnt(8) lgkmcnt(0)
	s_barrier
	s_setprio 1
	v_mfma_f32_16x16x32_bf16 v[60:63], v[140:143], v[182:185], v[60:63]
	v_mfma_f32_16x16x32_bf16 v[56:59], v[158:161], v[182:185], v[56:59]
	v_mfma_f32_16x16x32_bf16 v[44:47], v[140:143], v[192:195], v[44:47]
	v_mfma_f32_16x16x32_bf16 v[40:43], v[158:161], v[192:195], v[40:43]
	v_mfma_f32_16x16x32_bf16 v[28:31], v[140:143], v[200:203], v[28:31]
	v_mfma_f32_16x16x32_bf16 v[24:27], v[158:161], v[200:203], v[24:27]
	v_mfma_f32_16x16x32_bf16 v[12:15], v[140:143], v[208:211], v[12:15]
	v_mfma_f32_16x16x32_bf16 v[8:11], v[158:161], v[208:211], v[8:11]
	v_mfma_f32_16x16x32_bf16 v[60:63], v[154:157], v[188:191], v[60:63]
	v_mfma_f32_16x16x32_bf16 v[56:59], v[162:165], v[188:191], v[56:59]
	v_mfma_f32_16x16x32_bf16 v[44:47], v[154:157], v[196:199], v[44:47]
	v_mfma_f32_16x16x32_bf16 v[40:43], v[162:165], v[196:199], v[40:43]
	v_mfma_f32_16x16x32_bf16 v[28:31], v[154:157], v[204:207], v[28:31]
	v_mfma_f32_16x16x32_bf16 v[24:27], v[162:165], v[204:207], v[24:27]
	v_mfma_f32_16x16x32_bf16 v[12:15], v[154:157], v[212:215], v[12:15]
	v_mfma_f32_16x16x32_bf16 v[8:11], v[162:165], v[212:215], v[8:11]
	s_setprio 0
	s_setprio 1
	v_mfma_f32_16x16x32_bf16 v[52:55], v[166:169], v[182:185], v[52:55]
	v_mfma_f32_16x16x32_bf16 v[48:51], v[174:177], v[182:185], v[48:51]
	v_mfma_f32_16x16x32_bf16 v[36:39], v[166:169], v[192:195], v[36:39]
	v_mfma_f32_16x16x32_bf16 v[32:35], v[174:177], v[192:195], v[32:35]
	v_mfma_f32_16x16x32_bf16 v[20:23], v[166:169], v[200:203], v[20:23]
	v_mfma_f32_16x16x32_bf16 v[16:19], v[174:177], v[200:203], v[16:19]
	v_mfma_f32_16x16x32_bf16 v[4:7], v[166:169], v[208:211], v[4:7]
	v_mfma_f32_16x16x32_bf16 v[0:3], v[174:177], v[208:211], v[0:3]
	v_mfma_f32_16x16x32_bf16 v[52:55], v[170:173], v[188:191], v[52:55]
	v_mfma_f32_16x16x32_bf16 v[48:51], v[178:181], v[188:191], v[48:51]
	v_mfma_f32_16x16x32_bf16 v[36:39], v[170:173], v[196:199], v[36:39]
	v_mfma_f32_16x16x32_bf16 v[32:35], v[178:181], v[196:199], v[32:35]
	v_mfma_f32_16x16x32_bf16 v[20:23], v[170:173], v[204:207], v[20:23]
	v_mfma_f32_16x16x32_bf16 v[16:19], v[178:181], v[204:207], v[16:19]
	v_mfma_f32_16x16x32_bf16 v[4:7], v[170:173], v[212:215], v[4:7]
	s_barrier
	v_mfma_f32_16x16x32_bf16 v[0:3], v[178:181], v[212:215], v[0:3]
	s_setprio 0
	s_movk_i32 s38, 0x100
	s_andn2_b64 vcc, exec, s[8:9]
	s_mov_b64 s[36:37], -1
	s_mov_b64 s[8:9], 0
	s_cbranch_vccz .LBB0_542
	s_and_b64 vcc, exec, s[14:15]
	s_cbranch_vccz .LBB0_545
	s_barrier

; #define PG8_STAGE(bufoff, gbase, voff) do { _Pragma("unroll") for (int _i = 0; _i < 2; ++_i) \
;         __builtin_amdgcn_global_load_lds((const unsigned*)((const char*)(gbase) + (voff)[_i]), (PG8_LAS unsigned*)(lds + (bufoff) + ldsw + _i * 8192), 16, 0, 0); } while (0)
; #define PG8_LDA(dst, b, h) do { _Pragma("unroll") for (int m = 0; m < 4; ++m) _Pragma("unroll") for (int k = 0; k < 2; ++k) dst[m][k] = *(const PG8_LAS bf16x8*)(lds + PG8_SA(b, h) + aoff + m * 2048 + k * 1024); } while (0)
; #define PG8_LDB(dst, b, h) do { _Pragma("unroll") for (int n = 0; n < 2; ++n) _Pragma("unroll") for (int k = 0; k < 2; ++k) dst[n][k] = *(const PG8_LAS bf16x8*)(lds + PG8_SB(b, h) + boff + n * 2048 + k * 1024); } while (0)
; #define PG8_MMA(ai, bj, At, Bt) do { __builtin_amdgcn_s_setprio(1); _Pragma("unroll") for (int m = 0; m < 4; ++m) _Pragma("unroll") for (int n = 0; n < 2; ++n) _Pragma("unroll") for (int k = 0; k < 2; ++k) \
;         acc[ai][bj][m][n] = __builtin_amdgcn_mfma_f32_16x16x32_bf16(Bt[n][k], At[m][k], acc[ai][bj][m][n], 0, 0, 0); __builtin_amdgcn_s_setprio(0); } while (0)
; #define PG8_WAIT_V(n) asm volatile("s_waitcnt vmcnt(" #n ")" ::: "memory")
; #define PG8_BAR __builtin_amdgcn_s_barrier()
; template <class Epi, class Sched, bool ALIGN_EPI = false, bool SP2 = false>
; __device__ __forceinline__ void gemm_phase(PG8_LAS unsigned char* lds, const Gemm g, const Sched& S, const Epi& E) {
;     ...
;         for (int t = 0; t < nt; t += 2) {
;             const bool last = (t == nt - 2);
;             const char* a1 = cA + (size_t)(t + 1) * kstep;
;             const char* a2 = last ? nA : cA + (size_t)(t + 2) * kstep; const char* b2 = last ? nB : cB + (size_t)(t + 2) * kstep;
;             const char* a3 = a2 + kstep; const char* b3 = b2 + kstep;
;             if (last && has_next) S.a_ready(nxt);
;             if constexpr (SP2) {
;             PG8_LDB(B0, 0, 0); PG8_LDB(B1, 0, 1); PG8_SCHED; PG8_LDA(At, 0, 0); PG8_STAGE(PG8_SA(1, 1), a1 + hstepA, voffA);
;             PG8_WAIT_V(8); PG8_WAIT_L(0); PG8_BAR; PG8_MMA(0, 0, At, B0); PG8_MMA(0, 1, At, B1); PG8_BAR; PG8_SCHED;
;             PG8_LDA(At, 0, 1); PG8_STAGE(PG8_SB(0, 0), b2, voffB); PG8_STAGE(PG8_SB(0, 1), b2 + hstepB, voffB); PG8_STAGE(PG8_SA(0, 0), a2, voffA);
;             PG8_WAIT_V(8); PG8_WAIT_L(0); PG8_BAR; PG8_MMA(1, 0, At, B0); PG8_MMA(1, 1, At, B1); PG8_BAR; PG8_SCHED;
.LBB0_971:
	ds_read_b128 v[128:131], v191
	ds_read_b128 v[132:135], v191 offset:1024
	ds_read_b128 v[136:139], v191 offset:2048
	ds_read_b128 v[140:143], v191 offset:3072
	ds_read_b128 v[144:147], v192
	ds_read_b128 v[148:151], v192 offset:1024
	ds_read_b128 v[168:171], v192 offset:2048
	ds_read_b128 v[172:175], v192 offset:3072
	s_add_u32 s34, s30, 0xfffc0080
	s_addc_u32 s35, s31, -1
	s_cmp_eq_u32 s74, 12
	s_cselect_b32 s37, s21, s35
	s_cselect_b32 s36, s27, s34
	s_cselect_b32 s35, s19, s73
	s_cselect_b32 s34, s68, s69
	v_lshl_add_u64 v[184:185], s[30:31], 0, v[160:161]
	s_add_i32 m0, s29, 0xc000
	ds_read_b128 v[176:179], v193
	ds_read_b128 v[180:183], v193 offset:1024
	ds_read_b128 v[196:199], v193 offset:2048
	ds_read_b128 v[200:203], v193 offset:3072
	ds_read_b128 v[204:207], v193 offset:4096
	ds_read_b128 v[208:211], v193 offset:5120
	ds_read_b128 v[212:215], v193 offset:6144
	ds_read_b128 v[216:219], v193 offset:7168
	global_load_lds_dwordx4 v[184:185], off
	v_lshl_add_u64 v[184:185], s[30:31], 0, v[162:163]
	s_add_i32 m0, s29, 0xe000
	s_nop 0
	global_load_lds_dwordx4 v[184:185], off
	s_waitcnt vmcnt(8) lgkmcnt(0)
	s_barrier
	s_setprio 1
	v_mfma_f32_16x16x32_bf16 v[124:127], v[128:131], v[176:179], v[124:127]
	v_mfma_f32_16x16x32_bf16 v[120:123], v[136:139], v[176:179], v[120:123]
	v_mfma_f32_16x16x32_bf16 v[108:111], v[128:131], v[196:199], v[108:111]
	v_mfma_f32_16x16x32_bf16 v[104:107], v[136:139], v[196:199], v[104:107]
	v_mfma_f32_16x16x32_bf16 v[92:95], v[128:131], v[204:207], v[92:95]
	v_mfma_f32_16x16x32_bf16 v[88:91], v[136:139], v[204:207], v[88:91]
	v_mfma_f32_16x16x32_bf16 v[76:79], v[128:131], v[212:215], v[76:79]
	v_mfma_f32_16x16x32_bf16 v[72:75], v[136:139], v[212:215], v[72:75]
	v_mfma_f32_16x16x32_bf16 v[124:127], v[132:135], v[180:183], v[124:127]
	v_mfma_f32_16x16x32_bf16 v[120:123], v[140:143], v[180:183], v[120:123]
	v_mfma_f32_16x16x32_bf16 v[108:111], v[132:135], v[200:203], v[108:111]
	v_mfma_f32_16x16x32_bf16 v[104:107], v[140:143], v[200:203], v[104:107]
	v_mfma_f32_16x16x32_bf16 v[92:95], v[132:135], v[208:211], v[92:95]
	v_mfma_f32_16x16x32_bf16 v[88:91], v[140:143], v[208:211], v[88:91]
	v_mfma_f32_16x16x32_bf16 v[76:79], v[132:135], v[216:219], v[76:79]
	v_mfma_f32_16x16x32_bf16 v[72:75], v[140:143], v[216:219], v[72:75]
	s_setprio 0
	s_setprio 1
	v_mfma_f32_16x16x32_bf16 v[116:119], v[144:147], v[176:179], v[116:119]
	v_mfma_f32_16x16x32_bf16 v[112:115], v[168:171], v[176:179], v[112:115]
	v_mfma_f32_16x16x32_bf16 v[100:103], v[144:147], v[196:199], v[100:103]
	v_mfma_f32_16x16x32_bf16 v[96:99], v[168:171], v[196:199], v[96:99]
	v_mfma_f32_16x16x32_bf16 v[84:87], v[144:147], v[204:207], v[84:87]
	v_mfma_f32_16x16x32_bf16 v[80:83], v[168:171], v[204:207], v[80:83]
	v_mfma_f32_16x16x32_bf16 v[68:71], v[144:147], v[212:215], v[68:71]
	v_mfma_f32_16x16x32_bf16 v[64:67], v[168:171], v[212:215], v[64:67]
	v_mfma_f32_16x16x32_bf16 v[116:119], v[148:151], v[180:183], v[116:119]
	v_mfma_f32_16x16x32_bf16 v[112:115], v[172:175], v[180:183], v[112:115]
	v_mfma_f32_16x16x32_bf16 v[100:103], v[148:151], v[200:203], v[100:103]
	v_mfma_f32_16x16x32_bf16 v[96:99], v[172:175], v[200:203], v[96:99]
	v_mfma_f32_16x16x32_bf16 v[84:87], v[148:151], v[208:211], v[84:87]
	v_mfma_f32_16x16x32_bf16 v[80:83], v[172:175], v[208:211], v[80:83]
	v_mfma_f32_16x16x32_bf16 v[68:71], v[148:151], v[216:219], v[68:71]
	s_barrier
	v_mfma_f32_16x16x32_bf16 v[64:67], v[172:175], v[216:219], v[64:67]
	s_setprio 0
	s_add_i32 s58, s49, s39
	v_lshl_add_u64 v[184:185], s[34:35], 0, v[154:155]
	s_mov_b32 m0, s58
	ds_read_b128 v[176:179], v193 offset:16384
	ds_read_b128 v[180:183], v193 offset:17408
	ds_read_b128 v[196:199], v193 offset:18432
	ds_read_b128 v[200:203], v193 offset:19456
	ds_read_b128 v[204:207], v193 offset:20480
	ds_read_b128 v[208:211], v193 offset:21504
	ds_read_b128 v[212:215], v193 offset:22528
	ds_read_b128 v[216:219], v193 offset:23552
	global_load_lds_dwordx4 v[184:185], off
	s_add_i32 m0, s58, 0x2000
	s_add_u32 s58, s34, 0x40000
	v_lshl_add_u64 v[220:221], s[34:35], 0, v[158:159]
	s_addc_u32 s59, s35, 0
	s_add_i32 s75, s66, s39
	global_load_lds_dwordx4 v[220:221], off
	v_lshl_add_u64 v[222:223], s[58:59], 0, v[154:155]
	s_mov_b32 m0, s75
	v_lshl_add_u64 v[224:225], s[36:37], 0, v[156:157]
	global_load_lds_dwordx4 v[222:223], off
	v_lshl_add_u64 v[222:223], s[58:59], 0, v[158:159]
	s_add_i32 m0, s75, 0x2000
	s_nop 0
	global_load_lds_dwordx4 v[222:223], off
	v_lshl_add_u64 v[222:223], s[36:37], 0, v[152:153]
	s_mov_b32 m0, s29
	s_nop 0
	global_load_lds_dwordx4 v[222:223], off
	s_mov_b32 m0, s40
	s_nop 0
	global_load_lds_dwordx4 v[224:225], off
	s_waitcnt vmcnt(8) lgkmcnt(0)
	s_barrier
; #define PG8_STAGE(bufoff, gbase, voff) do { _Pragma("unroll") for (int _i = 0; _i < 2; ++_i) \
;         __builtin_amdgcn_global_load_lds((const unsigned*)((const char*)(gbase) + (voff)[_i]), (PG8_LAS unsigned*)(lds + (bufoff) + ldsw + _i * 8192), 16, 0, 0); } while (0)
; #define PG8_LDA(dst, b, h) do { _Pragma("unroll") for (int m = 0; m < 4; ++m) _Pragma("unroll") for (int k = 0; k < 2; ++k) dst[m][k] = *(const PG8_LAS bf16x8*)(lds + PG8_SA(b, h) + aoff + m * 2048 + k * 1024); } while (0)
; #define PG8_LDB(dst, b, h) do { _Pragma("unroll") for (int n = 0; n < 2; ++n) _Pragma("unroll") for (int k = 0; k < 2; ++k) dst[n][k] = *(const PG8_LAS bf16x8*)(lds + PG8_SB(b, h) + boff + n * 2048 + k * 1024); } while (0)
; #define PG8_MMA(ai, bj, At, Bt) do { __builtin_amdgcn_s_setprio(1); _Pragma("unroll") for (int m = 0; m < 4; ++m) _Pragma("unroll") for (int n = 0; n < 2; ++n) _Pragma("unroll") for (int k = 0; k < 2; ++k) \
;         acc[ai][bj][m][n] = __builtin_amdgcn_mfma_f32_16x16x32_bf16(Bt[n][k], At[m][k], acc[ai][bj][m][n], 0, 0, 0); __builtin_amdgcn_s_setprio(0); } while (0)
; #define PG8_WAIT_V(n) asm volatile("s_waitcnt vmcnt(" #n ")" ::: "memory")
; #define PG8_WAIT_L(n) asm volatile("s_waitcnt lgkmcnt(" #n ")" ::: "memory")
; #define PG8_BAR __builtin_amdgcn_s_barrier()
; #define PG8_SCHED __builtin_amdgcn_sched_barrier(0)
; template <class Epi, class Sched, bool ALIGN_EPI = false, bool SP2 = false>
; __device__ __forceinline__ void gemm_phase(PG8_LAS unsigned char* lds, const Gemm g, const Sched& S, const Epi& E) {
;     ...
;             PG8_WAIT_V(8); PG8_WAIT_L(0); PG8_BAR; PG8_MMA(1, 0, At, B0); PG8_MMA(1, 1, At, B1); PG8_BAR; PG8_SCHED;
;             PG8_LDB(B0, 1, 0); PG8_LDB(B1, 1, 1); PG8_SCHED; PG8_LDA(At, 1, 0); PG8_STAGE(PG8_SA(0, 1), a2 + hstepA, voffA);
;             PG8_WAIT_V(8); PG8_WAIT_L(0); PG8_BAR; PG8_MMA(0, 0, At, B0); PG8_MMA(0, 1, At, B1); PG8_BAR; PG8_SCHED;
	s_setprio 1
	v_mfma_f32_16x16x32_bf16 v[60:63], v[128:131], v[176:179], v[60:63]
	v_mfma_f32_16x16x32_bf16 v[56:59], v[136:139], v[176:179], v[56:59]
	v_mfma_f32_16x16x32_bf16 v[44:47], v[128:131], v[196:199], v[44:47]
	v_mfma_f32_16x16x32_bf16 v[40:43], v[136:139], v[196:199], v[40:43]
	v_mfma_f32_16x16x32_bf16 v[28:31], v[128:131], v[204:207], v[28:31]
	v_mfma_f32_16x16x32_bf16 v[24:27], v[136:139], v[204:207], v[24:27]
	v_mfma_f32_16x16x32_bf16 v[12:15], v[128:131], v[212:215], v[12:15]
	v_mfma_f32_16x16x32_bf16 v[8:11], v[136:139], v[212:215], v[8:11]
	v_mfma_f32_16x16x32_bf16 v[60:63], v[132:135], v[180:183], v[60:63]
	v_mfma_f32_16x16x32_bf16 v[56:59], v[140:143], v[180:183], v[56:59]
	v_mfma_f32_16x16x32_bf16 v[44:47], v[132:135], v[200:203], v[44:47]
	v_mfma_f32_16x16x32_bf16 v[40:43], v[140:143], v[200:203], v[40:43]
	v_mfma_f32_16x16x32_bf16 v[28:31], v[132:135], v[208:211], v[28:31]
	v_mfma_f32_16x16x32_bf16 v[24:27], v[140:143], v[208:211], v[24:27]
	v_mfma_f32_16x16x32_bf16 v[12:15], v[132:135], v[216:219], v[12:15]
	v_mfma_f32_16x16x32_bf16 v[8:11], v[140:143], v[216:219], v[8:11]
	s_setprio 0
	s_setprio 1
	v_mfma_f32_16x16x32_bf16 v[52:55], v[144:147], v[176:179], v[52:55]
	v_mfma_f32_16x16x32_bf16 v[48:51], v[168:171], v[176:179], v[48:51]
	v_mfma_f32_16x16x32_bf16 v[36:39], v[144:147], v[196:199], v[36:39]
	v_mfma_f32_16x16x32_bf16 v[32:35], v[168:171], v[196:199], v[32:35]
	v_mfma_f32_16x16x32_bf16 v[20:23], v[144:147], v[204:207], v[20:23]
	v_mfma_f32_16x16x32_bf16 v[16:19], v[168:171], v[204:207], v[16:19]
	v_mfma_f32_16x16x32_bf16 v[4:7], v[144:147], v[212:215], v[4:7]
	v_mfma_f32_16x16x32_bf16 v[0:3], v[168:171], v[212:215], v[0:3]
	v_mfma_f32_16x16x32_bf16 v[52:55], v[148:151], v[180:183], v[52:55]
	v_mfma_f32_16x16x32_bf16 v[48:51], v[172:175], v[180:183], v[48:51]
	v_mfma_f32_16x16x32_bf16 v[36:39], v[148:151], v[200:203], v[36:39]
	v_mfma_f32_16x16x32_bf16 v[32:35], v[172:175], v[200:203], v[32:35]
	v_mfma_f32_16x16x32_bf16 v[20:23], v[148:151], v[208:211], v[20:23]
	v_mfma_f32_16x16x32_bf16 v[16:19], v[172:175], v[208:211], v[16:19]
	v_mfma_f32_16x16x32_bf16 v[4:7], v[148:151], v[216:219], v[4:7]
	s_barrier
	v_mfma_f32_16x16x32_bf16 v[0:3], v[172:175], v[216:219], v[0:3]
	s_setprio 0
	s_add_i32 s58, 0, 0x18000
	s_add_i32 s59, 0, 0x1c000
	v_add_u32_e32 v140, s58, v189
	v_add_u32_e32 v172, s59, v189
	ds_read_b128 v[128:131], v140
	ds_read_b128 v[132:135], v140 offset:1024
	ds_read_b128 v[136:139], v140 offset:2048
	ds_read_b128 v[140:143], v140 offset:3072
	ds_read_b128 v[144:147], v172
	ds_read_b128 v[148:151], v172 offset:1024
	ds_read_b128 v[168:171], v172 offset:2048
	ds_read_b128 v[172:175], v172 offset:3072
	s_add_u32 s36, s36, 0x40000
	s_addc_u32 s37, s37, 0
	s_mov_b32 m0, s41
	v_lshl_add_u64 v[226:227], s[36:37], 0, v[152:153]
	ds_read_b128 v[176:179], v193 offset:32768
	ds_read_b128 v[180:183], v193 offset:33792
	ds_read_b128 v[196:199], v193 offset:34816
	ds_read_b128 v[200:203], v193 offset:35840
	ds_read_b128 v[204:207], v193 offset:36864
	ds_read_b128 v[208:211], v193 offset:37888
	ds_read_b128 v[212:215], v193 offset:38912
	ds_read_b128 v[216:219], v193 offset:39936
	global_load_lds_dwordx4 v[226:227], off
	v_lshl_add_u64 v[226:227], s[36:37], 0, v[156:157]
	s_mov_b32 m0, s42
	s_nop 0
	global_load_lds_dwordx4 v[226:227], off
	s_waitcnt vmcnt(8) lgkmcnt(0)
	s_barrier
	s_setprio 1
	v_mfma_f32_16x16x32_bf16 v[124:127], v[128:131], v[176:179], v[124:127]
	v_mfma_f32_16x16x32_bf16 v[120:123], v[136:139], v[176:179], v[120:123]
	v_mfma_f32_16x16x32_bf16 v[108:111], v[128:131], v[196:199], v[108:111]
	v_mfma_f32_16x16x32_bf16 v[104:107], v[136:139], v[196:199], v[104:107]
	v_mfma_f32_16x16x32_bf16 v[92:95], v[128:131], v[204:207], v[92:95]
	v_mfma_f32_16x16x32_bf16 v[88:91], v[136:139], v[204:207], v[88:91]
	v_mfma_f32_16x16x32_bf16 v[76:79], v[128:131], v[212:215], v[76:79]
	v_mfma_f32_16x16x32_bf16 v[72:75], v[136:139], v[212:215], v[72:75]
	v_mfma_f32_16x16x32_bf16 v[124:127], v[132:135], v[180:183], v[124:127]
	v_mfma_f32_16x16x32_bf16 v[120:123], v[140:143], v[180:183], v[120:123]
	v_mfma_f32_16x16x32_bf16 v[108:111], v[132:135], v[200:203], v[108:111]
	v_mfma_f32_16x16x32_bf16 v[104:107], v[140:143], v[200:203], v[104:107]
	v_mfma_f32_16x16x32_bf16 v[92:95], v[132:135], v[208:211], v[92:95]
	v_mfma_f32_16x16x32_bf16 v[88:91], v[140:143], v[208:211], v[88:91]
	v_mfma_f32_16x16x32_bf16 v[76:79], v[132:135], v[216:219], v[76:79]
	v_mfma_f32_16x16x32_bf16 v[72:75], v[140:143], v[216:219], v[72:75]
	s_setprio 0
	s_setprio 1
	v_mfma_f32_16x16x32_bf16 v[116:119], v[144:147], v[176:179], v[116:119]
	v_mfma_f32_16x16x32_bf16 v[112:115], v[168:171], v[176:179], v[112:115]
	v_mfma_f32_16x16x32_bf16 v[100:103], v[144:147], v[196:199], v[100:103]
	v_mfma_f32_16x16x32_bf16 v[96:99], v[168:171], v[196:199], v[96:99]
	v_mfma_f32_16x16x32_bf16 v[84:87], v[144:147], v[204:207], v[84:87]
	v_mfma_f32_16x16x32_bf16 v[80:83], v[168:171], v[204:207], v[80:83]
	v_mfma_f32_16x16x32_bf16 v[68:71], v[144:147], v[212:215], v[68:71]
	v_mfma_f32_16x16x32_bf16 v[64:67], v[168:171], v[212:215], v[64:67]
	v_mfma_f32_16x16x32_bf16 v[116:119], v[148:151], v[180:183], v[116:119]
	v_mfma_f32_16x16x32_bf16 v[112:115], v[172:175], v[180:183], v[112:115]
	v_mfma_f32_16x16x32_bf16 v[100:103], v[148:151], v[200:203], v[100:103]
	v_mfma_f32_16x16x32_bf16 v[96:99], v[172:175], v[200:203], v[96:99]
	v_mfma_f32_16x16x32_bf16 v[84:87], v[148:151], v[208:211], v[84:87]
	v_mfma_f32_16x16x32_bf16 v[80:83], v[172:175], v[208:211], v[80:83]
	v_mfma_f32_16x16x32_bf16 v[68:71], v[148:151], v[216:219], v[68:71]
	s_barrier
; #define PG8_STAGE(bufoff, gbase, voff) do { _Pragma("unroll") for (int _i = 0; _i < 2; ++_i) \
;         __builtin_amdgcn_global_load_lds((const unsigned*)((const char*)(gbase) + (voff)[_i]), (PG8_LAS unsigned*)(lds + (bufoff) + ldsw + _i * 8192), 16, 0, 0); } while (0)
; #define PG8_LDA(dst, b, h) do { _Pragma("unroll") for (int m = 0; m < 4; ++m) _Pragma("unroll") for (int k = 0; k < 2; ++k) dst[m][k] = *(const PG8_LAS bf16x8*)(lds + PG8_SA(b, h) + aoff + m * 2048 + k * 1024); } while (0)
; #define PG8_MMA(ai, bj, At, Bt) do { __builtin_amdgcn_s_setprio(1); _Pragma("unroll") for (int m = 0; m < 4; ++m) _Pragma("unroll") for (int n = 0; n < 2; ++n) _Pragma("unroll") for (int k = 0; k < 2; ++k) \
;         acc[ai][bj][m][n] = __builtin_amdgcn_mfma_f32_16x16x32_bf16(Bt[n][k], At[m][k], acc[ai][bj][m][n], 0, 0, 0); __builtin_amdgcn_s_setprio(0); } while (0)
; #define PG8_WAIT_V(n) asm volatile("s_waitcnt vmcnt(" #n ")" ::: "memory")
; #define PG8_WAIT_L(n) asm volatile("s_waitcnt lgkmcnt(" #n ")" ::: "memory")
; #define PG8_BAR __builtin_amdgcn_s_barrier()
; #define PG8_SCHED __builtin_amdgcn_sched_barrier(0)
; template <class Epi, class Sched, bool ALIGN_EPI = false, bool SP2 = false>
; __device__ __forceinline__ void gemm_phase(PG8_LAS unsigned char* lds, const Gemm g, const Sched& S, const Epi& E) {
;     ...
;         for (int t = 0; t < nt; t += 2) {
;             const bool last = (t == nt - 2);
;     ...
;             PG8_LDA(At, 1, 1); PG8_STAGE(PG8_SB(1, 0), b3, voffB); PG8_STAGE(PG8_SB(1, 1), b3 + hstepB, voffB); PG8_STAGE(PG8_SA(1, 0), a3, voffA);
;             PG8_WAIT_V(8); PG8_WAIT_L(0); PG8_BAR; PG8_MMA(1, 0, At, B0); PG8_MMA(1, 1, At, B1); PG8_BAR; PG8_SCHED;
	v_mfma_f32_16x16x32_bf16 v[64:67], v[172:175], v[216:219], v[64:67]
	s_setprio 0
	s_add_i32 s36, s58, s39
	v_lshl_add_u64 v[184:185], v[184:185], 0, s[14:15]
	s_mov_b32 m0, s36
	ds_read_b128 v[176:179], v193 offset:49152
	ds_read_b128 v[180:183], v193 offset:50176
	ds_read_b128 v[196:199], v193 offset:51200
	ds_read_b128 v[200:203], v193 offset:52224
	ds_read_b128 v[204:207], v193 offset:53248
	ds_read_b128 v[208:211], v193 offset:54272
	ds_read_b128 v[212:215], v193 offset:55296
	ds_read_b128 v[216:219], v193 offset:56320
	global_load_lds_dwordx4 v[184:185], off
	s_add_i32 m0, s36, 0x2000
	s_add_u32 s34, s34, 0x40080
	v_lshl_add_u64 v[184:185], v[220:221], 0, s[14:15]
	s_addc_u32 s35, s35, 0
	s_add_i32 s36, s59, s39
	global_load_lds_dwordx4 v[184:185], off
	v_lshl_add_u64 v[184:185], s[34:35], 0, v[154:155]
	s_mov_b32 m0, s36
	s_nop 0
	global_load_lds_dwordx4 v[184:185], off
	v_lshl_add_u64 v[184:185], s[34:35], 0, v[158:159]
	s_add_i32 m0, s36, 0x2000
	s_nop 0
	global_load_lds_dwordx4 v[184:185], off
	v_lshl_add_u64 v[184:185], v[222:223], 0, s[14:15]
	s_mov_b32 m0, s44
	s_nop 0
	global_load_lds_dwordx4 v[184:185], off
	v_lshl_add_u64 v[184:185], v[224:225], 0, s[14:15]
	s_mov_b32 m0, s45
	s_nop 0
	global_load_lds_dwordx4 v[184:185], off
	s_waitcnt vmcnt(8) lgkmcnt(0)
	s_barrier
	s_setprio 1
	v_mfma_f32_16x16x32_bf16 v[60:63], v[128:131], v[176:179], v[60:63]
	v_mfma_f32_16x16x32_bf16 v[56:59], v[136:139], v[176:179], v[56:59]
	v_mfma_f32_16x16x32_bf16 v[44:47], v[128:131], v[196:199], v[44:47]
	v_mfma_f32_16x16x32_bf16 v[40:43], v[136:139], v[196:199], v[40:43]
	v_mfma_f32_16x16x32_bf16 v[28:31], v[128:131], v[204:207], v[28:31]
	v_mfma_f32_16x16x32_bf16 v[24:27], v[136:139], v[204:207], v[24:27]
	v_mfma_f32_16x16x32_bf16 v[12:15], v[128:131], v[212:215], v[12:15]
	v_mfma_f32_16x16x32_bf16 v[8:11], v[136:139], v[212:215], v[8:11]
	v_mfma_f32_16x16x32_bf16 v[60:63], v[132:135], v[180:183], v[60:63]
	v_mfma_f32_16x16x32_bf16 v[56:59], v[140:143], v[180:183], v[56:59]
	v_mfma_f32_16x16x32_bf16 v[44:47], v[132:135], v[200:203], v[44:47]
	v_mfma_f32_16x16x32_bf16 v[40:43], v[140:143], v[200:203], v[40:43]
	v_mfma_f32_16x16x32_bf16 v[28:31], v[132:135], v[208:211], v[28:31]
	v_mfma_f32_16x16x32_bf16 v[24:27], v[140:143], v[208:211], v[24:27]
	v_mfma_f32_16x16x32_bf16 v[12:15], v[132:135], v[216:219], v[12:15]
	v_mfma_f32_16x16x32_bf16 v[8:11], v[140:143], v[216:219], v[8:11]
	s_setprio 0
	s_setprio 1
	v_mfma_f32_16x16x32_bf16 v[52:55], v[144:147], v[176:179], v[52:55]
	v_mfma_f32_16x16x32_bf16 v[48:51], v[168:171], v[176:179], v[48:51]
	v_mfma_f32_16x16x32_bf16 v[36:39], v[144:147], v[196:199], v[36:39]
	v_mfma_f32_16x16x32_bf16 v[32:35], v[168:171], v[196:199], v[32:35]
	v_mfma_f32_16x16x32_bf16 v[20:23], v[144:147], v[204:207], v[20:23]
	v_mfma_f32_16x16x32_bf16 v[16:19], v[168:171], v[204:207], v[16:19]
	v_mfma_f32_16x16x32_bf16 v[4:7], v[144:147], v[212:215], v[4:7]
	v_mfma_f32_16x16x32_bf16 v[0:3], v[168:171], v[212:215], v[0:3]
	v_mfma_f32_16x16x32_bf16 v[52:55], v[148:151], v[180:183], v[52:55]
	v_mfma_f32_16x16x32_bf16 v[48:51], v[172:175], v[180:183], v[48:51]
	v_mfma_f32_16x16x32_bf16 v[36:39], v[148:151], v[200:203], v[36:39]
	v_mfma_f32_16x16x32_bf16 v[32:35], v[172:175], v[200:203], v[32:35]
	v_mfma_f32_16x16x32_bf16 v[20:23], v[148:151], v[208:211], v[20:23]
	v_mfma_f32_16x16x32_bf16 v[16:19], v[172:175], v[208:211], v[16:19]
	v_mfma_f32_16x16x32_bf16 v[4:7], v[148:151], v[216:219], v[4:7]
	s_barrier
	v_mfma_f32_16x16x32_bf16 v[0:3], v[172:175], v[216:219], v[0:3]
	s_setprio 0
	s_add_i32 s74, s74, 2
	s_add_u32 s30, s30, 0x100
	s_addc_u32 s31, s31, 0
	s_add_u32 s69, s69, 0x100
	s_addc_u32 s73, s73, 0
	s_cmp_gt_u32 s74, 13
	s_cbranch_scc0 .LBB0_971
	s_and_b64 vcc, exec, s[16:17]
	s_cbranch_vccz .LBB0_974
	s_barrier

; #define PG8_STAGE(bufoff, gbase, voff) do { _Pragma("unroll") for (int _i = 0; _i < 2; ++_i) \
;         __builtin_amdgcn_global_load_lds((const unsigned*)((const char*)(gbase) + (voff)[_i]), (PG8_LAS unsigned*)(lds + (bufoff) + ldsw + _i * 8192), 16, 0, 0); } while (0)
; #define PG8_LDA(dst, b, h) do { _Pragma("unroll") for (int m = 0; m < 4; ++m) _Pragma("unroll") for (int k = 0; k < 2; ++k) dst[m][k] = *(const PG8_LAS bf16x8*)(lds + PG8_SA(b, h) + aoff + m * 2048 + k * 1024); } while (0)
; #define PG8_LDB(dst, b, h) do { _Pragma("unroll") for (int n = 0; n < 2; ++n) _Pragma("unroll") for (int k = 0; k < 2; ++k) dst[n][k] = *(const PG8_LAS bf16x8*)(lds + PG8_SB(b, h) + boff + n * 2048 + k * 1024); } while (0)
; #define PG8_MMA(ai, bj, At, Bt) do { __builtin_amdgcn_s_setprio(1); _Pragma("unroll") for (int m = 0; m < 4; ++m) _Pragma("unroll") for (int n = 0; n < 2; ++n) _Pragma("unroll") for (int k = 0; k < 2; ++k) \
;         acc[ai][bj][m][n] = __builtin_amdgcn_mfma_f32_16x16x32_bf16(Bt[n][k], At[m][k], acc[ai][bj][m][n], 0, 0, 0); __builtin_amdgcn_s_setprio(0); } while (0)
; #define PG8_WAIT_V(n) asm volatile("s_waitcnt vmcnt(" #n ")" ::: "memory")
; #define PG8_BAR __builtin_amdgcn_s_barrier()
; template <class Epi, class Sched, bool ALIGN_EPI = false, bool SP2 = false>
; __device__ __forceinline__ void gemm_phase(PG8_LAS unsigned char* lds, const Gemm g, const Sched& S, const Epi& E) {
;     ...
;         for (int t = 0; t < nt; t += 2) {
;             const bool last = (t == nt - 2);
;             const char* a1 = cA + (size_t)(t + 1) * kstep;
;             const char* a2 = last ? nA : cA + (size_t)(t + 2) * kstep; const char* b2 = last ? nB : cB + (size_t)(t + 2) * kstep;
;             const char* a3 = a2 + kstep; const char* b3 = b2 + kstep;
;             if (last && has_next) S.a_ready(nxt);
;             if constexpr (SP2) {
;             PG8_LDB(B0, 0, 0); PG8_LDB(B1, 0, 1); PG8_SCHED; PG8_LDA(At, 0, 0); PG8_STAGE(PG8_SA(1, 1), a1 + hstepA, voffA);
;             PG8_WAIT_V(8); PG8_WAIT_L(0); PG8_BAR; PG8_MMA(0, 0, At, B0); PG8_MMA(0, 1, At, B1); PG8_BAR; PG8_SCHED;
;             PG8_LDA(At, 0, 1); PG8_STAGE(PG8_SB(0, 0), b2, voffB); PG8_STAGE(PG8_SB(0, 1), b2 + hstepB, voffB); PG8_STAGE(PG8_SA(0, 0), a2, voffA);
;             PG8_WAIT_V(8); PG8_WAIT_L(0); PG8_BAR; PG8_MMA(1, 0, At, B0); PG8_MMA(1, 1, At, B1); PG8_BAR; PG8_SCHED;
.LBB0_1055:
	ds_read_b128 v[144:147], v153
	ds_read_b128 v[158:161], v153 offset:1024
	ds_read_b128 v[162:165], v153 offset:2048
	ds_read_b128 v[166:169], v153 offset:3072
	ds_read_b128 v[170:173], v154
	ds_read_b128 v[174:177], v154 offset:1024
	ds_read_b128 v[178:181], v154 offset:2048
	ds_read_b128 v[182:185], v154 offset:3072
	s_add_u32 s28, s26, 0xfffc0080
	s_addc_u32 s29, s27, -1
	s_cmp_eq_u32 s69, 12
	s_cselect_b32 s31, s19, s29
	s_cselect_b32 s30, s49, s28
	s_cselect_b32 s29, s17, s68
	s_cselect_b32 s28, s66, s67
	v_lshl_add_u64 v[148:149], s[26:27], 0, v[136:137]
	s_add_i32 m0, s25, 0xc000
	ds_read_b128 v[188:191], v155
	ds_read_b128 v[192:195], v155 offset:1024
	ds_read_b128 v[196:199], v155 offset:2048
	ds_read_b128 v[200:203], v155 offset:3072
	ds_read_b128 v[204:207], v155 offset:4096
	ds_read_b128 v[208:211], v155 offset:5120
	ds_read_b128 v[212:215], v155 offset:6144
	ds_read_b128 v[216:219], v155 offset:7168
	global_load_lds_dwordx4 v[148:149], off
	v_lshl_add_u64 v[148:149], s[26:27], 0, v[138:139]
	s_add_i32 m0, s25, 0xe000
	s_nop 0
	global_load_lds_dwordx4 v[148:149], off
	s_waitcnt vmcnt(8) lgkmcnt(0)
	s_barrier
	s_setprio 1
	v_mfma_f32_16x16x32_bf16 v[116:119], v[144:147], v[188:191], v[116:119]
	v_mfma_f32_16x16x32_bf16 v[112:115], v[162:165], v[188:191], v[112:115]
	v_mfma_f32_16x16x32_bf16 v[108:111], v[144:147], v[196:199], v[108:111]
	v_mfma_f32_16x16x32_bf16 v[100:103], v[162:165], v[196:199], v[100:103]
	v_mfma_f32_16x16x32_bf16 v[92:95], v[144:147], v[204:207], v[92:95]
	v_mfma_f32_16x16x32_bf16 v[84:87], v[162:165], v[204:207], v[84:87]
	v_mfma_f32_16x16x32_bf16 v[76:79], v[144:147], v[212:215], v[76:79]
	v_mfma_f32_16x16x32_bf16 v[68:71], v[162:165], v[212:215], v[68:71]
	v_mfma_f32_16x16x32_bf16 v[116:119], v[158:161], v[192:195], v[116:119]
	v_mfma_f32_16x16x32_bf16 v[112:115], v[166:169], v[192:195], v[112:115]
	v_mfma_f32_16x16x32_bf16 v[108:111], v[158:161], v[200:203], v[108:111]
	v_mfma_f32_16x16x32_bf16 v[100:103], v[166:169], v[200:203], v[100:103]
	v_mfma_f32_16x16x32_bf16 v[92:95], v[158:161], v[208:211], v[92:95]
	v_mfma_f32_16x16x32_bf16 v[84:87], v[166:169], v[208:211], v[84:87]
	v_mfma_f32_16x16x32_bf16 v[76:79], v[158:161], v[216:219], v[76:79]
	v_mfma_f32_16x16x32_bf16 v[68:71], v[166:169], v[216:219], v[68:71]
	s_setprio 0
	s_setprio 1
	v_mfma_f32_16x16x32_bf16 v[124:127], v[170:173], v[188:191], v[124:127]
	v_mfma_f32_16x16x32_bf16 v[120:123], v[178:181], v[188:191], v[120:123]
	v_mfma_f32_16x16x32_bf16 v[104:107], v[170:173], v[196:199], v[104:107]
	v_mfma_f32_16x16x32_bf16 v[96:99], v[178:181], v[196:199], v[96:99]
	v_mfma_f32_16x16x32_bf16 v[88:91], v[170:173], v[204:207], v[88:91]
	v_mfma_f32_16x16x32_bf16 v[80:83], v[178:181], v[204:207], v[80:83]
	v_mfma_f32_16x16x32_bf16 v[72:75], v[170:173], v[212:215], v[72:75]
	v_mfma_f32_16x16x32_bf16 v[64:67], v[178:181], v[212:215], v[64:67]
	v_mfma_f32_16x16x32_bf16 v[124:127], v[174:177], v[192:195], v[124:127]
	v_mfma_f32_16x16x32_bf16 v[120:123], v[182:185], v[192:195], v[120:123]
	v_mfma_f32_16x16x32_bf16 v[104:107], v[174:177], v[200:203], v[104:107]
	v_mfma_f32_16x16x32_bf16 v[96:99], v[182:185], v[200:203], v[96:99]
	v_mfma_f32_16x16x32_bf16 v[88:91], v[174:177], v[208:211], v[88:91]
	v_mfma_f32_16x16x32_bf16 v[80:83], v[182:185], v[208:211], v[80:83]
	v_mfma_f32_16x16x32_bf16 v[72:75], v[174:177], v[216:219], v[72:75]
	s_barrier
	v_mfma_f32_16x16x32_bf16 v[64:67], v[182:185], v[216:219], v[64:67]
	s_setprio 0
	s_add_i32 s58, s45, s35
	v_lshl_add_u64 v[148:149], s[28:29], 0, v[132:133]
	s_mov_b32 m0, s58
	ds_read_b128 v[188:191], v155 offset:16384
	ds_read_b128 v[192:195], v155 offset:17408
	ds_read_b128 v[196:199], v155 offset:18432
	ds_read_b128 v[200:203], v155 offset:19456
	ds_read_b128 v[204:207], v155 offset:20480
	ds_read_b128 v[208:211], v155 offset:21504
	ds_read_b128 v[212:215], v155 offset:22528
	ds_read_b128 v[216:219], v155 offset:23552
	global_load_lds_dwordx4 v[148:149], off
	s_add_i32 m0, s58, 0x2000
	s_add_u32 s58, s28, 0x40000
	v_lshl_add_u64 v[220:221], s[28:29], 0, v[128:129]
	s_addc_u32 s59, s29, 0
	s_add_i32 s73, s46, s35
	global_load_lds_dwordx4 v[220:221], off
	v_lshl_add_u64 v[222:223], s[58:59], 0, v[132:133]
	s_mov_b32 m0, s73
	v_lshl_add_u64 v[224:225], s[30:31], 0, v[130:131]
	global_load_lds_dwordx4 v[222:223], off
	v_lshl_add_u64 v[222:223], s[58:59], 0, v[128:129]
	s_add_i32 m0, s73, 0x2000
	s_nop 0
	global_load_lds_dwordx4 v[222:223], off
	v_lshl_add_u64 v[222:223], s[30:31], 0, v[134:135]
	s_mov_b32 m0, s25
	s_nop 0
	global_load_lds_dwordx4 v[222:223], off
	s_mov_b32 m0, s38
	s_nop 0
	global_load_lds_dwordx4 v[224:225], off
	s_waitcnt vmcnt(8) lgkmcnt(0)
	s_barrier
; #define PG8_STAGE(bufoff, gbase, voff) do { _Pragma("unroll") for (int _i = 0; _i < 2; ++_i) \
;         __builtin_amdgcn_global_load_lds((const unsigned*)((const char*)(gbase) + (voff)[_i]), (PG8_LAS unsigned*)(lds + (bufoff) + ldsw + _i * 8192), 16, 0, 0); } while (0)
; #define PG8_LDA(dst, b, h) do { _Pragma("unroll") for (int m = 0; m < 4; ++m) _Pragma("unroll") for (int k = 0; k < 2; ++k) dst[m][k] = *(const PG8_LAS bf16x8*)(lds + PG8_SA(b, h) + aoff + m * 2048 + k * 1024); } while (0)
; #define PG8_LDB(dst, b, h) do { _Pragma("unroll") for (int n = 0; n < 2; ++n) _Pragma("unroll") for (int k = 0; k < 2; ++k) dst[n][k] = *(const PG8_LAS bf16x8*)(lds + PG8_SB(b, h) + boff + n * 2048 + k * 1024); } while (0)
; #define PG8_MMA(ai, bj, At, Bt) do { __builtin_amdgcn_s_setprio(1); _Pragma("unroll") for (int m = 0; m < 4; ++m) _Pragma("unroll") for (int n = 0; n < 2; ++n) _Pragma("unroll") for (int k = 0; k < 2; ++k) \
;         acc[ai][bj][m][n] = __builtin_amdgcn_mfma_f32_16x16x32_bf16(Bt[n][k], At[m][k], acc[ai][bj][m][n], 0, 0, 0); __builtin_amdgcn_s_setprio(0); } while (0)
; #define PG8_WAIT_V(n) asm volatile("s_waitcnt vmcnt(" #n ")" ::: "memory")
; #define PG8_WAIT_L(n) asm volatile("s_waitcnt lgkmcnt(" #n ")" ::: "memory")
; #define PG8_BAR __builtin_amdgcn_s_barrier()
; #define PG8_SCHED __builtin_amdgcn_sched_barrier(0)
; template <class Epi, class Sched, bool ALIGN_EPI = false, bool SP2 = false>
; __device__ __forceinline__ void gemm_phase(PG8_LAS unsigned char* lds, const Gemm g, const Sched& S, const Epi& E) {
;     ...
;             PG8_WAIT_V(8); PG8_WAIT_L(0); PG8_BAR; PG8_MMA(1, 0, At, B0); PG8_MMA(1, 1, At, B1); PG8_BAR; PG8_SCHED;
;             PG8_LDB(B0, 1, 0); PG8_LDB(B1, 1, 1); PG8_SCHED; PG8_LDA(At, 1, 0); PG8_STAGE(PG8_SA(0, 1), a2 + hstepA, voffA);
;             PG8_WAIT_V(8); PG8_WAIT_L(0); PG8_BAR; PG8_MMA(0, 0, At, B0); PG8_MMA(0, 1, At, B1); PG8_BAR; PG8_SCHED;
	s_setprio 1
	v_mfma_f32_16x16x32_bf16 v[60:63], v[144:147], v[188:191], v[60:63]
	v_mfma_f32_16x16x32_bf16 v[52:55], v[162:165], v[188:191], v[52:55]
	v_mfma_f32_16x16x32_bf16 v[44:47], v[144:147], v[196:199], v[44:47]
	v_mfma_f32_16x16x32_bf16 v[36:39], v[162:165], v[196:199], v[36:39]
	v_mfma_f32_16x16x32_bf16 v[28:31], v[144:147], v[204:207], v[28:31]
	v_mfma_f32_16x16x32_bf16 v[20:23], v[162:165], v[204:207], v[20:23]
	v_mfma_f32_16x16x32_bf16 v[12:15], v[144:147], v[212:215], v[12:15]
	v_mfma_f32_16x16x32_bf16 v[4:7], v[162:165], v[212:215], v[4:7]
	v_mfma_f32_16x16x32_bf16 v[60:63], v[158:161], v[192:195], v[60:63]
	v_mfma_f32_16x16x32_bf16 v[52:55], v[166:169], v[192:195], v[52:55]
	v_mfma_f32_16x16x32_bf16 v[44:47], v[158:161], v[200:203], v[44:47]
	v_mfma_f32_16x16x32_bf16 v[36:39], v[166:169], v[200:203], v[36:39]
	v_mfma_f32_16x16x32_bf16 v[28:31], v[158:161], v[208:211], v[28:31]
	v_mfma_f32_16x16x32_bf16 v[20:23], v[166:169], v[208:211], v[20:23]
	v_mfma_f32_16x16x32_bf16 v[12:15], v[158:161], v[216:219], v[12:15]
	v_mfma_f32_16x16x32_bf16 v[4:7], v[166:169], v[216:219], v[4:7]
	s_setprio 0
	s_setprio 1
	v_mfma_f32_16x16x32_bf16 v[56:59], v[170:173], v[188:191], v[56:59]
	v_mfma_f32_16x16x32_bf16 v[48:51], v[178:181], v[188:191], v[48:51]
	v_mfma_f32_16x16x32_bf16 v[40:43], v[170:173], v[196:199], v[40:43]
	v_mfma_f32_16x16x32_bf16 v[32:35], v[178:181], v[196:199], v[32:35]
	v_mfma_f32_16x16x32_bf16 v[24:27], v[170:173], v[204:207], v[24:27]
	v_mfma_f32_16x16x32_bf16 v[16:19], v[178:181], v[204:207], v[16:19]
	v_mfma_f32_16x16x32_bf16 v[8:11], v[170:173], v[212:215], v[8:11]
	v_mfma_f32_16x16x32_bf16 v[0:3], v[178:181], v[212:215], v[0:3]
	v_mfma_f32_16x16x32_bf16 v[56:59], v[174:177], v[192:195], v[56:59]
	v_mfma_f32_16x16x32_bf16 v[48:51], v[182:185], v[192:195], v[48:51]
	v_mfma_f32_16x16x32_bf16 v[40:43], v[174:177], v[200:203], v[40:43]
	v_mfma_f32_16x16x32_bf16 v[32:35], v[182:185], v[200:203], v[32:35]
	v_mfma_f32_16x16x32_bf16 v[24:27], v[174:177], v[208:211], v[24:27]
	v_mfma_f32_16x16x32_bf16 v[16:19], v[182:185], v[208:211], v[16:19]
	v_mfma_f32_16x16x32_bf16 v[8:11], v[174:177], v[216:219], v[8:11]
	s_barrier
	v_mfma_f32_16x16x32_bf16 v[0:3], v[182:185], v[216:219], v[0:3]
	s_setprio 0
	s_add_i32 s58, 0, 0x18000
	v_add_u32_e32 v157, s58, v151
	s_add_i32 s59, 0, 0x1c000
	ds_read_b128 v[144:147], v157
	ds_read_b128 v[158:161], v157 offset:1024
	ds_read_b128 v[162:165], v157 offset:2048
	ds_read_b128 v[166:169], v157 offset:3072
	v_add_u32_e32 v157, s59, v151
	ds_read_b128 v[170:173], v157
	ds_read_b128 v[174:177], v157 offset:1024
	ds_read_b128 v[178:181], v157 offset:2048
	ds_read_b128 v[182:185], v157 offset:3072
	s_add_u32 s30, s30, 0x40000
	s_addc_u32 s31, s31, 0
	s_mov_b32 m0, s39
	v_lshl_add_u64 v[226:227], s[30:31], 0, v[134:135]
	ds_read_b128 v[188:191], v155 offset:32768
	ds_read_b128 v[192:195], v155 offset:33792
	ds_read_b128 v[196:199], v155 offset:34816
	ds_read_b128 v[200:203], v155 offset:35840
	ds_read_b128 v[204:207], v155 offset:36864
	ds_read_b128 v[208:211], v155 offset:37888
	ds_read_b128 v[212:215], v155 offset:38912
	ds_read_b128 v[216:219], v155 offset:39936
	global_load_lds_dwordx4 v[226:227], off
	v_lshl_add_u64 v[226:227], s[30:31], 0, v[130:131]
	s_mov_b32 m0, s40
	s_nop 0
	global_load_lds_dwordx4 v[226:227], off
	s_waitcnt vmcnt(8) lgkmcnt(0)
	s_barrier
	s_setprio 1
	v_mfma_f32_16x16x32_bf16 v[116:119], v[144:147], v[188:191], v[116:119]
	v_mfma_f32_16x16x32_bf16 v[112:115], v[162:165], v[188:191], v[112:115]
	v_mfma_f32_16x16x32_bf16 v[108:111], v[144:147], v[196:199], v[108:111]
	v_mfma_f32_16x16x32_bf16 v[100:103], v[162:165], v[196:199], v[100:103]
	v_mfma_f32_16x16x32_bf16 v[92:95], v[144:147], v[204:207], v[92:95]
	v_mfma_f32_16x16x32_bf16 v[84:87], v[162:165], v[204:207], v[84:87]
	v_mfma_f32_16x16x32_bf16 v[76:79], v[144:147], v[212:215], v[76:79]
	v_mfma_f32_16x16x32_bf16 v[68:71], v[162:165], v[212:215], v[68:71]
	v_mfma_f32_16x16x32_bf16 v[116:119], v[158:161], v[192:195], v[116:119]
	v_mfma_f32_16x16x32_bf16 v[112:115], v[166:169], v[192:195], v[112:115]
	v_mfma_f32_16x16x32_bf16 v[108:111], v[158:161], v[200:203], v[108:111]
	v_mfma_f32_16x16x32_bf16 v[100:103], v[166:169], v[200:203], v[100:103]
	v_mfma_f32_16x16x32_bf16 v[92:95], v[158:161], v[208:211], v[92:95]
	v_mfma_f32_16x16x32_bf16 v[84:87], v[166:169], v[208:211], v[84:87]
	v_mfma_f32_16x16x32_bf16 v[76:79], v[158:161], v[216:219], v[76:79]
	v_mfma_f32_16x16x32_bf16 v[68:71], v[166:169], v[216:219], v[68:71]
	s_setprio 0
	s_setprio 1
	v_mfma_f32_16x16x32_bf16 v[124:127], v[170:173], v[188:191], v[124:127]
	v_mfma_f32_16x16x32_bf16 v[120:123], v[178:181], v[188:191], v[120:123]
	v_mfma_f32_16x16x32_bf16 v[104:107], v[170:173], v[196:199], v[104:107]
	v_mfma_f32_16x16x32_bf16 v[96:99], v[178:181], v[196:199], v[96:99]
	v_mfma_f32_16x16x32_bf16 v[88:91], v[170:173], v[204:207], v[88:91]
	v_mfma_f32_16x16x32_bf16 v[80:83], v[178:181], v[204:207], v[80:83]
	v_mfma_f32_16x16x32_bf16 v[72:75], v[170:173], v[212:215], v[72:75]
	v_mfma_f32_16x16x32_bf16 v[64:67], v[178:181], v[212:215], v[64:67]
	v_mfma_f32_16x16x32_bf16 v[124:127], v[174:177], v[192:195], v[124:127]
	v_mfma_f32_16x16x32_bf16 v[120:123], v[182:185], v[192:195], v[120:123]
	v_mfma_f32_16x16x32_bf16 v[104:107], v[174:177], v[200:203], v[104:107]
	v_mfma_f32_16x16x32_bf16 v[96:99], v[182:185], v[200:203], v[96:99]
	v_mfma_f32_16x16x32_bf16 v[88:91], v[174:177], v[208:211], v[88:91]
	v_mfma_f32_16x16x32_bf16 v[80:83], v[182:185], v[208:211], v[80:83]
	v_mfma_f32_16x16x32_bf16 v[72:75], v[174:177], v[216:219], v[72:75]
	s_barrier
; #define PG8_STAGE(bufoff, gbase, voff) do { _Pragma("unroll") for (int _i = 0; _i < 2; ++_i) \
;         __builtin_amdgcn_global_load_lds((const unsigned*)((const char*)(gbase) + (voff)[_i]), (PG8_LAS unsigned*)(lds + (bufoff) + ldsw + _i * 8192), 16, 0, 0); } while (0)
; #define PG8_LDA(dst, b, h) do { _Pragma("unroll") for (int m = 0; m < 4; ++m) _Pragma("unroll") for (int k = 0; k < 2; ++k) dst[m][k] = *(const PG8_LAS bf16x8*)(lds + PG8_SA(b, h) + aoff + m * 2048 + k * 1024); } while (0)
; #define PG8_MMA(ai, bj, At, Bt) do { __builtin_amdgcn_s_setprio(1); _Pragma("unroll") for (int m = 0; m < 4; ++m) _Pragma("unroll") for (int n = 0; n < 2; ++n) _Pragma("unroll") for (int k = 0; k < 2; ++k) \
;         acc[ai][bj][m][n] = __builtin_amdgcn_mfma_f32_16x16x32_bf16(Bt[n][k], At[m][k], acc[ai][bj][m][n], 0, 0, 0); __builtin_amdgcn_s_setprio(0); } while (0)
; #define PG8_WAIT_V(n) asm volatile("s_waitcnt vmcnt(" #n ")" ::: "memory")
; #define PG8_WAIT_L(n) asm volatile("s_waitcnt lgkmcnt(" #n ")" ::: "memory")
; #define PG8_BAR __builtin_amdgcn_s_barrier()
; #define PG8_SCHED __builtin_amdgcn_sched_barrier(0)
; template <class Epi, class Sched, bool ALIGN_EPI = false, bool SP2 = false>
; __device__ __forceinline__ void gemm_phase(PG8_LAS unsigned char* lds, const Gemm g, const Sched& S, const Epi& E) {
;     ...
;         for (int t = 0; t < nt; t += 2) {
;             const bool last = (t == nt - 2);
;     ...
;             PG8_LDA(At, 1, 1); PG8_STAGE(PG8_SB(1, 0), b3, voffB); PG8_STAGE(PG8_SB(1, 1), b3 + hstepB, voffB); PG8_STAGE(PG8_SA(1, 0), a3, voffA);
;             PG8_WAIT_V(8); PG8_WAIT_L(0); PG8_BAR; PG8_MMA(1, 0, At, B0); PG8_MMA(1, 1, At, B1); PG8_BAR; PG8_SCHED;
	v_mfma_f32_16x16x32_bf16 v[64:67], v[182:185], v[216:219], v[64:67]
	s_setprio 0
	s_add_i32 s30, s58, s35
	v_lshl_add_u64 v[148:149], v[148:149], 0, s[12:13]
	s_mov_b32 m0, s30
	ds_read_b128 v[188:191], v155 offset:49152
	ds_read_b128 v[192:195], v155 offset:50176
	ds_read_b128 v[196:199], v155 offset:51200
	ds_read_b128 v[200:203], v155 offset:52224
	ds_read_b128 v[204:207], v155 offset:53248
	ds_read_b128 v[208:211], v155 offset:54272
	ds_read_b128 v[212:215], v155 offset:55296
	ds_read_b128 v[216:219], v155 offset:56320
	global_load_lds_dwordx4 v[148:149], off
	s_add_i32 m0, s30, 0x2000
	s_add_u32 s28, s28, 0x40080
	v_lshl_add_u64 v[148:149], v[220:221], 0, s[12:13]
	s_addc_u32 s29, s29, 0
	s_add_i32 s30, s59, s35
	global_load_lds_dwordx4 v[148:149], off
	v_lshl_add_u64 v[148:149], s[28:29], 0, v[132:133]
	s_mov_b32 m0, s30
	s_nop 0
	global_load_lds_dwordx4 v[148:149], off
	v_lshl_add_u64 v[148:149], s[28:29], 0, v[128:129]
	s_add_i32 m0, s30, 0x2000
	s_nop 0
	global_load_lds_dwordx4 v[148:149], off
	v_lshl_add_u64 v[148:149], v[222:223], 0, s[12:13]
	s_mov_b32 m0, s42
	s_nop 0
	global_load_lds_dwordx4 v[148:149], off
	v_lshl_add_u64 v[148:149], v[224:225], 0, s[12:13]
	s_mov_b32 m0, s43
	s_nop 0
	global_load_lds_dwordx4 v[148:149], off
	s_waitcnt vmcnt(8) lgkmcnt(0)
	s_barrier
	s_setprio 1
	v_mfma_f32_16x16x32_bf16 v[60:63], v[144:147], v[188:191], v[60:63]
	v_mfma_f32_16x16x32_bf16 v[52:55], v[162:165], v[188:191], v[52:55]
	v_mfma_f32_16x16x32_bf16 v[44:47], v[144:147], v[196:199], v[44:47]
	v_mfma_f32_16x16x32_bf16 v[36:39], v[162:165], v[196:199], v[36:39]
	v_mfma_f32_16x16x32_bf16 v[28:31], v[144:147], v[204:207], v[28:31]
	v_mfma_f32_16x16x32_bf16 v[20:23], v[162:165], v[204:207], v[20:23]
	v_mfma_f32_16x16x32_bf16 v[12:15], v[144:147], v[212:215], v[12:15]
	v_mfma_f32_16x16x32_bf16 v[4:7], v[162:165], v[212:215], v[4:7]
	v_mfma_f32_16x16x32_bf16 v[60:63], v[158:161], v[192:195], v[60:63]
	v_mfma_f32_16x16x32_bf16 v[52:55], v[166:169], v[192:195], v[52:55]
	v_mfma_f32_16x16x32_bf16 v[44:47], v[158:161], v[200:203], v[44:47]
	v_mfma_f32_16x16x32_bf16 v[36:39], v[166:169], v[200:203], v[36:39]
	v_mfma_f32_16x16x32_bf16 v[28:31], v[158:161], v[208:211], v[28:31]
	v_mfma_f32_16x16x32_bf16 v[20:23], v[166:169], v[208:211], v[20:23]
	v_mfma_f32_16x16x32_bf16 v[12:15], v[158:161], v[216:219], v[12:15]
	v_mfma_f32_16x16x32_bf16 v[4:7], v[166:169], v[216:219], v[4:7]
	s_setprio 0
	s_setprio 1
	v_mfma_f32_16x16x32_bf16 v[56:59], v[170:173], v[188:191], v[56:59]
	v_mfma_f32_16x16x32_bf16 v[48:51], v[178:181], v[188:191], v[48:51]
	v_mfma_f32_16x16x32_bf16 v[40:43], v[170:173], v[196:199], v[40:43]
	v_mfma_f32_16x16x32_bf16 v[32:35], v[178:181], v[196:199], v[32:35]
	v_mfma_f32_16x16x32_bf16 v[24:27], v[170:173], v[204:207], v[24:27]
	v_mfma_f32_16x16x32_bf16 v[16:19], v[178:181], v[204:207], v[16:19]
	v_mfma_f32_16x16x32_bf16 v[8:11], v[170:173], v[212:215], v[8:11]
	v_mfma_f32_16x16x32_bf16 v[0:3], v[178:181], v[212:215], v[0:3]
	v_mfma_f32_16x16x32_bf16 v[56:59], v[174:177], v[192:195], v[56:59]
	v_mfma_f32_16x16x32_bf16 v[48:51], v[182:185], v[192:195], v[48:51]
	v_mfma_f32_16x16x32_bf16 v[40:43], v[174:177], v[200:203], v[40:43]
	v_mfma_f32_16x16x32_bf16 v[32:35], v[182:185], v[200:203], v[32:35]
	v_mfma_f32_16x16x32_bf16 v[24:27], v[174:177], v[208:211], v[24:27]
	v_mfma_f32_16x16x32_bf16 v[16:19], v[182:185], v[208:211], v[16:19]
	v_mfma_f32_16x16x32_bf16 v[8:11], v[174:177], v[216:219], v[8:11]
	s_barrier
	v_mfma_f32_16x16x32_bf16 v[0:3], v[182:185], v[216:219], v[0:3]
	s_setprio 0
	s_add_i32 s69, s69, 2
	s_add_u32 s26, s26, 0x100
	s_addc_u32 s27, s27, 0
	s_add_u32 s67, s67, 0x100
	s_addc_u32 s68, s68, 0
	s_cmp_gt_u32 s69, 13
	s_cbranch_scc0 .LBB0_1055
	s_and_b64 vcc, exec, s[14:15]
	s_cbranch_vccz .LBB0_1058
	s_barrier

; #define PG8_STAGE(bufoff, gbase, voff) do { _Pragma("unroll") for (int _i = 0; _i < 2; ++_i) \
;         __builtin_amdgcn_global_load_lds((const unsigned*)((const char*)(gbase) + (voff)[_i]), (PG8_LAS unsigned*)(lds + (bufoff) + ldsw + _i * 8192), 16, 0, 0); } while (0)
; #define PG8_LDA(dst, b, h) do { _Pragma("unroll") for (int m = 0; m < 4; ++m) _Pragma("unroll") for (int k = 0; k < 2; ++k) dst[m][k] = *(const PG8_LAS bf16x8*)(lds + PG8_SA(b, h) + aoff + m * 2048 + k * 1024); } while (0)
; #define PG8_LDB(dst, b, h) do { _Pragma("unroll") for (int n = 0; n < 2; ++n) _Pragma("unroll") for (int k = 0; k < 2; ++k) dst[n][k] = *(const PG8_LAS bf16x8*)(lds + PG8_SB(b, h) + boff + n * 2048 + k * 1024); } while (0)
; #define PG8_MMA(ai, bj, At, Bt) do { __builtin_amdgcn_s_setprio(1); _Pragma("unroll") for (int m = 0; m < 4; ++m) _Pragma("unroll") for (int n = 0; n < 2; ++n) _Pragma("unroll") for (int k = 0; k < 2; ++k) \
;         acc[ai][bj][m][n] = __builtin_amdgcn_mfma_f32_16x16x32_bf16(Bt[n][k], At[m][k], acc[ai][bj][m][n], 0, 0, 0); __builtin_amdgcn_s_setprio(0); } while (0)
; #define PG8_WAIT_V(n) asm volatile("s_waitcnt vmcnt(" #n ")" ::: "memory")
; #define PG8_BAR __builtin_amdgcn_s_barrier()
; template <class Epi, class Sched, bool ALIGN_EPI = false, bool SP2 = false>
; __device__ __forceinline__ void gemm_phase(PG8_LAS unsigned char* lds, const Gemm g, const Sched& S, const Epi& E) {
;     ...
;         for (int t = 0; t < nt; t += 2) {
;             const bool last = (t == nt - 2);
;             const char* a1 = cA + (size_t)(t + 1) * kstep;
;             const char* a2 = last ? nA : cA + (size_t)(t + 2) * kstep; const char* b2 = last ? nB : cB + (size_t)(t + 2) * kstep;
;             const char* a3 = a2 + kstep; const char* b3 = b2 + kstep;
;             if (last && has_next) S.a_ready(nxt);
;             if constexpr (SP2) {
;             PG8_LDB(B0, 0, 0); PG8_LDB(B1, 0, 1); PG8_SCHED; PG8_LDA(At, 0, 0); PG8_STAGE(PG8_SA(1, 1), a1 + hstepA, voffA);
;             PG8_WAIT_V(8); PG8_WAIT_L(0); PG8_BAR; PG8_MMA(0, 0, At, B0); PG8_MMA(0, 1, At, B1); PG8_BAR; PG8_SCHED;
;             PG8_LDA(At, 0, 1); PG8_STAGE(PG8_SB(0, 0), b2, voffB); PG8_STAGE(PG8_SB(0, 1), b2 + hstepB, voffB); PG8_STAGE(PG8_SA(0, 0), a2, voffA);
;             PG8_WAIT_V(8); PG8_WAIT_L(0); PG8_BAR; PG8_MMA(1, 0, At, B0); PG8_MMA(1, 1, At, B1); PG8_BAR; PG8_SCHED;
.LBB0_1129:
	ds_read_b128 v[128:131], v191
	ds_read_b128 v[132:135], v191 offset:1024
	ds_read_b128 v[136:139], v191 offset:2048
	ds_read_b128 v[140:143], v191 offset:3072
	ds_read_b128 v[144:147], v192
	ds_read_b128 v[148:151], v192 offset:1024
	ds_read_b128 v[168:171], v192 offset:2048
	ds_read_b128 v[172:175], v192 offset:3072
	s_add_u32 s24, s22, 0x100
	s_addc_u32 s25, s23, 0
	s_cmp_eq_u32 s69, 40
	s_cselect_b32 s29, s11, s25
	s_cselect_b32 s28, s10, s24
	s_cselect_b32 s27, s21, s68
	s_cselect_b32 s26, s20, s67
	v_lshl_add_u64 v[184:185], s[22:23], 0, v[160:161]
	s_add_i32 m0, s34, 0xc000
	ds_read_b128 v[176:179], v193
	ds_read_b128 v[180:183], v193 offset:1024
	ds_read_b128 v[196:199], v193 offset:2048
	ds_read_b128 v[200:203], v193 offset:3072
	ds_read_b128 v[204:207], v193 offset:4096
	ds_read_b128 v[208:211], v193 offset:5120
	ds_read_b128 v[212:215], v193 offset:6144
	ds_read_b128 v[216:219], v193 offset:7168
	global_load_lds_dwordx4 v[184:185], off
	v_lshl_add_u64 v[184:185], s[22:23], 0, v[162:163]
	s_add_i32 m0, s34, 0xe000
	s_nop 0
	global_load_lds_dwordx4 v[184:185], off
	s_waitcnt vmcnt(8) lgkmcnt(0)
	s_barrier
	s_setprio 1
	v_mfma_f32_16x16x32_bf16 v[124:127], v[128:131], v[176:179], v[124:127]
	v_mfma_f32_16x16x32_bf16 v[120:123], v[136:139], v[176:179], v[120:123]
	v_mfma_f32_16x16x32_bf16 v[108:111], v[128:131], v[196:199], v[108:111]
	v_mfma_f32_16x16x32_bf16 v[104:107], v[136:139], v[196:199], v[104:107]
	v_mfma_f32_16x16x32_bf16 v[92:95], v[128:131], v[204:207], v[92:95]
	v_mfma_f32_16x16x32_bf16 v[88:91], v[136:139], v[204:207], v[88:91]
	v_mfma_f32_16x16x32_bf16 v[76:79], v[128:131], v[212:215], v[76:79]
	v_mfma_f32_16x16x32_bf16 v[72:75], v[136:139], v[212:215], v[72:75]
	v_mfma_f32_16x16x32_bf16 v[124:127], v[132:135], v[180:183], v[124:127]
	v_mfma_f32_16x16x32_bf16 v[120:123], v[140:143], v[180:183], v[120:123]
	v_mfma_f32_16x16x32_bf16 v[108:111], v[132:135], v[200:203], v[108:111]
	v_mfma_f32_16x16x32_bf16 v[104:107], v[140:143], v[200:203], v[104:107]
	v_mfma_f32_16x16x32_bf16 v[92:95], v[132:135], v[208:211], v[92:95]
	v_mfma_f32_16x16x32_bf16 v[88:91], v[140:143], v[208:211], v[88:91]
	v_mfma_f32_16x16x32_bf16 v[76:79], v[132:135], v[216:219], v[76:79]
	v_mfma_f32_16x16x32_bf16 v[72:75], v[140:143], v[216:219], v[72:75]
	s_setprio 0
	s_setprio 1
	v_mfma_f32_16x16x32_bf16 v[116:119], v[144:147], v[176:179], v[116:119]
	v_mfma_f32_16x16x32_bf16 v[112:115], v[168:171], v[176:179], v[112:115]
	v_mfma_f32_16x16x32_bf16 v[100:103], v[144:147], v[196:199], v[100:103]
	v_mfma_f32_16x16x32_bf16 v[96:99], v[168:171], v[196:199], v[96:99]
	v_mfma_f32_16x16x32_bf16 v[84:87], v[144:147], v[204:207], v[84:87]
	v_mfma_f32_16x16x32_bf16 v[80:83], v[168:171], v[204:207], v[80:83]
	v_mfma_f32_16x16x32_bf16 v[68:71], v[144:147], v[212:215], v[68:71]
	v_mfma_f32_16x16x32_bf16 v[64:67], v[168:171], v[212:215], v[64:67]
	v_mfma_f32_16x16x32_bf16 v[116:119], v[148:151], v[180:183], v[116:119]
	v_mfma_f32_16x16x32_bf16 v[112:115], v[172:175], v[180:183], v[112:115]
	v_mfma_f32_16x16x32_bf16 v[100:103], v[148:151], v[200:203], v[100:103]
	v_mfma_f32_16x16x32_bf16 v[96:99], v[172:175], v[200:203], v[96:99]
	v_mfma_f32_16x16x32_bf16 v[84:87], v[148:151], v[208:211], v[84:87]
	v_mfma_f32_16x16x32_bf16 v[80:83], v[172:175], v[208:211], v[80:83]
	v_mfma_f32_16x16x32_bf16 v[68:71], v[148:151], v[216:219], v[68:71]
	s_barrier
	v_mfma_f32_16x16x32_bf16 v[64:67], v[172:175], v[216:219], v[64:67]
	s_setprio 0
	s_add_i32 s22, s44, s31
	v_lshl_add_u64 v[184:185], s[26:27], 0, v[154:155]
	s_mov_b32 m0, s22
	ds_read_b128 v[176:179], v193 offset:16384
	ds_read_b128 v[180:183], v193 offset:17408
	ds_read_b128 v[196:199], v193 offset:18432
	ds_read_b128 v[200:203], v193 offset:19456
	ds_read_b128 v[204:207], v193 offset:20480
	ds_read_b128 v[208:211], v193 offset:21504
	ds_read_b128 v[212:215], v193 offset:22528
	ds_read_b128 v[216:219], v193 offset:23552
	global_load_lds_dwordx4 v[184:185], off
	s_add_i32 m0, s22, 0x2000
	s_add_u32 s22, s26, 0xb0000
	v_lshl_add_u64 v[220:221], s[26:27], 0, v[158:159]
	s_addc_u32 s23, s27, 0
	s_add_i32 s58, s45, s31
	global_load_lds_dwordx4 v[220:221], off
	v_lshl_add_u64 v[222:223], s[22:23], 0, v[154:155]
	s_mov_b32 m0, s58
	v_lshl_add_u64 v[224:225], s[28:29], 0, v[156:157]
	global_load_lds_dwordx4 v[222:223], off
	v_lshl_add_u64 v[222:223], s[22:23], 0, v[158:159]
	s_add_i32 m0, s58, 0x2000
	s_nop 0
	global_load_lds_dwordx4 v[222:223], off
	v_lshl_add_u64 v[222:223], s[28:29], 0, v[152:153]
	s_mov_b32 m0, s34
	s_nop 0
	global_load_lds_dwordx4 v[222:223], off
	s_mov_b32 m0, s35
	s_nop 0
	global_load_lds_dwordx4 v[224:225], off
	s_waitcnt vmcnt(8) lgkmcnt(0)
	s_barrier
; #define PG8_STAGE(bufoff, gbase, voff) do { _Pragma("unroll") for (int _i = 0; _i < 2; ++_i) \
;         __builtin_amdgcn_global_load_lds((const unsigned*)((const char*)(gbase) + (voff)[_i]), (PG8_LAS unsigned*)(lds + (bufoff) + ldsw + _i * 8192), 16, 0, 0); } while (0)
; #define PG8_LDA(dst, b, h) do { _Pragma("unroll") for (int m = 0; m < 4; ++m) _Pragma("unroll") for (int k = 0; k < 2; ++k) dst[m][k] = *(const PG8_LAS bf16x8*)(lds + PG8_SA(b, h) + aoff + m * 2048 + k * 1024); } while (0)
; #define PG8_LDB(dst, b, h) do { _Pragma("unroll") for (int n = 0; n < 2; ++n) _Pragma("unroll") for (int k = 0; k < 2; ++k) dst[n][k] = *(const PG8_LAS bf16x8*)(lds + PG8_SB(b, h) + boff + n * 2048 + k * 1024); } while (0)
; #define PG8_MMA(ai, bj, At, Bt) do { __builtin_amdgcn_s_setprio(1); _Pragma("unroll") for (int m = 0; m < 4; ++m) _Pragma("unroll") for (int n = 0; n < 2; ++n) _Pragma("unroll") for (int k = 0; k < 2; ++k) \
;         acc[ai][bj][m][n] = __builtin_amdgcn_mfma_f32_16x16x32_bf16(Bt[n][k], At[m][k], acc[ai][bj][m][n], 0, 0, 0); __builtin_amdgcn_s_setprio(0); } while (0)
; #define PG8_WAIT_V(n) asm volatile("s_waitcnt vmcnt(" #n ")" ::: "memory")
; #define PG8_WAIT_L(n) asm volatile("s_waitcnt lgkmcnt(" #n ")" ::: "memory")
; #define PG8_BAR __builtin_amdgcn_s_barrier()
; #define PG8_SCHED __builtin_amdgcn_sched_barrier(0)
; template <class Epi, class Sched, bool ALIGN_EPI = false, bool SP2 = false>
; __device__ __forceinline__ void gemm_phase(PG8_LAS unsigned char* lds, const Gemm g, const Sched& S, const Epi& E) {
;     ...
;             PG8_WAIT_V(8); PG8_WAIT_L(0); PG8_BAR; PG8_MMA(1, 0, At, B0); PG8_MMA(1, 1, At, B1); PG8_BAR; PG8_SCHED;
;             PG8_LDB(B0, 1, 0); PG8_LDB(B1, 1, 1); PG8_SCHED; PG8_LDA(At, 1, 0); PG8_STAGE(PG8_SA(0, 1), a2 + hstepA, voffA);
;             PG8_WAIT_V(8); PG8_WAIT_L(0); PG8_BAR; PG8_MMA(0, 0, At, B0); PG8_MMA(0, 1, At, B1); PG8_BAR; PG8_SCHED;
	s_setprio 1
	v_mfma_f32_16x16x32_bf16 v[60:63], v[128:131], v[176:179], v[60:63]
	v_mfma_f32_16x16x32_bf16 v[56:59], v[136:139], v[176:179], v[56:59]
	v_mfma_f32_16x16x32_bf16 v[44:47], v[128:131], v[196:199], v[44:47]
	v_mfma_f32_16x16x32_bf16 v[40:43], v[136:139], v[196:199], v[40:43]
	v_mfma_f32_16x16x32_bf16 v[28:31], v[128:131], v[204:207], v[28:31]
	v_mfma_f32_16x16x32_bf16 v[24:27], v[136:139], v[204:207], v[24:27]
	v_mfma_f32_16x16x32_bf16 v[12:15], v[128:131], v[212:215], v[12:15]
	v_mfma_f32_16x16x32_bf16 v[8:11], v[136:139], v[212:215], v[8:11]
	v_mfma_f32_16x16x32_bf16 v[60:63], v[132:135], v[180:183], v[60:63]
	v_mfma_f32_16x16x32_bf16 v[56:59], v[140:143], v[180:183], v[56:59]
	v_mfma_f32_16x16x32_bf16 v[44:47], v[132:135], v[200:203], v[44:47]
	v_mfma_f32_16x16x32_bf16 v[40:43], v[140:143], v[200:203], v[40:43]
	v_mfma_f32_16x16x32_bf16 v[28:31], v[132:135], v[208:211], v[28:31]
	v_mfma_f32_16x16x32_bf16 v[24:27], v[140:143], v[208:211], v[24:27]
	v_mfma_f32_16x16x32_bf16 v[12:15], v[132:135], v[216:219], v[12:15]
	v_mfma_f32_16x16x32_bf16 v[8:11], v[140:143], v[216:219], v[8:11]
	s_setprio 0
	s_setprio 1
	v_mfma_f32_16x16x32_bf16 v[52:55], v[144:147], v[176:179], v[52:55]
	v_mfma_f32_16x16x32_bf16 v[48:51], v[168:171], v[176:179], v[48:51]
	v_mfma_f32_16x16x32_bf16 v[36:39], v[144:147], v[196:199], v[36:39]
	v_mfma_f32_16x16x32_bf16 v[32:35], v[168:171], v[196:199], v[32:35]
	v_mfma_f32_16x16x32_bf16 v[20:23], v[144:147], v[204:207], v[20:23]
	v_mfma_f32_16x16x32_bf16 v[16:19], v[168:171], v[204:207], v[16:19]
	v_mfma_f32_16x16x32_bf16 v[4:7], v[144:147], v[212:215], v[4:7]
	v_mfma_f32_16x16x32_bf16 v[0:3], v[168:171], v[212:215], v[0:3]
	v_mfma_f32_16x16x32_bf16 v[52:55], v[148:151], v[180:183], v[52:55]
	v_mfma_f32_16x16x32_bf16 v[48:51], v[172:175], v[180:183], v[48:51]
	v_mfma_f32_16x16x32_bf16 v[36:39], v[148:151], v[200:203], v[36:39]
	v_mfma_f32_16x16x32_bf16 v[32:35], v[172:175], v[200:203], v[32:35]
	v_mfma_f32_16x16x32_bf16 v[20:23], v[148:151], v[208:211], v[20:23]
	v_mfma_f32_16x16x32_bf16 v[16:19], v[172:175], v[208:211], v[16:19]
	v_mfma_f32_16x16x32_bf16 v[4:7], v[148:151], v[216:219], v[4:7]
	s_barrier
	v_mfma_f32_16x16x32_bf16 v[0:3], v[172:175], v[216:219], v[0:3]
	s_setprio 0
	s_add_i32 s58, 0, 0x18000
	s_add_i32 s59, 0, 0x1c000
	v_add_u32_e32 v140, s58, v189
	v_add_u32_e32 v172, s59, v189
	ds_read_b128 v[128:131], v140
	ds_read_b128 v[132:135], v140 offset:1024
	ds_read_b128 v[136:139], v140 offset:2048
	ds_read_b128 v[140:143], v140 offset:3072
	ds_read_b128 v[144:147], v172
	ds_read_b128 v[148:151], v172 offset:1024
	ds_read_b128 v[168:171], v172 offset:2048
	ds_read_b128 v[172:175], v172 offset:3072
	s_add_u32 s22, s28, 0xb0000
	s_addc_u32 s23, s29, 0
	s_mov_b32 m0, s36
	v_lshl_add_u64 v[226:227], s[22:23], 0, v[152:153]
	ds_read_b128 v[176:179], v193 offset:32768
	ds_read_b128 v[180:183], v193 offset:33792
	ds_read_b128 v[196:199], v193 offset:34816
	ds_read_b128 v[200:203], v193 offset:35840
	ds_read_b128 v[204:207], v193 offset:36864
	ds_read_b128 v[208:211], v193 offset:37888
	ds_read_b128 v[212:215], v193 offset:38912
	ds_read_b128 v[216:219], v193 offset:39936
	global_load_lds_dwordx4 v[226:227], off
	v_lshl_add_u64 v[226:227], s[22:23], 0, v[156:157]
	s_mov_b32 m0, s37
	s_nop 0
	global_load_lds_dwordx4 v[226:227], off
	s_waitcnt vmcnt(8) lgkmcnt(0)
	s_barrier
	s_setprio 1
	v_mfma_f32_16x16x32_bf16 v[124:127], v[128:131], v[176:179], v[124:127]
	v_mfma_f32_16x16x32_bf16 v[120:123], v[136:139], v[176:179], v[120:123]
	v_mfma_f32_16x16x32_bf16 v[108:111], v[128:131], v[196:199], v[108:111]
	v_mfma_f32_16x16x32_bf16 v[104:107], v[136:139], v[196:199], v[104:107]
	v_mfma_f32_16x16x32_bf16 v[92:95], v[128:131], v[204:207], v[92:95]
	v_mfma_f32_16x16x32_bf16 v[88:91], v[136:139], v[204:207], v[88:91]
	v_mfma_f32_16x16x32_bf16 v[76:79], v[128:131], v[212:215], v[76:79]
	v_mfma_f32_16x16x32_bf16 v[72:75], v[136:139], v[212:215], v[72:75]
	v_mfma_f32_16x16x32_bf16 v[124:127], v[132:135], v[180:183], v[124:127]
	v_mfma_f32_16x16x32_bf16 v[120:123], v[140:143], v[180:183], v[120:123]
	v_mfma_f32_16x16x32_bf16 v[108:111], v[132:135], v[200:203], v[108:111]
	v_mfma_f32_16x16x32_bf16 v[104:107], v[140:143], v[200:203], v[104:107]
	v_mfma_f32_16x16x32_bf16 v[92:95], v[132:135], v[208:211], v[92:95]
	v_mfma_f32_16x16x32_bf16 v[88:91], v[140:143], v[208:211], v[88:91]
	v_mfma_f32_16x16x32_bf16 v[76:79], v[132:135], v[216:219], v[76:79]
	v_mfma_f32_16x16x32_bf16 v[72:75], v[140:143], v[216:219], v[72:75]
	s_setprio 0
	s_setprio 1
	v_mfma_f32_16x16x32_bf16 v[116:119], v[144:147], v[176:179], v[116:119]
	v_mfma_f32_16x16x32_bf16 v[112:115], v[168:171], v[176:179], v[112:115]
	v_mfma_f32_16x16x32_bf16 v[100:103], v[144:147], v[196:199], v[100:103]
	v_mfma_f32_16x16x32_bf16 v[96:99], v[168:171], v[196:199], v[96:99]
	v_mfma_f32_16x16x32_bf16 v[84:87], v[144:147], v[204:207], v[84:87]
	v_mfma_f32_16x16x32_bf16 v[80:83], v[168:171], v[204:207], v[80:83]
	v_mfma_f32_16x16x32_bf16 v[68:71], v[144:147], v[212:215], v[68:71]
	v_mfma_f32_16x16x32_bf16 v[64:67], v[168:171], v[212:215], v[64:67]
	v_mfma_f32_16x16x32_bf16 v[116:119], v[148:151], v[180:183], v[116:119]
	v_mfma_f32_16x16x32_bf16 v[112:115], v[172:175], v[180:183], v[112:115]
	v_mfma_f32_16x16x32_bf16 v[100:103], v[148:151], v[200:203], v[100:103]
	v_mfma_f32_16x16x32_bf16 v[96:99], v[172:175], v[200:203], v[96:99]
	v_mfma_f32_16x16x32_bf16 v[84:87], v[148:151], v[208:211], v[84:87]
	v_mfma_f32_16x16x32_bf16 v[80:83], v[172:175], v[208:211], v[80:83]
	v_mfma_f32_16x16x32_bf16 v[68:71], v[148:151], v[216:219], v[68:71]
	s_barrier
; #define PG8_STAGE(bufoff, gbase, voff) do { _Pragma("unroll") for (int _i = 0; _i < 2; ++_i) \
;         __builtin_amdgcn_global_load_lds((const unsigned*)((const char*)(gbase) + (voff)[_i]), (PG8_LAS unsigned*)(lds + (bufoff) + ldsw + _i * 8192), 16, 0, 0); } while (0)
; #define PG8_LDA(dst, b, h) do { _Pragma("unroll") for (int m = 0; m < 4; ++m) _Pragma("unroll") for (int k = 0; k < 2; ++k) dst[m][k] = *(const PG8_LAS bf16x8*)(lds + PG8_SA(b, h) + aoff + m * 2048 + k * 1024); } while (0)
; #define PG8_MMA(ai, bj, At, Bt) do { __builtin_amdgcn_s_setprio(1); _Pragma("unroll") for (int m = 0; m < 4; ++m) _Pragma("unroll") for (int n = 0; n < 2; ++n) _Pragma("unroll") for (int k = 0; k < 2; ++k) \
;         acc[ai][bj][m][n] = __builtin_amdgcn_mfma_f32_16x16x32_bf16(Bt[n][k], At[m][k], acc[ai][bj][m][n], 0, 0, 0); __builtin_amdgcn_s_setprio(0); } while (0)
; #define PG8_WAIT_V(n) asm volatile("s_waitcnt vmcnt(" #n ")" ::: "memory")
; #define PG8_WAIT_L(n) asm volatile("s_waitcnt lgkmcnt(" #n ")" ::: "memory")
; #define PG8_BAR __builtin_amdgcn_s_barrier()
; #define PG8_SCHED __builtin_amdgcn_sched_barrier(0)
; template <class Epi, class Sched, bool ALIGN_EPI = false, bool SP2 = false>
; __device__ __forceinline__ void gemm_phase(PG8_LAS unsigned char* lds, const Gemm g, const Sched& S, const Epi& E) {
;     ...
;         for (int t = 0; t < nt; t += 2) {
;             const bool last = (t == nt - 2);
;     ...
;             PG8_LDA(At, 1, 1); PG8_STAGE(PG8_SB(1, 0), b3, voffB); PG8_STAGE(PG8_SB(1, 1), b3 + hstepB, voffB); PG8_STAGE(PG8_SA(1, 0), a3, voffA);
;             PG8_WAIT_V(8); PG8_WAIT_L(0); PG8_BAR; PG8_MMA(1, 0, At, B0); PG8_MMA(1, 1, At, B1); PG8_BAR; PG8_SCHED;
	v_mfma_f32_16x16x32_bf16 v[64:67], v[172:175], v[216:219], v[64:67]
	s_setprio 0
	s_add_i32 s22, s58, s31
	v_lshl_add_u64 v[184:185], v[184:185], 0, s[16:17]
	s_mov_b32 m0, s22
	ds_read_b128 v[176:179], v193 offset:49152
	ds_read_b128 v[180:183], v193 offset:50176
	ds_read_b128 v[196:199], v193 offset:51200
	ds_read_b128 v[200:203], v193 offset:52224
	ds_read_b128 v[204:207], v193 offset:53248
	ds_read_b128 v[208:211], v193 offset:54272
	ds_read_b128 v[212:215], v193 offset:55296
	ds_read_b128 v[216:219], v193 offset:56320
	global_load_lds_dwordx4 v[184:185], off
	s_add_i32 m0, s22, 0x2000
	s_add_u32 s22, s26, 0xb0080
	v_lshl_add_u64 v[184:185], v[220:221], 0, s[16:17]
	s_addc_u32 s23, s27, 0
	s_add_i32 s26, s59, s31
	global_load_lds_dwordx4 v[184:185], off
	v_lshl_add_u64 v[184:185], s[22:23], 0, v[154:155]
	s_mov_b32 m0, s26
	s_nop 0
	global_load_lds_dwordx4 v[184:185], off
	v_lshl_add_u64 v[184:185], s[22:23], 0, v[158:159]
	s_add_i32 m0, s26, 0x2000
	s_nop 0
	global_load_lds_dwordx4 v[184:185], off
	v_lshl_add_u64 v[184:185], v[222:223], 0, s[16:17]
	s_mov_b32 m0, s39
	s_nop 0
	global_load_lds_dwordx4 v[184:185], off
	v_lshl_add_u64 v[184:185], v[224:225], 0, s[16:17]
	s_mov_b32 m0, s40
	s_nop 0
	global_load_lds_dwordx4 v[184:185], off
	s_waitcnt vmcnt(8) lgkmcnt(0)
	s_barrier
	s_setprio 1
	v_mfma_f32_16x16x32_bf16 v[60:63], v[128:131], v[176:179], v[60:63]
	v_mfma_f32_16x16x32_bf16 v[56:59], v[136:139], v[176:179], v[56:59]
	v_mfma_f32_16x16x32_bf16 v[44:47], v[128:131], v[196:199], v[44:47]
	v_mfma_f32_16x16x32_bf16 v[40:43], v[136:139], v[196:199], v[40:43]
	v_mfma_f32_16x16x32_bf16 v[28:31], v[128:131], v[204:207], v[28:31]
	v_mfma_f32_16x16x32_bf16 v[24:27], v[136:139], v[204:207], v[24:27]
	v_mfma_f32_16x16x32_bf16 v[12:15], v[128:131], v[212:215], v[12:15]
	v_mfma_f32_16x16x32_bf16 v[8:11], v[136:139], v[212:215], v[8:11]
	v_mfma_f32_16x16x32_bf16 v[60:63], v[132:135], v[180:183], v[60:63]
	v_mfma_f32_16x16x32_bf16 v[56:59], v[140:143], v[180:183], v[56:59]
	v_mfma_f32_16x16x32_bf16 v[44:47], v[132:135], v[200:203], v[44:47]
	v_mfma_f32_16x16x32_bf16 v[40:43], v[140:143], v[200:203], v[40:43]
	v_mfma_f32_16x16x32_bf16 v[28:31], v[132:135], v[208:211], v[28:31]
	v_mfma_f32_16x16x32_bf16 v[24:27], v[140:143], v[208:211], v[24:27]
	v_mfma_f32_16x16x32_bf16 v[12:15], v[132:135], v[216:219], v[12:15]
	v_mfma_f32_16x16x32_bf16 v[8:11], v[140:143], v[216:219], v[8:11]
	s_setprio 0
	s_setprio 1
	v_mfma_f32_16x16x32_bf16 v[52:55], v[144:147], v[176:179], v[52:55]
	v_mfma_f32_16x16x32_bf16 v[48:51], v[168:171], v[176:179], v[48:51]
	v_mfma_f32_16x16x32_bf16 v[36:39], v[144:147], v[196:199], v[36:39]
	v_mfma_f32_16x16x32_bf16 v[32:35], v[168:171], v[196:199], v[32:35]
	v_mfma_f32_16x16x32_bf16 v[20:23], v[144:147], v[204:207], v[20:23]
	v_mfma_f32_16x16x32_bf16 v[16:19], v[168:171], v[204:207], v[16:19]
	v_mfma_f32_16x16x32_bf16 v[4:7], v[144:147], v[212:215], v[4:7]
	v_mfma_f32_16x16x32_bf16 v[0:3], v[168:171], v[212:215], v[0:3]
	v_mfma_f32_16x16x32_bf16 v[52:55], v[148:151], v[180:183], v[52:55]
	v_mfma_f32_16x16x32_bf16 v[48:51], v[172:175], v[180:183], v[48:51]
	v_mfma_f32_16x16x32_bf16 v[36:39], v[148:151], v[200:203], v[36:39]
	v_mfma_f32_16x16x32_bf16 v[32:35], v[172:175], v[200:203], v[32:35]
	v_mfma_f32_16x16x32_bf16 v[20:23], v[148:151], v[208:211], v[20:23]
	v_mfma_f32_16x16x32_bf16 v[16:19], v[172:175], v[208:211], v[16:19]
	v_mfma_f32_16x16x32_bf16 v[4:7], v[148:151], v[216:219], v[4:7]
	s_barrier
	v_mfma_f32_16x16x32_bf16 v[0:3], v[172:175], v[216:219], v[0:3]
	s_setprio 0
	s_add_i32 s69, s69, 2
	s_add_u32 s67, s67, 0x100
	s_addc_u32 s68, s68, 0
	s_cmp_gt_u32 s69, 41
	s_mov_b64 s[22:23], s[24:25]
	s_cbranch_scc0 .LBB0_1129
	s_and_b64 vcc, exec, s[18:19]
	s_cbranch_vccz .LBB0_1132
	s_barrier

; #define PG8_STAGE(bufoff, gbase, voff) do { _Pragma("unroll") for (int _i = 0; _i < 2; ++_i) \
;         __builtin_amdgcn_global_load_lds((const unsigned*)((const char*)(gbase) + (voff)[_i]), (PG8_LAS unsigned*)(lds + (bufoff) + ldsw + _i * 8192), 16, 0, 0); } while (0)
; #define PG8_LDA(dst, b, h) do { _Pragma("unroll") for (int m = 0; m < 4; ++m) _Pragma("unroll") for (int k = 0; k < 2; ++k) dst[m][k] = *(const PG8_LAS bf16x8*)(lds + PG8_SA(b, h) + aoff + m * 2048 + k * 1024); } while (0)
; #define PG8_LDB(dst, b, h) do { _Pragma("unroll") for (int n = 0; n < 2; ++n) _Pragma("unroll") for (int k = 0; k < 2; ++k) dst[n][k] = *(const PG8_LAS bf16x8*)(lds + PG8_SB(b, h) + boff + n * 2048 + k * 1024); } while (0)
; #define PG8_WAIT_V(n) asm volatile("s_waitcnt vmcnt(" #n ")" ::: "memory")
; #define PG8_WAIT_L(n) asm volatile("s_waitcnt lgkmcnt(" #n ")" ::: "memory")
; #define PG8_BAR __builtin_amdgcn_s_barrier()
; #define PG8_SCHED __builtin_amdgcn_sched_barrier(0)
; template <class Epi, class Sched, bool ALIGN_EPI = false, bool SP2 = false>
; __device__ __forceinline__ void gemm_phase(PG8_LAS unsigned char* lds, const Gemm g, const Sched& S, const Epi& E) {
;     ...
;         const bool has_next = S.next(ui + 1, nxt);
;         const char* nA = has_next ? (const char*)g.A + (size_t)nxt.pm * tstepA : cA; const char* nB = has_next ? (const char*)g.Bt + (size_t)nxt.pn * tstepB : cB;
;         for (int t = 0; t < nt; t += 2) {
;             const bool last = (t == nt - 2);
;             const char* a1 = cA + (size_t)(t + 1) * kstep;
;             const char* a2 = last ? nA : cA + (size_t)(t + 2) * kstep; const char* b2 = last ? nB : cB + (size_t)(t + 2) * kstep;
;             const char* a3 = a2 + kstep; const char* b3 = b2 + kstep;
;             if (last && has_next) S.a_ready(nxt);
;             if constexpr (SP2) {
;             PG8_LDB(B0, 0, 0); PG8_LDB(B1, 0, 1); PG8_SCHED; PG8_LDA(At, 0, 0); PG8_STAGE(PG8_SA(1, 1), a1 + hstepA, voffA);
;             PG8_WAIT_V(8); PG8_WAIT_L(0); PG8_BAR; PG8_MMA(0, 0, At, B0); PG8_MMA(0, 1, At, B1); PG8_BAR; PG8_SCHED;
;             PG8_LDA(At, 0, 1); PG8_STAGE(PG8_SB(0, 0), b2, voffB); PG8_STAGE(PG8_SB(0, 1), b2 + hstepB, voffB); PG8_STAGE(PG8_SA(0, 0), a2, voffA);
;             PG8_WAIT_V(8); PG8_WAIT_L(0); PG8_BAR; PG8_MMA(1, 0, At, B0); PG8_MMA(1, 1, At, B1); PG8_BAR; PG8_SCHED;
.LBB0_1161:
	s_add_u32 s43, s36, s42
	s_addc_u32 s48, s37, 0
	s_add_u32 s46, s43, 0x100
	s_addc_u32 s47, s48, 0
	s_and_b64 s[44:45], s[40:41], exec
	s_cselect_b32 s45, s25, s47
	s_cselect_b32 s44, s89, s46
	s_add_u32 s42, s34, s42
	s_addc_u32 s46, s35, 0
	s_add_u32 s42, s42, 0x100
	s_addc_u32 s46, s46, 0
	s_and_b64 s[40:41], s[40:41], exec
	s_cselect_b32 s47, s23, s46
	s_cselect_b32 s46, s90, s42
	s_add_u32 s64, s43, 0x10080
	ds_read_b128 v[146:149], v143
	ds_read_b128 v[150:153], v143 offset:1024
	ds_read_b128 v[154:157], v143 offset:2048
	ds_read_b128 v[158:161], v143 offset:3072
	ds_read_b128 v[162:165], v144
	ds_read_b128 v[166:169], v144 offset:1024
	ds_read_b128 v[170:173], v144 offset:2048
	ds_read_b128 v[174:177], v144 offset:3072
	s_addc_u32 s65, s48, 0
	s_add_i32 s97, s82, s67
	s_add_i32 m0, s31, 0xc000
	s_add_i32 s59, s31, 0xe000
	s_add_i32 s58, s97, 0x2000
	s_add_u32 s48, s46, 0x10000
	s_addc_u32 s49, s47, 0
	s_add_i32 vcc_hi, s83, s67
	s_add_i32 vcc_lo, vcc_hi, 0x2000
	s_add_i32 s96, 0, 0x18000
	s_add_i32 s95, 0, 0x1c000
	s_add_u32 s42, s44, 0x10000
	s_addc_u32 s43, s45, 0
	s_add_i32 s94, s96, s67
	s_add_i32 s92, s94, 0x2000
	s_add_u32 s40, s46, 0x10080
	s_addc_u32 s41, s47, 0
	s_add_i32 s93, s95, s67
	s_add_i32 s91, s93, 0x2000
	v_lshl_add_u64 v[212:213], s[64:65], 0, v[134:135]
	ds_read_b128 v[178:181], v145
	ds_read_b128 v[182:185], v145 offset:1024
	ds_read_b128 v[188:191], v145 offset:2048
	ds_read_b128 v[192:195], v145 offset:3072
	ds_read_b128 v[196:199], v145 offset:4096
	ds_read_b128 v[200:203], v145 offset:5120
	ds_read_b128 v[204:207], v145 offset:6144
	ds_read_b128 v[208:211], v145 offset:7168
	global_load_lds_dwordx4 v[212:213], off
	v_lshl_add_u64 v[212:213], s[64:65], 0, v[130:131]
	s_mov_b32 m0, s59
	s_nop 0
	global_load_lds_dwordx4 v[212:213], off
	s_waitcnt vmcnt(8) lgkmcnt(0)
	s_barrier
	s_setprio 1
	v_mfma_f32_16x16x32_bf16 v[124:127], v[146:149], v[178:181], v[124:127]
	v_mfma_f32_16x16x32_bf16 v[120:123], v[154:157], v[178:181], v[120:123]
	v_mfma_f32_16x16x32_bf16 v[116:119], v[146:149], v[188:191], v[116:119]
	v_mfma_f32_16x16x32_bf16 v[108:111], v[154:157], v[188:191], v[108:111]
	v_mfma_f32_16x16x32_bf16 v[100:103], v[146:149], v[196:199], v[100:103]
	v_mfma_f32_16x16x32_bf16 v[92:95], v[154:157], v[196:199], v[92:95]
	v_mfma_f32_16x16x32_bf16 v[84:87], v[146:149], v[204:207], v[84:87]
	v_mfma_f32_16x16x32_bf16 v[76:79], v[154:157], v[204:207], v[76:79]
	v_mfma_f32_16x16x32_bf16 v[124:127], v[150:153], v[182:185], v[124:127]
	v_mfma_f32_16x16x32_bf16 v[120:123], v[158:161], v[182:185], v[120:123]
	v_mfma_f32_16x16x32_bf16 v[116:119], v[150:153], v[192:195], v[116:119]
	v_mfma_f32_16x16x32_bf16 v[108:111], v[158:161], v[192:195], v[108:111]
	v_mfma_f32_16x16x32_bf16 v[100:103], v[150:153], v[200:203], v[100:103]
	v_mfma_f32_16x16x32_bf16 v[92:95], v[158:161], v[200:203], v[92:95]
	v_mfma_f32_16x16x32_bf16 v[84:87], v[150:153], v[208:211], v[84:87]
	v_mfma_f32_16x16x32_bf16 v[76:79], v[158:161], v[208:211], v[76:79]
	s_setprio 0
	s_setprio 1
	v_mfma_f32_16x16x32_bf16 v[112:115], v[162:165], v[178:181], v[112:115]
	v_mfma_f32_16x16x32_bf16 v[104:107], v[170:173], v[178:181], v[104:107]
	v_mfma_f32_16x16x32_bf16 v[96:99], v[162:165], v[188:191], v[96:99]
	v_mfma_f32_16x16x32_bf16 v[88:91], v[170:173], v[188:191], v[88:91]
	v_mfma_f32_16x16x32_bf16 v[80:83], v[162:165], v[196:199], v[80:83]
	v_mfma_f32_16x16x32_bf16 v[72:75], v[170:173], v[196:199], v[72:75]
	v_mfma_f32_16x16x32_bf16 v[68:71], v[162:165], v[204:207], v[68:71]
	v_mfma_f32_16x16x32_bf16 v[64:67], v[170:173], v[204:207], v[64:67]
	v_mfma_f32_16x16x32_bf16 v[112:115], v[166:169], v[182:185], v[112:115]
	v_mfma_f32_16x16x32_bf16 v[104:107], v[174:177], v[182:185], v[104:107]
	v_mfma_f32_16x16x32_bf16 v[96:99], v[166:169], v[192:195], v[96:99]
	v_mfma_f32_16x16x32_bf16 v[88:91], v[174:177], v[192:195], v[88:91]
	v_mfma_f32_16x16x32_bf16 v[80:83], v[166:169], v[200:203], v[80:83]
	v_mfma_f32_16x16x32_bf16 v[72:75], v[174:177], v[200:203], v[72:75]
	v_mfma_f32_16x16x32_bf16 v[68:71], v[166:169], v[208:211], v[68:71]
	s_barrier
	v_mfma_f32_16x16x32_bf16 v[64:67], v[174:177], v[208:211], v[64:67]
	s_setprio 0
	s_mov_b32 m0, s97
	v_lshl_add_u64 v[212:213], s[46:47], 0, v[132:133]
	ds_read_b128 v[178:181], v145 offset:16384
	ds_read_b128 v[182:185], v145 offset:17408
	ds_read_b128 v[188:191], v145 offset:18432
	ds_read_b128 v[192:195], v145 offset:19456
	ds_read_b128 v[196:199], v145 offset:20480
	ds_read_b128 v[200:203], v145 offset:21504
	ds_read_b128 v[204:207], v145 offset:22528
	ds_read_b128 v[208:211], v145 offset:23552
	global_load_lds_dwordx4 v[212:213], off
	v_lshl_add_u64 v[214:215], s[46:47], 0, v[128:129]
	s_mov_b32 m0, s58
	v_lshl_add_u64 v[216:217], s[48:49], 0, v[132:133]
	global_load_lds_dwordx4 v[214:215], off
	s_mov_b32 m0, vcc_hi
	v_lshl_add_u64 v[218:219], s[44:45], 0, v[130:131]
	global_load_lds_dwordx4 v[216:217], off
	v_lshl_add_u64 v[216:217], s[48:49], 0, v[128:129]
	s_mov_b32 m0, vcc_lo
	s_nop 0
	global_load_lds_dwordx4 v[216:217], off
	v_lshl_add_u64 v[216:217], s[44:45], 0, v[134:135]
	s_mov_b32 m0, s31
	s_nop 0
	global_load_lds_dwordx4 v[216:217], off
	s_mov_b32 m0, s74
	s_nop 0
	global_load_lds_dwordx4 v[218:219], off
	s_waitcnt vmcnt(8) lgkmcnt(0)
	s_barrier
; #define PG8_STAGE(bufoff, gbase, voff) do { _Pragma("unroll") for (int _i = 0; _i < 2; ++_i) \
;         __builtin_amdgcn_global_load_lds((const unsigned*)((const char*)(gbase) + (voff)[_i]), (PG8_LAS unsigned*)(lds + (bufoff) + ldsw + _i * 8192), 16, 0, 0); } while (0)
; #define PG8_LDA(dst, b, h) do { _Pragma("unroll") for (int m = 0; m < 4; ++m) _Pragma("unroll") for (int k = 0; k < 2; ++k) dst[m][k] = *(const PG8_LAS bf16x8*)(lds + PG8_SA(b, h) + aoff + m * 2048 + k * 1024); } while (0)
; #define PG8_LDB(dst, b, h) do { _Pragma("unroll") for (int n = 0; n < 2; ++n) _Pragma("unroll") for (int k = 0; k < 2; ++k) dst[n][k] = *(const PG8_LAS bf16x8*)(lds + PG8_SB(b, h) + boff + n * 2048 + k * 1024); } while (0)
; #define PG8_MMA(ai, bj, At, Bt) do { __builtin_amdgcn_s_setprio(1); _Pragma("unroll") for (int m = 0; m < 4; ++m) _Pragma("unroll") for (int n = 0; n < 2; ++n) _Pragma("unroll") for (int k = 0; k < 2; ++k) \
;         acc[ai][bj][m][n] = __builtin_amdgcn_mfma_f32_16x16x32_bf16(Bt[n][k], At[m][k], acc[ai][bj][m][n], 0, 0, 0); __builtin_amdgcn_s_setprio(0); } while (0)
; #define PG8_WAIT_V(n) asm volatile("s_waitcnt vmcnt(" #n ")" ::: "memory")
; #define PG8_WAIT_L(n) asm volatile("s_waitcnt lgkmcnt(" #n ")" ::: "memory")
; #define PG8_BAR __builtin_amdgcn_s_barrier()
; #define PG8_SCHED __builtin_amdgcn_sched_barrier(0)
; template <class Epi, class Sched, bool ALIGN_EPI = false, bool SP2 = false>
; __device__ __forceinline__ void gemm_phase(PG8_LAS unsigned char* lds, const Gemm g, const Sched& S, const Epi& E) {
;     ...
;             PG8_WAIT_V(8); PG8_WAIT_L(0); PG8_BAR; PG8_MMA(1, 0, At, B0); PG8_MMA(1, 1, At, B1); PG8_BAR; PG8_SCHED;
;             PG8_LDB(B0, 1, 0); PG8_LDB(B1, 1, 1); PG8_SCHED; PG8_LDA(At, 1, 0); PG8_STAGE(PG8_SA(0, 1), a2 + hstepA, voffA);
;             PG8_WAIT_V(8); PG8_WAIT_L(0); PG8_BAR; PG8_MMA(0, 0, At, B0); PG8_MMA(0, 1, At, B1); PG8_BAR; PG8_SCHED;
	s_setprio 1
	v_mfma_f32_16x16x32_bf16 v[60:63], v[146:149], v[178:181], v[60:63]
	v_mfma_f32_16x16x32_bf16 v[56:59], v[154:157], v[178:181], v[56:59]
	v_mfma_f32_16x16x32_bf16 v[52:55], v[146:149], v[188:191], v[52:55]
	v_mfma_f32_16x16x32_bf16 v[44:47], v[154:157], v[188:191], v[44:47]
	v_mfma_f32_16x16x32_bf16 v[36:39], v[146:149], v[196:199], v[36:39]
	v_mfma_f32_16x16x32_bf16 v[28:31], v[154:157], v[196:199], v[28:31]
	v_mfma_f32_16x16x32_bf16 v[20:23], v[146:149], v[204:207], v[20:23]
	v_mfma_f32_16x16x32_bf16 v[12:15], v[154:157], v[204:207], v[12:15]
	v_mfma_f32_16x16x32_bf16 v[60:63], v[150:153], v[182:185], v[60:63]
	v_mfma_f32_16x16x32_bf16 v[56:59], v[158:161], v[182:185], v[56:59]
	v_mfma_f32_16x16x32_bf16 v[52:55], v[150:153], v[192:195], v[52:55]
	v_mfma_f32_16x16x32_bf16 v[44:47], v[158:161], v[192:195], v[44:47]
	v_mfma_f32_16x16x32_bf16 v[36:39], v[150:153], v[200:203], v[36:39]
	v_mfma_f32_16x16x32_bf16 v[28:31], v[158:161], v[200:203], v[28:31]
	v_mfma_f32_16x16x32_bf16 v[20:23], v[150:153], v[208:211], v[20:23]
	v_mfma_f32_16x16x32_bf16 v[12:15], v[158:161], v[208:211], v[12:15]
	s_setprio 0
	s_setprio 1
	v_mfma_f32_16x16x32_bf16 v[48:51], v[162:165], v[178:181], v[48:51]
	v_mfma_f32_16x16x32_bf16 v[40:43], v[170:173], v[178:181], v[40:43]
	v_mfma_f32_16x16x32_bf16 v[32:35], v[162:165], v[188:191], v[32:35]
	v_mfma_f32_16x16x32_bf16 v[24:27], v[170:173], v[188:191], v[24:27]
	v_mfma_f32_16x16x32_bf16 v[16:19], v[162:165], v[196:199], v[16:19]
	v_mfma_f32_16x16x32_bf16 v[8:11], v[170:173], v[196:199], v[8:11]
	v_mfma_f32_16x16x32_bf16 v[4:7], v[162:165], v[204:207], v[4:7]
	v_mfma_f32_16x16x32_bf16 v[0:3], v[170:173], v[204:207], v[0:3]
	v_mfma_f32_16x16x32_bf16 v[48:51], v[166:169], v[182:185], v[48:51]
	v_mfma_f32_16x16x32_bf16 v[40:43], v[174:177], v[182:185], v[40:43]
	v_mfma_f32_16x16x32_bf16 v[32:35], v[166:169], v[192:195], v[32:35]
	v_mfma_f32_16x16x32_bf16 v[24:27], v[174:177], v[192:195], v[24:27]
	v_mfma_f32_16x16x32_bf16 v[16:19], v[166:169], v[200:203], v[16:19]
	v_mfma_f32_16x16x32_bf16 v[8:11], v[174:177], v[200:203], v[8:11]
	v_mfma_f32_16x16x32_bf16 v[4:7], v[166:169], v[208:211], v[4:7]
	s_barrier
	v_mfma_f32_16x16x32_bf16 v[0:3], v[174:177], v[208:211], v[0:3]
	s_setprio 0
	v_add_u32_e32 v158, s96, v141
	v_add_u32_e32 v174, s95, v141
	ds_read_b128 v[146:149], v158
	ds_read_b128 v[150:153], v158 offset:1024
	ds_read_b128 v[154:157], v158 offset:2048
	ds_read_b128 v[158:161], v158 offset:3072
	ds_read_b128 v[162:165], v174
	ds_read_b128 v[166:169], v174 offset:1024
	ds_read_b128 v[170:173], v174 offset:2048
	ds_read_b128 v[174:177], v174 offset:3072
	s_mov_b32 m0, s75
	v_lshl_add_u64 v[220:221], s[42:43], 0, v[134:135]
	ds_read_b128 v[178:181], v145 offset:32768
	ds_read_b128 v[182:185], v145 offset:33792
	ds_read_b128 v[188:191], v145 offset:34816
	ds_read_b128 v[192:195], v145 offset:35840
	ds_read_b128 v[196:199], v145 offset:36864
	ds_read_b128 v[200:203], v145 offset:37888
	ds_read_b128 v[204:207], v145 offset:38912
	ds_read_b128 v[208:211], v145 offset:39936
	global_load_lds_dwordx4 v[220:221], off
	v_lshl_add_u64 v[220:221], s[42:43], 0, v[130:131]
	s_mov_b32 m0, s76
	s_nop 0
	global_load_lds_dwordx4 v[220:221], off
	s_waitcnt vmcnt(8) lgkmcnt(0)
	s_barrier
	s_setprio 1
	v_mfma_f32_16x16x32_bf16 v[124:127], v[146:149], v[178:181], v[124:127]
	v_mfma_f32_16x16x32_bf16 v[120:123], v[154:157], v[178:181], v[120:123]
	v_mfma_f32_16x16x32_bf16 v[116:119], v[146:149], v[188:191], v[116:119]
	v_mfma_f32_16x16x32_bf16 v[108:111], v[154:157], v[188:191], v[108:111]
	v_mfma_f32_16x16x32_bf16 v[100:103], v[146:149], v[196:199], v[100:103]
	v_mfma_f32_16x16x32_bf16 v[92:95], v[154:157], v[196:199], v[92:95]
	v_mfma_f32_16x16x32_bf16 v[84:87], v[146:149], v[204:207], v[84:87]
	v_mfma_f32_16x16x32_bf16 v[76:79], v[154:157], v[204:207], v[76:79]
	v_mfma_f32_16x16x32_bf16 v[124:127], v[150:153], v[182:185], v[124:127]
	v_mfma_f32_16x16x32_bf16 v[120:123], v[158:161], v[182:185], v[120:123]
	v_mfma_f32_16x16x32_bf16 v[116:119], v[150:153], v[192:195], v[116:119]
	v_mfma_f32_16x16x32_bf16 v[108:111], v[158:161], v[192:195], v[108:111]
	v_mfma_f32_16x16x32_bf16 v[100:103], v[150:153], v[200:203], v[100:103]
	v_mfma_f32_16x16x32_bf16 v[92:95], v[158:161], v[200:203], v[92:95]
	v_mfma_f32_16x16x32_bf16 v[84:87], v[150:153], v[208:211], v[84:87]
	v_mfma_f32_16x16x32_bf16 v[76:79], v[158:161], v[208:211], v[76:79]
	s_setprio 0
	s_setprio 1
	v_mfma_f32_16x16x32_bf16 v[112:115], v[162:165], v[178:181], v[112:115]
	v_mfma_f32_16x16x32_bf16 v[104:107], v[170:173], v[178:181], v[104:107]
	v_mfma_f32_16x16x32_bf16 v[96:99], v[162:165], v[188:191], v[96:99]
	v_mfma_f32_16x16x32_bf16 v[88:91], v[170:173], v[188:191], v[88:91]
	v_mfma_f32_16x16x32_bf16 v[80:83], v[162:165], v[196:199], v[80:83]
	v_mfma_f32_16x16x32_bf16 v[72:75], v[170:173], v[196:199], v[72:75]
	v_mfma_f32_16x16x32_bf16 v[68:71], v[162:165], v[204:207], v[68:71]
	v_mfma_f32_16x16x32_bf16 v[64:67], v[170:173], v[204:207], v[64:67]
	v_mfma_f32_16x16x32_bf16 v[112:115], v[166:169], v[182:185], v[112:115]
	v_mfma_f32_16x16x32_bf16 v[104:107], v[174:177], v[182:185], v[104:107]
	v_mfma_f32_16x16x32_bf16 v[96:99], v[166:169], v[192:195], v[96:99]
	v_mfma_f32_16x16x32_bf16 v[88:91], v[174:177], v[192:195], v[88:91]
	v_mfma_f32_16x16x32_bf16 v[80:83], v[166:169], v[200:203], v[80:83]
	v_mfma_f32_16x16x32_bf16 v[72:75], v[174:177], v[200:203], v[72:75]
	v_mfma_f32_16x16x32_bf16 v[68:71], v[166:169], v[208:211], v[68:71]
	s_barrier
; #define PG8_STAGE(bufoff, gbase, voff) do { _Pragma("unroll") for (int _i = 0; _i < 2; ++_i) \
;         __builtin_amdgcn_global_load_lds((const unsigned*)((const char*)(gbase) + (voff)[_i]), (PG8_LAS unsigned*)(lds + (bufoff) + ldsw + _i * 8192), 16, 0, 0); } while (0)
; #define PG8_LDA(dst, b, h) do { _Pragma("unroll") for (int m = 0; m < 4; ++m) _Pragma("unroll") for (int k = 0; k < 2; ++k) dst[m][k] = *(const PG8_LAS bf16x8*)(lds + PG8_SA(b, h) + aoff + m * 2048 + k * 1024); } while (0)
; #define PG8_MMA(ai, bj, At, Bt) do { __builtin_amdgcn_s_setprio(1); _Pragma("unroll") for (int m = 0; m < 4; ++m) _Pragma("unroll") for (int n = 0; n < 2; ++n) _Pragma("unroll") for (int k = 0; k < 2; ++k) \
;         acc[ai][bj][m][n] = __builtin_amdgcn_mfma_f32_16x16x32_bf16(Bt[n][k], At[m][k], acc[ai][bj][m][n], 0, 0, 0); __builtin_amdgcn_s_setprio(0); } while (0)
; #define PG8_WAIT_V(n) asm volatile("s_waitcnt vmcnt(" #n ")" ::: "memory")
; #define PG8_WAIT_L(n) asm volatile("s_waitcnt lgkmcnt(" #n ")" ::: "memory")
; #define PG8_BAR __builtin_amdgcn_s_barrier()
; #define PG8_SCHED __builtin_amdgcn_sched_barrier(0)
; template <class Epi, class Sched, bool ALIGN_EPI = false, bool SP2 = false>
; __device__ __forceinline__ void gemm_phase(PG8_LAS unsigned char* lds, const Gemm g, const Sched& S, const Epi& E) {
;     ...
;         for (int t = 0; t < nt; t += 2) {
;     ...
;             PG8_LDA(At, 1, 1); PG8_STAGE(PG8_SB(1, 0), b3, voffB); PG8_STAGE(PG8_SB(1, 1), b3 + hstepB, voffB); PG8_STAGE(PG8_SA(1, 0), a3, voffA);
;             PG8_WAIT_V(8); PG8_WAIT_L(0); PG8_BAR; PG8_MMA(1, 0, At, B0); PG8_MMA(1, 1, At, B1); PG8_BAR; PG8_SCHED;
	v_mfma_f32_16x16x32_bf16 v[64:67], v[174:177], v[208:211], v[64:67]
	s_setprio 0
	s_mov_b32 m0, s94
	v_lshl_add_u64 v[212:213], v[212:213], 0, s[10:11]
	ds_read_b128 v[178:181], v145 offset:49152
	ds_read_b128 v[182:185], v145 offset:50176
	ds_read_b128 v[188:191], v145 offset:51200
	ds_read_b128 v[192:195], v145 offset:52224
	ds_read_b128 v[196:199], v145 offset:53248
	ds_read_b128 v[200:203], v145 offset:54272
	ds_read_b128 v[204:207], v145 offset:55296
	ds_read_b128 v[208:211], v145 offset:56320
	global_load_lds_dwordx4 v[212:213], off
	v_lshl_add_u64 v[212:213], v[214:215], 0, s[10:11]
	s_mov_b32 m0, s92
	s_nop 0
	global_load_lds_dwordx4 v[212:213], off
	v_lshl_add_u64 v[212:213], s[40:41], 0, v[132:133]
	s_mov_b32 m0, s93
	s_nop 0
	global_load_lds_dwordx4 v[212:213], off
	v_lshl_add_u64 v[212:213], s[40:41], 0, v[128:129]
	s_mov_b32 m0, s91
	s_nop 0
	global_load_lds_dwordx4 v[212:213], off
	v_lshl_add_u64 v[212:213], v[216:217], 0, s[10:11]
	s_mov_b32 m0, s78
	s_nop 0
	global_load_lds_dwordx4 v[212:213], off
	v_lshl_add_u64 v[212:213], v[218:219], 0, s[10:11]
	s_mov_b32 m0, s79
	s_nop 0
	global_load_lds_dwordx4 v[212:213], off
	s_waitcnt vmcnt(8) lgkmcnt(0)
	s_barrier
	s_setprio 1
	v_mfma_f32_16x16x32_bf16 v[60:63], v[146:149], v[178:181], v[60:63]
	v_mfma_f32_16x16x32_bf16 v[56:59], v[154:157], v[178:181], v[56:59]
	v_mfma_f32_16x16x32_bf16 v[52:55], v[146:149], v[188:191], v[52:55]
	v_mfma_f32_16x16x32_bf16 v[44:47], v[154:157], v[188:191], v[44:47]
	v_mfma_f32_16x16x32_bf16 v[36:39], v[146:149], v[196:199], v[36:39]
	v_mfma_f32_16x16x32_bf16 v[28:31], v[154:157], v[196:199], v[28:31]
	v_mfma_f32_16x16x32_bf16 v[20:23], v[146:149], v[204:207], v[20:23]
	v_mfma_f32_16x16x32_bf16 v[12:15], v[154:157], v[204:207], v[12:15]
	v_mfma_f32_16x16x32_bf16 v[60:63], v[150:153], v[182:185], v[60:63]
	v_mfma_f32_16x16x32_bf16 v[56:59], v[158:161], v[182:185], v[56:59]
	v_mfma_f32_16x16x32_bf16 v[52:55], v[150:153], v[192:195], v[52:55]
	v_mfma_f32_16x16x32_bf16 v[44:47], v[158:161], v[192:195], v[44:47]
	v_mfma_f32_16x16x32_bf16 v[36:39], v[150:153], v[200:203], v[36:39]
	v_mfma_f32_16x16x32_bf16 v[28:31], v[158:161], v[200:203], v[28:31]
	v_mfma_f32_16x16x32_bf16 v[20:23], v[150:153], v[208:211], v[20:23]
	v_mfma_f32_16x16x32_bf16 v[12:15], v[158:161], v[208:211], v[12:15]
	s_setprio 0
	s_setprio 1
	v_mfma_f32_16x16x32_bf16 v[48:51], v[162:165], v[178:181], v[48:51]
	v_mfma_f32_16x16x32_bf16 v[40:43], v[170:173], v[178:181], v[40:43]
	v_mfma_f32_16x16x32_bf16 v[32:35], v[162:165], v[188:191], v[32:35]
	v_mfma_f32_16x16x32_bf16 v[24:27], v[170:173], v[188:191], v[24:27]
	v_mfma_f32_16x16x32_bf16 v[16:19], v[162:165], v[196:199], v[16:19]
	v_mfma_f32_16x16x32_bf16 v[8:11], v[170:173], v[196:199], v[8:11]
	v_mfma_f32_16x16x32_bf16 v[4:7], v[162:165], v[204:207], v[4:7]
	v_mfma_f32_16x16x32_bf16 v[0:3], v[170:173], v[204:207], v[0:3]
	v_mfma_f32_16x16x32_bf16 v[48:51], v[166:169], v[182:185], v[48:51]
	v_mfma_f32_16x16x32_bf16 v[40:43], v[174:177], v[182:185], v[40:43]
	v_mfma_f32_16x16x32_bf16 v[32:35], v[166:169], v[192:195], v[32:35]
	v_mfma_f32_16x16x32_bf16 v[24:27], v[174:177], v[192:195], v[24:27]
	v_mfma_f32_16x16x32_bf16 v[16:19], v[166:169], v[200:203], v[16:19]
	v_mfma_f32_16x16x32_bf16 v[8:11], v[174:177], v[200:203], v[8:11]
	v_mfma_f32_16x16x32_bf16 v[4:7], v[166:169], v[208:211], v[4:7]
	s_barrier
	v_mfma_f32_16x16x32_bf16 v[0:3], v[174:177], v[208:211], v[0:3]
	s_setprio 0
	s_movk_i32 s42, 0x100
	s_andn2_b64 vcc, exec, s[38:39]
	s_mov_b64 s[40:41], -1
	s_mov_b64 s[38:39], 0
	s_cbranch_vccz .LBB0_1161
	s_and_b64 vcc, exec, s[14:15]
	s_cbranch_vccz .LBB0_1164
	s_barrier

; #define PG8_STAGE(bufoff, gbase, voff) do { _Pragma("unroll") for (int _i = 0; _i < 2; ++_i) \
;         __builtin_amdgcn_global_load_lds((const unsigned*)((const char*)(gbase) + (voff)[_i]), (PG8_LAS unsigned*)(lds + (bufoff) + ldsw + _i * 8192), 16, 0, 0); } while (0)
; #define PG8_LDA(dst, b, h) do { _Pragma("unroll") for (int m = 0; m < 4; ++m) _Pragma("unroll") for (int k = 0; k < 2; ++k) dst[m][k] = *(const PG8_LAS bf16x8*)(lds + PG8_SA(b, h) + aoff + m * 2048 + k * 1024); } while (0)
; #define PG8_LDB(dst, b, h) do { _Pragma("unroll") for (int n = 0; n < 2; ++n) _Pragma("unroll") for (int k = 0; k < 2; ++k) dst[n][k] = *(const PG8_LAS bf16x8*)(lds + PG8_SB(b, h) + boff + n * 2048 + k * 1024); } while (0)
; #define PG8_MMA(ai, bj, At, Bt) do { __builtin_amdgcn_s_setprio(1); _Pragma("unroll") for (int m = 0; m < 4; ++m) _Pragma("unroll") for (int n = 0; n < 2; ++n) _Pragma("unroll") for (int k = 0; k < 2; ++k) \
;         acc[ai][bj][m][n] = __builtin_amdgcn_mfma_f32_16x16x32_bf16(Bt[n][k], At[m][k], acc[ai][bj][m][n], 0, 0, 0); __builtin_amdgcn_s_setprio(0); } while (0)
; #define PG8_WAIT_V(n) asm volatile("s_waitcnt vmcnt(" #n ")" ::: "memory")
; #define PG8_BAR __builtin_amdgcn_s_barrier()
; template <class Epi, class Sched, bool ALIGN_EPI = false, bool SP2 = false>
; __device__ __forceinline__ void gemm_phase(PG8_LAS unsigned char* lds, const Gemm g, const Sched& S, const Epi& E) {
;     ...
;         for (int t = 0; t < nt; t += 2) {
;             const bool last = (t == nt - 2);
;             const char* a1 = cA + (size_t)(t + 1) * kstep;
;             const char* a2 = last ? nA : cA + (size_t)(t + 2) * kstep; const char* b2 = last ? nB : cB + (size_t)(t + 2) * kstep;
;             const char* a3 = a2 + kstep; const char* b3 = b2 + kstep;
;             if (last && has_next) S.a_ready(nxt);
;             if constexpr (SP2) {
;             PG8_LDB(B0, 0, 0); PG8_LDB(B1, 0, 1); PG8_SCHED; PG8_LDA(At, 0, 0); PG8_STAGE(PG8_SA(1, 1), a1 + hstepA, voffA);
;             PG8_WAIT_V(8); PG8_WAIT_L(0); PG8_BAR; PG8_MMA(0, 0, At, B0); PG8_MMA(0, 1, At, B1); PG8_BAR; PG8_SCHED;
;             PG8_LDA(At, 0, 1); PG8_STAGE(PG8_SB(0, 0), b2, voffB); PG8_STAGE(PG8_SB(0, 1), b2 + hstepB, voffB); PG8_STAGE(PG8_SA(0, 0), a2, voffA);
;             PG8_WAIT_V(8); PG8_WAIT_L(0); PG8_BAR; PG8_MMA(1, 0, At, B0); PG8_MMA(1, 1, At, B1); PG8_BAR; PG8_SCHED;
.LBB0_1231:
	ds_read_b128 v[112:115], v185
	ds_read_b128 v[116:119], v185 offset:1024
	ds_read_b128 v[128:131], v185 offset:2048
	ds_read_b128 v[140:143], v185 offset:3072
	ds_read_b128 v[144:147], v188
	ds_read_b128 v[148:151], v188 offset:1024
	ds_read_b128 v[168:171], v188 offset:2048
	ds_read_b128 v[172:175], v188 offset:3072
	s_add_u32 s34, s30, 0xfffc0080
	s_addc_u32 s35, s31, -1
	s_cmp_eq_u32 s69, 12
	s_cselect_b32 s37, s21, s35
	s_cselect_b32 s36, s27, s34
	s_cselect_b32 s35, s19, s68
	s_cselect_b32 s34, s66, s67
	v_lshl_add_u64 v[180:181], s[30:31], 0, v[160:161]
	s_add_i32 m0, s29, 0xc000
	ds_read_b128 v[176:179], v189
	ds_read_b128 v[192:195], v189 offset:1024
	ds_read_b128 v[196:199], v189 offset:2048
	ds_read_b128 v[200:203], v189 offset:3072
	ds_read_b128 v[204:207], v189 offset:4096
	ds_read_b128 v[208:211], v189 offset:5120
	ds_read_b128 v[212:215], v189 offset:6144
	ds_read_b128 v[216:219], v189 offset:7168
	global_load_lds_dwordx4 v[180:181], off
	v_lshl_add_u64 v[180:181], s[30:31], 0, v[162:163]
	s_add_i32 m0, s29, 0xe000
	s_nop 0
	global_load_lds_dwordx4 v[180:181], off
	s_waitcnt vmcnt(8) lgkmcnt(0)
	s_barrier
	s_setprio 1
	v_mfma_f32_16x16x32_bf16 v[136:139], v[112:115], v[176:179], v[136:139]
	v_mfma_f32_16x16x32_bf16 v[132:135], v[128:131], v[176:179], v[132:135]
	v_mfma_f32_16x16x32_bf16 v[108:111], v[112:115], v[196:199], v[108:111]
	v_mfma_f32_16x16x32_bf16 v[104:107], v[128:131], v[196:199], v[104:107]
	v_mfma_f32_16x16x32_bf16 v[92:95], v[112:115], v[204:207], v[92:95]
	v_mfma_f32_16x16x32_bf16 v[88:91], v[128:131], v[204:207], v[88:91]
	v_mfma_f32_16x16x32_bf16 v[76:79], v[112:115], v[212:215], v[76:79]
	v_mfma_f32_16x16x32_bf16 v[72:75], v[128:131], v[212:215], v[72:75]
	v_mfma_f32_16x16x32_bf16 v[136:139], v[116:119], v[192:195], v[136:139]
	v_mfma_f32_16x16x32_bf16 v[132:135], v[140:143], v[192:195], v[132:135]
	v_mfma_f32_16x16x32_bf16 v[108:111], v[116:119], v[200:203], v[108:111]
	v_mfma_f32_16x16x32_bf16 v[104:107], v[140:143], v[200:203], v[104:107]
	v_mfma_f32_16x16x32_bf16 v[92:95], v[116:119], v[208:211], v[92:95]
	v_mfma_f32_16x16x32_bf16 v[88:91], v[140:143], v[208:211], v[88:91]
	v_mfma_f32_16x16x32_bf16 v[76:79], v[116:119], v[216:219], v[76:79]
	v_mfma_f32_16x16x32_bf16 v[72:75], v[140:143], v[216:219], v[72:75]
	s_setprio 0
	s_setprio 1
	v_mfma_f32_16x16x32_bf16 v[124:127], v[144:147], v[176:179], v[124:127]
	v_mfma_f32_16x16x32_bf16 v[120:123], v[168:171], v[176:179], v[120:123]
	v_mfma_f32_16x16x32_bf16 v[100:103], v[144:147], v[196:199], v[100:103]
	v_mfma_f32_16x16x32_bf16 v[96:99], v[168:171], v[196:199], v[96:99]
	v_mfma_f32_16x16x32_bf16 v[84:87], v[144:147], v[204:207], v[84:87]
	v_mfma_f32_16x16x32_bf16 v[80:83], v[168:171], v[204:207], v[80:83]
	v_mfma_f32_16x16x32_bf16 v[68:71], v[144:147], v[212:215], v[68:71]
	v_mfma_f32_16x16x32_bf16 v[64:67], v[168:171], v[212:215], v[64:67]
	v_mfma_f32_16x16x32_bf16 v[124:127], v[148:151], v[192:195], v[124:127]
	v_mfma_f32_16x16x32_bf16 v[120:123], v[172:175], v[192:195], v[120:123]
	v_mfma_f32_16x16x32_bf16 v[100:103], v[148:151], v[200:203], v[100:103]
	v_mfma_f32_16x16x32_bf16 v[96:99], v[172:175], v[200:203], v[96:99]
	v_mfma_f32_16x16x32_bf16 v[84:87], v[148:151], v[208:211], v[84:87]
	v_mfma_f32_16x16x32_bf16 v[80:83], v[172:175], v[208:211], v[80:83]
	v_mfma_f32_16x16x32_bf16 v[68:71], v[148:151], v[216:219], v[68:71]
	s_barrier
	v_mfma_f32_16x16x32_bf16 v[64:67], v[172:175], v[216:219], v[64:67]
	s_setprio 0
	s_add_i32 s58, s49, s39
	v_lshl_add_u64 v[180:181], s[34:35], 0, v[154:155]
	s_mov_b32 m0, s58
	ds_read_b128 v[176:179], v189 offset:16384
	ds_read_b128 v[192:195], v189 offset:17408
	ds_read_b128 v[196:199], v189 offset:18432
	ds_read_b128 v[200:203], v189 offset:19456
	ds_read_b128 v[204:207], v189 offset:20480
	ds_read_b128 v[208:211], v189 offset:21504
	ds_read_b128 v[212:215], v189 offset:22528
	ds_read_b128 v[216:219], v189 offset:23552
	global_load_lds_dwordx4 v[180:181], off
	s_add_i32 m0, s58, 0x2000
	s_add_u32 s58, s34, 0x40000
	v_lshl_add_u64 v[220:221], s[34:35], 0, v[158:159]
	s_addc_u32 s59, s35, 0
	s_add_i32 s73, s64, s39
	global_load_lds_dwordx4 v[220:221], off
	v_lshl_add_u64 v[222:223], s[58:59], 0, v[154:155]
	s_mov_b32 m0, s73
	v_lshl_add_u64 v[224:225], s[36:37], 0, v[156:157]
	global_load_lds_dwordx4 v[222:223], off
	v_lshl_add_u64 v[222:223], s[58:59], 0, v[158:159]
	s_add_i32 m0, s73, 0x2000
	s_nop 0
	global_load_lds_dwordx4 v[222:223], off
	v_lshl_add_u64 v[222:223], s[36:37], 0, v[152:153]
	s_mov_b32 m0, s29
	s_nop 0
	global_load_lds_dwordx4 v[222:223], off
	s_mov_b32 m0, s40
	s_nop 0
	global_load_lds_dwordx4 v[224:225], off
	s_waitcnt vmcnt(8) lgkmcnt(0)
	s_barrier
; #define PG8_STAGE(bufoff, gbase, voff) do { _Pragma("unroll") for (int _i = 0; _i < 2; ++_i) \
;         __builtin_amdgcn_global_load_lds((const unsigned*)((const char*)(gbase) + (voff)[_i]), (PG8_LAS unsigned*)(lds + (bufoff) + ldsw + _i * 8192), 16, 0, 0); } while (0)
; #define PG8_LDA(dst, b, h) do { _Pragma("unroll") for (int m = 0; m < 4; ++m) _Pragma("unroll") for (int k = 0; k < 2; ++k) dst[m][k] = *(const PG8_LAS bf16x8*)(lds + PG8_SA(b, h) + aoff + m * 2048 + k * 1024); } while (0)
; #define PG8_LDB(dst, b, h) do { _Pragma("unroll") for (int n = 0; n < 2; ++n) _Pragma("unroll") for (int k = 0; k < 2; ++k) dst[n][k] = *(const PG8_LAS bf16x8*)(lds + PG8_SB(b, h) + boff + n * 2048 + k * 1024); } while (0)
; #define PG8_MMA(ai, bj, At, Bt) do { __builtin_amdgcn_s_setprio(1); _Pragma("unroll") for (int m = 0; m < 4; ++m) _Pragma("unroll") for (int n = 0; n < 2; ++n) _Pragma("unroll") for (int k = 0; k < 2; ++k) \
;         acc[ai][bj][m][n] = __builtin_amdgcn_mfma_f32_16x16x32_bf16(Bt[n][k], At[m][k], acc[ai][bj][m][n], 0, 0, 0); __builtin_amdgcn_s_setprio(0); } while (0)
; #define PG8_WAIT_V(n) asm volatile("s_waitcnt vmcnt(" #n ")" ::: "memory")
; #define PG8_WAIT_L(n) asm volatile("s_waitcnt lgkmcnt(" #n ")" ::: "memory")
; #define PG8_BAR __builtin_amdgcn_s_barrier()
; #define PG8_SCHED __builtin_amdgcn_sched_barrier(0)
; template <class Epi, class Sched, bool ALIGN_EPI = false, bool SP2 = false>
; __device__ __forceinline__ void gemm_phase(PG8_LAS unsigned char* lds, const Gemm g, const Sched& S, const Epi& E) {
;     ...
;             PG8_WAIT_V(8); PG8_WAIT_L(0); PG8_BAR; PG8_MMA(1, 0, At, B0); PG8_MMA(1, 1, At, B1); PG8_BAR; PG8_SCHED;
;             PG8_LDB(B0, 1, 0); PG8_LDB(B1, 1, 1); PG8_SCHED; PG8_LDA(At, 1, 0); PG8_STAGE(PG8_SA(0, 1), a2 + hstepA, voffA);
;             PG8_WAIT_V(8); PG8_WAIT_L(0); PG8_BAR; PG8_MMA(0, 0, At, B0); PG8_MMA(0, 1, At, B1); PG8_BAR; PG8_SCHED;
	s_setprio 1
	v_mfma_f32_16x16x32_bf16 v[60:63], v[112:115], v[176:179], v[60:63]
	v_mfma_f32_16x16x32_bf16 v[56:59], v[128:131], v[176:179], v[56:59]
	v_mfma_f32_16x16x32_bf16 v[44:47], v[112:115], v[196:199], v[44:47]
	v_mfma_f32_16x16x32_bf16 v[40:43], v[128:131], v[196:199], v[40:43]
	v_mfma_f32_16x16x32_bf16 v[28:31], v[112:115], v[204:207], v[28:31]
	v_mfma_f32_16x16x32_bf16 v[24:27], v[128:131], v[204:207], v[24:27]
	v_mfma_f32_16x16x32_bf16 v[12:15], v[112:115], v[212:215], v[12:15]
	v_mfma_f32_16x16x32_bf16 v[8:11], v[128:131], v[212:215], v[8:11]
	v_mfma_f32_16x16x32_bf16 v[60:63], v[116:119], v[192:195], v[60:63]
	v_mfma_f32_16x16x32_bf16 v[56:59], v[140:143], v[192:195], v[56:59]
	v_mfma_f32_16x16x32_bf16 v[44:47], v[116:119], v[200:203], v[44:47]
	v_mfma_f32_16x16x32_bf16 v[40:43], v[140:143], v[200:203], v[40:43]
	v_mfma_f32_16x16x32_bf16 v[28:31], v[116:119], v[208:211], v[28:31]
	v_mfma_f32_16x16x32_bf16 v[24:27], v[140:143], v[208:211], v[24:27]
	v_mfma_f32_16x16x32_bf16 v[12:15], v[116:119], v[216:219], v[12:15]
	v_mfma_f32_16x16x32_bf16 v[8:11], v[140:143], v[216:219], v[8:11]
	s_setprio 0
	s_setprio 1
	v_mfma_f32_16x16x32_bf16 v[52:55], v[144:147], v[176:179], v[52:55]
	v_mfma_f32_16x16x32_bf16 v[48:51], v[168:171], v[176:179], v[48:51]
	v_mfma_f32_16x16x32_bf16 v[36:39], v[144:147], v[196:199], v[36:39]
	v_mfma_f32_16x16x32_bf16 v[32:35], v[168:171], v[196:199], v[32:35]
	v_mfma_f32_16x16x32_bf16 v[20:23], v[144:147], v[204:207], v[20:23]
	v_mfma_f32_16x16x32_bf16 v[16:19], v[168:171], v[204:207], v[16:19]
	v_mfma_f32_16x16x32_bf16 v[4:7], v[144:147], v[212:215], v[4:7]
	v_mfma_f32_16x16x32_bf16 v[0:3], v[168:171], v[212:215], v[0:3]
	v_mfma_f32_16x16x32_bf16 v[52:55], v[148:151], v[192:195], v[52:55]
	v_mfma_f32_16x16x32_bf16 v[48:51], v[172:175], v[192:195], v[48:51]
	v_mfma_f32_16x16x32_bf16 v[36:39], v[148:151], v[200:203], v[36:39]
	v_mfma_f32_16x16x32_bf16 v[32:35], v[172:175], v[200:203], v[32:35]
	v_mfma_f32_16x16x32_bf16 v[20:23], v[148:151], v[208:211], v[20:23]
	v_mfma_f32_16x16x32_bf16 v[16:19], v[172:175], v[208:211], v[16:19]
	v_mfma_f32_16x16x32_bf16 v[4:7], v[148:151], v[216:219], v[4:7]
	s_barrier
	v_mfma_f32_16x16x32_bf16 v[0:3], v[172:175], v[216:219], v[0:3]
	s_setprio 0
	s_add_i32 s58, 0, 0x18000
	s_add_i32 s59, 0, 0x1c000
	v_add_u32_e32 v140, s58, v183
	v_add_u32_e32 v172, s59, v183
	ds_read_b128 v[112:115], v140
	ds_read_b128 v[116:119], v140 offset:1024
	ds_read_b128 v[128:131], v140 offset:2048
	ds_read_b128 v[140:143], v140 offset:3072
	ds_read_b128 v[144:147], v172
	ds_read_b128 v[148:151], v172 offset:1024
	ds_read_b128 v[168:171], v172 offset:2048
	ds_read_b128 v[172:175], v172 offset:3072
	s_add_u32 s36, s36, 0x40000
	s_addc_u32 s37, s37, 0
	s_mov_b32 m0, s41
	v_lshl_add_u64 v[226:227], s[36:37], 0, v[152:153]
	ds_read_b128 v[176:179], v189 offset:32768
	ds_read_b128 v[192:195], v189 offset:33792
	ds_read_b128 v[196:199], v189 offset:34816
	ds_read_b128 v[200:203], v189 offset:35840
	ds_read_b128 v[204:207], v189 offset:36864
	ds_read_b128 v[208:211], v189 offset:37888
	ds_read_b128 v[212:215], v189 offset:38912
	ds_read_b128 v[216:219], v189 offset:39936
	global_load_lds_dwordx4 v[226:227], off
	v_lshl_add_u64 v[226:227], s[36:37], 0, v[156:157]
	s_mov_b32 m0, s42
	s_nop 0
	global_load_lds_dwordx4 v[226:227], off
	s_waitcnt vmcnt(8) lgkmcnt(0)
	s_barrier
	s_setprio 1
	v_mfma_f32_16x16x32_bf16 v[136:139], v[112:115], v[176:179], v[136:139]
	v_mfma_f32_16x16x32_bf16 v[132:135], v[128:131], v[176:179], v[132:135]
	v_mfma_f32_16x16x32_bf16 v[108:111], v[112:115], v[196:199], v[108:111]
	v_mfma_f32_16x16x32_bf16 v[104:107], v[128:131], v[196:199], v[104:107]
	v_mfma_f32_16x16x32_bf16 v[92:95], v[112:115], v[204:207], v[92:95]
	v_mfma_f32_16x16x32_bf16 v[88:91], v[128:131], v[204:207], v[88:91]
	v_mfma_f32_16x16x32_bf16 v[76:79], v[112:115], v[212:215], v[76:79]
	v_mfma_f32_16x16x32_bf16 v[72:75], v[128:131], v[212:215], v[72:75]
	v_mfma_f32_16x16x32_bf16 v[136:139], v[116:119], v[192:195], v[136:139]
	v_mfma_f32_16x16x32_bf16 v[132:135], v[140:143], v[192:195], v[132:135]
	v_mfma_f32_16x16x32_bf16 v[108:111], v[116:119], v[200:203], v[108:111]
	v_mfma_f32_16x16x32_bf16 v[104:107], v[140:143], v[200:203], v[104:107]
	v_mfma_f32_16x16x32_bf16 v[92:95], v[116:119], v[208:211], v[92:95]
	v_mfma_f32_16x16x32_bf16 v[88:91], v[140:143], v[208:211], v[88:91]
	v_mfma_f32_16x16x32_bf16 v[76:79], v[116:119], v[216:219], v[76:79]
	v_mfma_f32_16x16x32_bf16 v[72:75], v[140:143], v[216:219], v[72:75]
	s_setprio 0
	s_setprio 1
	v_mfma_f32_16x16x32_bf16 v[124:127], v[144:147], v[176:179], v[124:127]
	v_mfma_f32_16x16x32_bf16 v[120:123], v[168:171], v[176:179], v[120:123]
	v_mfma_f32_16x16x32_bf16 v[100:103], v[144:147], v[196:199], v[100:103]
	v_mfma_f32_16x16x32_bf16 v[96:99], v[168:171], v[196:199], v[96:99]
	v_mfma_f32_16x16x32_bf16 v[84:87], v[144:147], v[204:207], v[84:87]
	v_mfma_f32_16x16x32_bf16 v[80:83], v[168:171], v[204:207], v[80:83]
	v_mfma_f32_16x16x32_bf16 v[68:71], v[144:147], v[212:215], v[68:71]
	v_mfma_f32_16x16x32_bf16 v[64:67], v[168:171], v[212:215], v[64:67]
	v_mfma_f32_16x16x32_bf16 v[124:127], v[148:151], v[192:195], v[124:127]
	v_mfma_f32_16x16x32_bf16 v[120:123], v[172:175], v[192:195], v[120:123]
	v_mfma_f32_16x16x32_bf16 v[100:103], v[148:151], v[200:203], v[100:103]
	v_mfma_f32_16x16x32_bf16 v[96:99], v[172:175], v[200:203], v[96:99]
	v_mfma_f32_16x16x32_bf16 v[84:87], v[148:151], v[208:211], v[84:87]
	v_mfma_f32_16x16x32_bf16 v[80:83], v[172:175], v[208:211], v[80:83]
	v_mfma_f32_16x16x32_bf16 v[68:71], v[148:151], v[216:219], v[68:71]
	s_barrier
; #define PG8_STAGE(bufoff, gbase, voff) do { _Pragma("unroll") for (int _i = 0; _i < 2; ++_i) \
;         __builtin_amdgcn_global_load_lds((const unsigned*)((const char*)(gbase) + (voff)[_i]), (PG8_LAS unsigned*)(lds + (bufoff) + ldsw + _i * 8192), 16, 0, 0); } while (0)
; #define PG8_LDA(dst, b, h) do { _Pragma("unroll") for (int m = 0; m < 4; ++m) _Pragma("unroll") for (int k = 0; k < 2; ++k) dst[m][k] = *(const PG8_LAS bf16x8*)(lds + PG8_SA(b, h) + aoff + m * 2048 + k * 1024); } while (0)
; #define PG8_MMA(ai, bj, At, Bt) do { __builtin_amdgcn_s_setprio(1); _Pragma("unroll") for (int m = 0; m < 4; ++m) _Pragma("unroll") for (int n = 0; n < 2; ++n) _Pragma("unroll") for (int k = 0; k < 2; ++k) \
;         acc[ai][bj][m][n] = __builtin_amdgcn_mfma_f32_16x16x32_bf16(Bt[n][k], At[m][k], acc[ai][bj][m][n], 0, 0, 0); __builtin_amdgcn_s_setprio(0); } while (0)
; #define PG8_WAIT_V(n) asm volatile("s_waitcnt vmcnt(" #n ")" ::: "memory")
; #define PG8_WAIT_L(n) asm volatile("s_waitcnt lgkmcnt(" #n ")" ::: "memory")
; #define PG8_BAR __builtin_amdgcn_s_barrier()
; #define PG8_SCHED __builtin_amdgcn_sched_barrier(0)
; template <class Epi, class Sched, bool ALIGN_EPI = false, bool SP2 = false>
; __device__ __forceinline__ void gemm_phase(PG8_LAS unsigned char* lds, const Gemm g, const Sched& S, const Epi& E) {
;     ...
;         for (int t = 0; t < nt; t += 2) {
;             const bool last = (t == nt - 2);
;     ...
;             PG8_LDA(At, 1, 1); PG8_STAGE(PG8_SB(1, 0), b3, voffB); PG8_STAGE(PG8_SB(1, 1), b3 + hstepB, voffB); PG8_STAGE(PG8_SA(1, 0), a3, voffA);
;             PG8_WAIT_V(8); PG8_WAIT_L(0); PG8_BAR; PG8_MMA(1, 0, At, B0); PG8_MMA(1, 1, At, B1); PG8_BAR; PG8_SCHED;
	v_mfma_f32_16x16x32_bf16 v[64:67], v[172:175], v[216:219], v[64:67]
	s_setprio 0
	s_add_i32 s36, s58, s39
	v_lshl_add_u64 v[180:181], v[180:181], 0, s[14:15]
	s_mov_b32 m0, s36
	ds_read_b128 v[176:179], v189 offset:49152
	ds_read_b128 v[192:195], v189 offset:50176
	ds_read_b128 v[196:199], v189 offset:51200
	ds_read_b128 v[200:203], v189 offset:52224
	ds_read_b128 v[204:207], v189 offset:53248
	ds_read_b128 v[208:211], v189 offset:54272
	ds_read_b128 v[212:215], v189 offset:55296
	ds_read_b128 v[216:219], v189 offset:56320
	global_load_lds_dwordx4 v[180:181], off
	s_add_i32 m0, s36, 0x2000
	s_add_u32 s34, s34, 0x40080
	v_lshl_add_u64 v[180:181], v[220:221], 0, s[14:15]
	s_addc_u32 s35, s35, 0
	s_add_i32 s36, s59, s39
	global_load_lds_dwordx4 v[180:181], off
	v_lshl_add_u64 v[180:181], s[34:35], 0, v[154:155]
	s_mov_b32 m0, s36
	s_nop 0
	global_load_lds_dwordx4 v[180:181], off
	v_lshl_add_u64 v[180:181], s[34:35], 0, v[158:159]
	s_add_i32 m0, s36, 0x2000
	s_nop 0
	global_load_lds_dwordx4 v[180:181], off
	v_lshl_add_u64 v[180:181], v[222:223], 0, s[14:15]
	s_mov_b32 m0, s44
	s_nop 0
	global_load_lds_dwordx4 v[180:181], off
	v_lshl_add_u64 v[180:181], v[224:225], 0, s[14:15]
	s_mov_b32 m0, s45
	s_nop 0
	global_load_lds_dwordx4 v[180:181], off
	s_waitcnt vmcnt(8) lgkmcnt(0)
	s_barrier
	s_setprio 1
	v_mfma_f32_16x16x32_bf16 v[60:63], v[112:115], v[176:179], v[60:63]
	v_mfma_f32_16x16x32_bf16 v[56:59], v[128:131], v[176:179], v[56:59]
	v_mfma_f32_16x16x32_bf16 v[44:47], v[112:115], v[196:199], v[44:47]
	v_mfma_f32_16x16x32_bf16 v[40:43], v[128:131], v[196:199], v[40:43]
	v_mfma_f32_16x16x32_bf16 v[28:31], v[112:115], v[204:207], v[28:31]
	v_mfma_f32_16x16x32_bf16 v[24:27], v[128:131], v[204:207], v[24:27]
	v_mfma_f32_16x16x32_bf16 v[12:15], v[112:115], v[212:215], v[12:15]
	v_mfma_f32_16x16x32_bf16 v[8:11], v[128:131], v[212:215], v[8:11]
	v_mfma_f32_16x16x32_bf16 v[60:63], v[116:119], v[192:195], v[60:63]
	v_mfma_f32_16x16x32_bf16 v[56:59], v[140:143], v[192:195], v[56:59]
	v_mfma_f32_16x16x32_bf16 v[44:47], v[116:119], v[200:203], v[44:47]
	v_mfma_f32_16x16x32_bf16 v[40:43], v[140:143], v[200:203], v[40:43]
	v_mfma_f32_16x16x32_bf16 v[28:31], v[116:119], v[208:211], v[28:31]
	v_mfma_f32_16x16x32_bf16 v[24:27], v[140:143], v[208:211], v[24:27]
	v_mfma_f32_16x16x32_bf16 v[12:15], v[116:119], v[216:219], v[12:15]
	v_mfma_f32_16x16x32_bf16 v[8:11], v[140:143], v[216:219], v[8:11]
	s_setprio 0
	s_setprio 1
	v_mfma_f32_16x16x32_bf16 v[52:55], v[144:147], v[176:179], v[52:55]
	v_mfma_f32_16x16x32_bf16 v[48:51], v[168:171], v[176:179], v[48:51]
	v_mfma_f32_16x16x32_bf16 v[36:39], v[144:147], v[196:199], v[36:39]
	v_mfma_f32_16x16x32_bf16 v[32:35], v[168:171], v[196:199], v[32:35]
	v_mfma_f32_16x16x32_bf16 v[20:23], v[144:147], v[204:207], v[20:23]
	v_mfma_f32_16x16x32_bf16 v[16:19], v[168:171], v[204:207], v[16:19]
	v_mfma_f32_16x16x32_bf16 v[4:7], v[144:147], v[212:215], v[4:7]
	v_mfma_f32_16x16x32_bf16 v[0:3], v[168:171], v[212:215], v[0:3]
	v_mfma_f32_16x16x32_bf16 v[52:55], v[148:151], v[192:195], v[52:55]
	v_mfma_f32_16x16x32_bf16 v[48:51], v[172:175], v[192:195], v[48:51]
	v_mfma_f32_16x16x32_bf16 v[36:39], v[148:151], v[200:203], v[36:39]
	v_mfma_f32_16x16x32_bf16 v[32:35], v[172:175], v[200:203], v[32:35]
	v_mfma_f32_16x16x32_bf16 v[20:23], v[148:151], v[208:211], v[20:23]
	v_mfma_f32_16x16x32_bf16 v[16:19], v[172:175], v[208:211], v[16:19]
	v_mfma_f32_16x16x32_bf16 v[4:7], v[148:151], v[216:219], v[4:7]
	s_barrier
	v_mfma_f32_16x16x32_bf16 v[0:3], v[172:175], v[216:219], v[0:3]
	s_setprio 0
	s_add_i32 s69, s69, 2
	s_add_u32 s30, s30, 0x100
	s_addc_u32 s31, s31, 0
	s_add_u32 s67, s67, 0x100
	s_addc_u32 s68, s68, 0
	s_cmp_gt_u32 s69, 13
	s_cbranch_scc0 .LBB0_1231
	s_and_b64 vcc, exec, s[16:17]
	s_cbranch_vccz .LBB0_1234
	s_barrier
